# LayerNorm y loads with default cache policy (x loads stay nt)
# baseline (speedup 1.0000x reference)
.LBB0_49:
	s_and_b64 vcc, exec, s[42:43]
	s_cbranch_vccz .LBB0_226
	v_mov_b32_e32 v0, v135
	v_readlane_b32 s1, v252, 49
	v_readfirstlane_b32 s0, v0
	s_ashr_i32 s0, s0, 6
	s_add_i32 s6, s0, s1
	s_cmpk_gt_i32 s6, 0x7fff
	v_readlane_b32 s3, v252, 8
	s_cbranch_scc1 .LBB0_53
	s_mul_i32 s0, s16, 0x90000
	v_readlane_b32 s1, v252, 4
	s_add_u32 s7, s1, s0
	v_readlane_b32 s0, v252, 5
	s_addc_u32 s18, s0, 0
	s_cmp_eq_u32 s64, 1
	s_cselect_b64 s[0:1], -1, 0
	v_cndmask_b32_e64 v8, 0.5, 1.0, s[0:1]
	s_and_b64 s[0:1], s[0:1], s[92:93]
	s_and_b64 s[0:1], s[0:1], exec
	s_brev_b32 s0, 16
	s_cselect_b32 s0, s0, 0xc000000
	v_readlane_b32 s20, v252, 2
	v_readlane_b32 s21, v252, 3
	s_add_u32 s0, s20, s0
	s_addc_u32 s1, s21, 0
	s_cmp_lt_u32 s86, 39
	s_mul_i32 s30, s64, 0xc00
	s_cselect_b64 s[20:21], -1, 0
	s_add_i32 s25, s30, 0xc00
	s_cmp_eq_u32 s64, 2
	s_cselect_b64 s[22:23], -1, 0
	s_and_b64 s[34:35], s[22:23], exec
	s_cselect_b32 s34, 0, s25
	s_and_b64 s[20:21], s[22:23], s[20:21]
	s_and_b64 s[20:21], s[20:21], exec
	s_cselect_b32 s20, 0x90000, 0
	s_add_u32 s25, s7, s20
	s_addc_u32 s40, s18, 0
	s_lshl_b64 s[20:21], s[30:31], 2
	s_add_u32 s20, s7, s20
	s_mov_b32 s35, s31
	s_addc_u32 s21, s18, s21
	s_lshl_b64 s[22:23], s[34:35], 2
	s_add_u32 s22, s25, s22
	s_mul_i32 s7, s16, 3
	s_addc_u32 s23, s40, s23
	s_add_i32 s7, s64, s7
	v_lshlrev_b32_e32 v0, 2, v0
	s_lshl_b32 s30, s7, 10
	v_readlane_b32 s40, v254, 24
	v_and_b32_e32 v1, 0xfc, v0
	s_movk_i32 s7, 0x80
	v_bfrev_b32_e32 v2, 0.5
	s_lshl_b64 s[34:35], s[30:31], 2
	v_readlane_b32 s50, v254, 34
	s_waitcnt vmcnt(0)
	v_bitop3_b32 v52, v0, s7, v2 bitop3:0x6c
	v_lshlrev_b32_e32 v32, 2, v1
	v_lshlrev_b32_e32 v0, 1, v1
	v_mov_b32_e32 v1, v33
	v_readlane_b32 s41, v254, 25
	v_readlane_b32 s51, v254, 35
	s_add_u32 s40, s50, s34
	v_lshl_add_u64 v[18:19], s[0:1], 0, v[0:1]
	v_lshl_add_u64 v[2:3], s[20:21], 0, v[32:33]
	s_mov_b64 s[0:1], 0x2000
	v_readlane_b32 s48, v254, 32
	s_addc_u32 s41, s51, s35
	v_lshl_add_u64 v[20:21], v[2:3], 0, s[0:1]
	v_lshl_add_u64 v[22:23], s[22:23], 0, v[32:33]
	s_mov_b64 s[0:1], 0x1000
	v_readlane_b32 s49, v254, 33
	s_add_u32 s34, s48, s34
	v_lshl_add_u64 v[24:25], v[22:23], 0, s[0:1]
	v_readlane_b32 s0, v252, 6
	s_addc_u32 s35, s49, s35
	v_readlane_b32 s1, v252, 7
	v_mov_b32_e32 v10, v8
	v_mov_b32_e32 v11, v8
	v_lshl_add_u64 v[12:13], s[34:35], 0, v[32:33]
	v_lshl_add_u64 v[14:15], s[40:41], 0, v[32:33]
	v_lshl_add_u64 v[16:17], s[68:69], 0, v[32:33]
	v_lshl_add_u64 v[26:27], s[0:1], 0, v[0:1]
	v_readlane_b32 s42, v254, 26
	v_readlane_b32 s43, v254, 27
	v_readlane_b32 s44, v254, 28
	v_readlane_b32 s45, v254, 29
	v_readlane_b32 s46, v254, 30
	v_readlane_b32 s47, v254, 31
	v_readlane_b32 s52, v254, 36
	v_readlane_b32 s53, v254, 37
	v_readlane_b32 s54, v254, 38
	v_readlane_b32 s55, v254, 39
	s_cmpk_lg_i32 s3, 0x800
	s_cbranch_scc1 .LBB0_52
	v_mov_b32_e32 v96, v52
	s_lshr_b32 s0, s6, 7
	s_and_b32 s7, s6, 7
	s_andn2_b32 s6, s6, 7
	s_lshl_b32 s6, s6, 4
	s_or_b32 s6, s6, s7
	v_mad_i64_i32 v[28:29], s[22:23], s0, v193, v[20:21]
	v_mad_i64_i32 v[30:31], s[22:23], s0, v193, v[22:23]
	v_mad_i64_i32 v[0:1], s[22:23], s0, v193, v[24:25]
	global_load_dwordx4 v[194:197], v[28:29], off
	global_load_dwordx4 v[198:201], v[28:29], off offset:1024
	global_load_dwordx4 v[202:205], v[28:29], off offset:2048
	global_load_dwordx4 v[206:209], v[28:29], off offset:3072
	global_load_dwordx4 v[210:213], v[30:31], off
	global_load_dwordx4 v[214:217], v[30:31], off offset:1024
	global_load_dwordx4 v[218:221], v[30:31], off offset:2048
	global_load_dwordx4 v[222:225], v[30:31], off offset:3072
	global_load_dwordx4 v[226:229], v[0:1], off
	global_load_dwordx4 v[230:233], v[0:1], off offset:1024
	global_load_dwordx4 v[234:237], v[0:1], off offset:2048
	global_load_dwordx4 v[238:241], v[0:1], off offset:3072
	global_load_dwordx4 v[140:143], v[12:13], off
	global_load_dwordx4 v[144:147], v[12:13], off offset:1024
	global_load_dwordx4 v[148:151], v[12:13], off offset:2048
	global_load_dwordx4 v[152:155], v[12:13], off offset:3072
	global_load_dwordx4 v[98:101], v[14:15], off
	global_load_dwordx4 v[102:105], v[14:15], off offset:1024
	global_load_dwordx4 v[106:109], v[14:15], off offset:2048
	global_load_dwordx4 v[110:113], v[14:15], off offset:3072
	s_ashr_i32 s7, s6, 31
	s_lshl_b64 s[40:41], s[6:7], 12
	s_lshl_b64 s[20:21], s[6:7], 11
	v_lshl_add_u64 v[82:83], v[16:17], 0, s[40:41]
	v_lshl_add_u64 v[84:85], v[18:19], 0, s[20:21]
	v_lshl_add_u64 v[88:89], v[26:27], 0, s[20:21]
	v_lshl_add_u64 v[86:87], v[16:17], 0, s[40:41]
	s_mov_b64 s[0:1], 0x8000
	s_mov_b64 s[20:21], 0x4000
	global_load_dwordx4 v[34:37], v[82:83], off nt
	global_load_dwordx4 v[38:41], v[82:83], off offset:1024 nt
	global_load_dwordx4 v[42:45], v[82:83], off offset:2048 nt
	global_load_dwordx4 v[46:49], v[82:83], off offset:3072 nt
	global_load_dwordx2 v[50:51], v[84:85], off
	global_load_dwordx2 v[52:53], v[84:85], off offset:512
	global_load_dwordx2 v[54:55], v[84:85], off offset:1024
	global_load_dwordx2 v[56:57], v[84:85], off offset:1536
	v_lshl_add_u64 v[82:83], v[82:83], 0, s[0:1]
	v_lshl_add_u64 v[84:85], v[84:85], 0, s[20:21]
	global_load_dwordx4 v[58:61], v[82:83], off nt
	global_load_dwordx4 v[62:65], v[82:83], off offset:1024 nt
	global_load_dwordx4 v[66:69], v[82:83], off offset:2048 nt
	global_load_dwordx4 v[70:73], v[82:83], off offset:3072 nt
	global_load_dwordx2 v[74:75], v[84:85], off
	global_load_dwordx2 v[76:77], v[84:85], off offset:512
	global_load_dwordx2 v[78:79], v[84:85], off offset:1024
	global_load_dwordx2 v[80:81], v[84:85], off offset:1536
	v_lshl_add_u64 v[82:83], v[82:83], 0, s[0:1]
	v_lshl_add_u64 v[84:85], v[84:85], 0, s[20:21]
	global_load_dwordx4 v[20:23], v[82:83], off nt
	global_load_dwordx4 v[24:27], v[82:83], off offset:1024 nt
	global_load_dwordx4 v[0:3], v[82:83], off offset:2048 nt
	global_load_dwordx4 v[4:7], v[82:83], off offset:3072 nt
	global_load_dwordx2 v[12:13], v[84:85], off
	global_load_dwordx2 v[14:15], v[84:85], off offset:512
	global_load_dwordx2 v[16:17], v[84:85], off offset:1024
	global_load_dwordx2 v[18:19], v[84:85], off offset:1536
	v_lshl_add_u64 v[82:83], v[82:83], 0, s[0:1]
	v_lshl_add_u64 v[84:85], v[84:85], 0, s[20:21]
	s_waitcnt vmcnt(24)
	v_pk_add_f32 v[194:195], v[194:195], 1.0 op_sel_hi:[1,0]
	v_pk_add_f32 v[196:197], v[196:197], 1.0 op_sel_hi:[1,0]
	v_pk_add_f32 v[198:199], v[198:199], 1.0 op_sel_hi:[1,0]
	v_pk_add_f32 v[200:201], v[200:201], 1.0 op_sel_hi:[1,0]
	v_pk_add_f32 v[202:203], v[202:203], 1.0 op_sel_hi:[1,0]
	v_pk_add_f32 v[204:205], v[204:205], 1.0 op_sel_hi:[1,0]
	v_pk_add_f32 v[206:207], v[206:207], 1.0 op_sel_hi:[1,0]
	v_pk_add_f32 v[208:209], v[208:209], 1.0 op_sel_hi:[1,0]
	v_pk_add_f32 v[226:227], v[226:227], 1.0 op_sel_hi:[1,0]
	v_pk_add_f32 v[228:229], v[228:229], 1.0 op_sel_hi:[1,0]
	v_pk_add_f32 v[230:231], v[230:231], 1.0 op_sel_hi:[1,0]
	v_pk_add_f32 v[232:233], v[232:233], 1.0 op_sel_hi:[1,0]
	v_pk_add_f32 v[234:235], v[234:235], 1.0 op_sel_hi:[1,0]
	v_pk_add_f32 v[236:237], v[236:237], 1.0 op_sel_hi:[1,0]
	v_pk_add_f32 v[238:239], v[238:239], 1.0 op_sel_hi:[1,0]
	v_pk_add_f32 v[240:241], v[240:241], 1.0 op_sel_hi:[1,0]
	s_waitcnt vmcnt(16)
	v_lshlrev_b32_e32 v156, 16, v50
	v_and_b32_e32 v157, 0xffff0000, v50
	v_lshlrev_b32_e32 v50, 16, v51
	v_and_b32_e32 v51, 0xffff0000, v51
	v_lshlrev_b32_e32 v158, 16, v52
	v_and_b32_e32 v159, 0xffff0000, v52
	v_lshlrev_b32_e32 v52, 16, v53
	v_and_b32_e32 v53, 0xffff0000, v53
	v_lshlrev_b32_e32 v160, 16, v54
	v_and_b32_e32 v161, 0xffff0000, v54
	v_lshlrev_b32_e32 v54, 16, v55
	v_and_b32_e32 v55, 0xffff0000, v55
	v_lshlrev_b32_e32 v162, 16, v56
	v_and_b32_e32 v163, 0xffff0000, v56
	v_lshlrev_b32_e32 v56, 16, v57
	v_and_b32_e32 v57, 0xffff0000, v57
	v_pk_mul_f32 v[114:115], v[194:195], v[156:157]
	v_pk_mul_f32 v[116:117], v[196:197], v[50:51]
	v_pk_mul_f32 v[118:119], v[198:199], v[158:159]
	v_pk_mul_f32 v[120:121], v[200:201], v[52:53]
	v_pk_mul_f32 v[122:123], v[202:203], v[160:161]
	v_pk_mul_f32 v[124:125], v[204:205], v[54:55]
	v_pk_mul_f32 v[126:127], v[206:207], v[162:163]
	v_pk_mul_f32 v[128:129], v[208:209], v[56:57]
	v_pk_mul_f32 v[114:115], v[10:11], v[114:115]
	v_pk_mul_f32 v[116:117], v[10:11], v[116:117]
	v_pk_mul_f32 v[118:119], v[10:11], v[118:119]
	v_pk_mul_f32 v[120:121], v[10:11], v[120:121]
	v_pk_mul_f32 v[122:123], v[10:11], v[122:123]
	v_pk_mul_f32 v[124:125], v[10:11], v[124:125]
	v_pk_mul_f32 v[126:127], v[10:11], v[126:127]
	v_pk_mul_f32 v[128:129], v[10:11], v[128:129]
	v_pk_fma_f32 v[114:115], v[34:35], s[28:29], v[114:115] op_sel_hi:[1,0,1]
	v_pk_fma_f32 v[116:117], v[36:37], s[28:29], v[116:117] op_sel_hi:[1,0,1]
	v_pk_fma_f32 v[118:119], v[38:39], s[28:29], v[118:119] op_sel_hi:[1,0,1]
	v_pk_fma_f32 v[120:121], v[40:41], s[28:29], v[120:121] op_sel_hi:[1,0,1]
	v_pk_fma_f32 v[122:123], v[42:43], s[28:29], v[122:123] op_sel_hi:[1,0,1]
	v_pk_fma_f32 v[124:125], v[44:45], s[28:29], v[124:125] op_sel_hi:[1,0,1]
	v_pk_fma_f32 v[126:127], v[46:47], s[28:29], v[126:127] op_sel_hi:[1,0,1]
	v_pk_fma_f32 v[128:129], v[48:49], s[28:29], v[128:129] op_sel_hi:[1,0,1]
	v_add_f32_e32 v164, v114, v115
	v_add_f32_e32 v165, v116, v117
	v_add_f32_e32 v166, v118, v119
	v_add_f32_e32 v167, v120, v121
	v_add_f32_e32 v168, v122, v123
	v_add_f32_e32 v169, v124, v125
	v_add_f32_e32 v242, v126, v127
	v_add_f32_e32 v243, v128, v129
	v_add_f32_e32 v164, v164, v165
	v_add_f32_e32 v166, v166, v167
	v_add_f32_e32 v168, v168, v169
	v_add_f32_e32 v242, v242, v243
	v_add_f32_e32 v9, 0, v164
	v_add_f32_e32 v9, v9, v166
	v_add_f32_e32 v9, v9, v168
	v_add_f32_e32 v9, v9, v242
	ds_bpermute_b32 v28, v96, v9
	s_waitcnt lgkmcnt(0)
	v_add_f32_e32 v9, v9, v28
	ds_swizzle_b32 v28, v9 offset:swizzle(SWAP,16)
	s_waitcnt lgkmcnt(0)
	v_add_f32_e32 v9, v9, v28
	ds_swizzle_b32 v28, v9 offset:swizzle(SWAP,8)
	s_waitcnt lgkmcnt(0)
	v_add_f32_e32 v9, v9, v28
	ds_swizzle_b32 v28, v9 offset:swizzle(SWAP,4)
	s_waitcnt lgkmcnt(0)
	v_add_f32_e32 v9, v9, v28
	ds_swizzle_b32 v28, v9 offset:swizzle(SWAP,2)
	s_waitcnt lgkmcnt(0)
	v_add_f32_e32 v9, v9, v28
	ds_swizzle_b32 v28, v9 offset:swizzle(SWAP,1)
	s_waitcnt lgkmcnt(0)
	v_add_f32_e32 v9, v9, v28
	v_fmac_f32_e32 v114, 0xba800000, v9
	v_fmac_f32_e32 v115, 0xba800000, v9
	v_fmac_f32_e32 v116, 0xba800000, v9
	v_fmac_f32_e32 v117, 0xba800000, v9
	v_fmac_f32_e32 v118, 0xba800000, v9
	v_fmac_f32_e32 v119, 0xba800000, v9
	v_fmac_f32_e32 v120, 0xba800000, v9
	v_fmac_f32_e32 v121, 0xba800000, v9
	v_fmac_f32_e32 v122, 0xba800000, v9
	v_fmac_f32_e32 v123, 0xba800000, v9
	v_fmac_f32_e32 v124, 0xba800000, v9
	v_fmac_f32_e32 v125, 0xba800000, v9
	v_fmac_f32_e32 v126, 0xba800000, v9
	v_fmac_f32_e32 v127, 0xba800000, v9
	v_fmac_f32_e32 v128, 0xba800000, v9
	v_fmac_f32_e32 v129, 0xba800000, v9
	v_pk_mul_f32 v[244:245], v[114:115], v[114:115]
	v_pk_mul_f32 v[246:247], v[116:117], v[116:117]
	v_add_f32_e32 v244, v245, v244
	v_add_f32_e32 v246, v246, v247
	v_add_f32_e32 v164, v244, v246
	v_pk_mul_f32 v[244:245], v[118:119], v[118:119]
	v_pk_mul_f32 v[246:247], v[120:121], v[120:121]
	v_add_f32_e32 v244, v245, v244
	v_add_f32_e32 v246, v246, v247
	v_add_f32_e32 v165, v244, v246
	v_mul_f32_e32 v248, v122, v122
	v_mul_f32_e32 v249, v124, v124
	v_fmac_f32_e32 v248, v123, v123
	v_fmac_f32_e32 v249, v125, v125
	v_add_f32_e32 v166, v248, v249
	v_pk_mul_f32 v[244:245], v[126:127], v[126:127]
	v_pk_mul_f32 v[246:247], v[128:129], v[128:129]
	v_add_f32_e32 v244, v244, v245
	v_add_f32_e32 v246, v246, v247
	v_add_f32_e32 v167, v244, v246
	v_add_f32_e32 v164, v164, v165
	v_add_f32_e32 v164, v166, v164
	v_add_f32_e32 v9, v167, v164
	ds_bpermute_b32 v28, v96, v9
	s_waitcnt lgkmcnt(0)
	v_add_f32_e32 v9, v9, v28
	ds_swizzle_b32 v28, v9 offset:swizzle(SWAP,16)
	s_waitcnt lgkmcnt(0)
	v_add_f32_e32 v9, v9, v28
	ds_swizzle_b32 v28, v9 offset:swizzle(SWAP,8)
	s_waitcnt lgkmcnt(0)
	v_add_f32_e32 v9, v9, v28
	ds_swizzle_b32 v28, v9 offset:swizzle(SWAP,4)
	s_waitcnt lgkmcnt(0)
	v_add_f32_e32 v9, v9, v28
	ds_swizzle_b32 v28, v9 offset:swizzle(SWAP,2)
	s_waitcnt lgkmcnt(0)
	v_add_f32_e32 v9, v9, v28
	ds_swizzle_b32 v28, v9 offset:swizzle(SWAP,1)
	s_waitcnt lgkmcnt(0)
	v_add_f32_e32 v9, v9, v28
	v_mov_b32_e32 v28, 0x3727c5ac
	v_fmamk_f32 v9, v9, 0x3a800000, v28
	v_mul_f32_e32 v28, 0x4b800000, v9
	v_cmp_gt_f32_e32 vcc, s37, v9
	s_nop 1
	v_cndmask_b32_e32 v9, v9, v28, vcc
	v_rsq_f32_e32 v9, v9
	s_nop 0
	v_mul_f32_e32 v28, 0x45800000, v9
	v_cndmask_b32_e32 v30, v9, v28, vcc
	v_pk_mul_f32 v[114:115], v[114:115], v[30:31] op_sel_hi:[1,0]
	v_pk_mul_f32 v[116:117], v[116:117], v[30:31] op_sel_hi:[1,0]
	v_pk_fma_f32 v[34:35], v[140:141], v[114:115], v[98:99]
	v_pk_fma_f32 v[36:37], v[142:143], v[116:117], v[100:101]
	global_store_dwordx4 v[86:87], v[34:37], off sc1 nt
	v_pk_fma_f32 v[114:115], v[226:227], v[34:35], v[210:211]
	v_pk_fma_f32 v[116:117], v[228:229], v[36:37], v[212:213]
	s_nop 0
	v_cvt_pk_bf16_f32 v50, v114, v115
	v_cvt_pk_bf16_f32 v51, v116, v117
	global_store_dwordx2 v[88:89], v[50:51], off sc1
	v_pk_mul_f32 v[118:119], v[118:119], v[30:31] op_sel_hi:[1,0]
	v_pk_mul_f32 v[120:121], v[120:121], v[30:31] op_sel_hi:[1,0]
	v_pk_fma_f32 v[38:39], v[144:145], v[118:119], v[102:103]
	v_pk_fma_f32 v[40:41], v[146:147], v[120:121], v[104:105]
	global_store_dwordx4 v[86:87], v[38:41], off offset:1024 sc1 nt
	v_pk_fma_f32 v[118:119], v[230:231], v[38:39], v[214:215]
	v_pk_fma_f32 v[120:121], v[232:233], v[40:41], v[216:217]
	s_nop 0
	v_cvt_pk_bf16_f32 v52, v118, v119
	v_cvt_pk_bf16_f32 v53, v120, v121
	global_store_dwordx2 v[88:89], v[52:53], off offset:512 sc1
	v_pk_mul_f32 v[122:123], v[122:123], v[30:31] op_sel_hi:[1,0]
	v_pk_mul_f32 v[124:125], v[124:125], v[30:31] op_sel_hi:[1,0]
	v_pk_fma_f32 v[42:43], v[148:149], v[122:123], v[106:107]
	v_pk_fma_f32 v[44:45], v[150:151], v[124:125], v[108:109]
	global_store_dwordx4 v[86:87], v[42:45], off offset:2048 sc1 nt
	v_pk_fma_f32 v[122:123], v[234:235], v[42:43], v[218:219]
	v_pk_fma_f32 v[124:125], v[236:237], v[44:45], v[220:221]
	s_nop 0
	v_cvt_pk_bf16_f32 v54, v122, v123
	v_cvt_pk_bf16_f32 v55, v124, v125
	global_store_dwordx2 v[88:89], v[54:55], off offset:1024 sc1
	v_pk_mul_f32 v[126:127], v[126:127], v[30:31] op_sel_hi:[1,0]
	v_pk_mul_f32 v[128:129], v[128:129], v[30:31] op_sel_hi:[1,0]
	v_pk_fma_f32 v[46:47], v[152:153], v[126:127], v[110:111]
	v_pk_fma_f32 v[48:49], v[154:155], v[128:129], v[112:113]
	global_store_dwordx4 v[86:87], v[46:49], off offset:3072 sc1 nt
	v_pk_fma_f32 v[126:127], v[238:239], v[46:47], v[222:223]
	v_pk_fma_f32 v[128:129], v[240:241], v[48:49], v[224:225]
	s_nop 0
	v_cvt_pk_bf16_f32 v56, v126, v127
	v_cvt_pk_bf16_f32 v57, v128, v129
	global_store_dwordx2 v[88:89], v[56:57], off offset:1536 sc1
	v_lshl_add_u64 v[86:87], v[86:87], 0, s[0:1]
	v_lshl_add_u64 v[88:89], v[88:89], 0, s[20:21]
	global_load_dwordx4 v[34:37], v[82:83], off nt
	global_load_dwordx4 v[38:41], v[82:83], off offset:1024 nt
	global_load_dwordx4 v[42:45], v[82:83], off offset:2048 nt
	global_load_dwordx4 v[46:49], v[82:83], off offset:3072 nt
	global_load_dwordx2 v[50:51], v[84:85], off
	global_load_dwordx2 v[52:53], v[84:85], off offset:512
	global_load_dwordx2 v[54:55], v[84:85], off offset:1024
	global_load_dwordx2 v[56:57], v[84:85], off offset:1536
	v_lshl_add_u64 v[82:83], v[82:83], 0, s[0:1]
	v_lshl_add_u64 v[84:85], v[84:85], 0, s[20:21]
	s_waitcnt vmcnt(24)
	v_lshlrev_b32_e32 v156, 16, v74
	v_and_b32_e32 v157, 0xffff0000, v74
	v_lshlrev_b32_e32 v74, 16, v75
	v_and_b32_e32 v75, 0xffff0000, v75
	v_lshlrev_b32_e32 v158, 16, v76
	v_and_b32_e32 v159, 0xffff0000, v76
	v_lshlrev_b32_e32 v76, 16, v77
	v_and_b32_e32 v77, 0xffff0000, v77
	v_lshlrev_b32_e32 v160, 16, v78
	v_and_b32_e32 v161, 0xffff0000, v78
	v_lshlrev_b32_e32 v78, 16, v79
	v_and_b32_e32 v79, 0xffff0000, v79
	v_lshlrev_b32_e32 v162, 16, v80
	v_and_b32_e32 v163, 0xffff0000, v80
	v_lshlrev_b32_e32 v80, 16, v81
	v_and_b32_e32 v81, 0xffff0000, v81
	v_pk_mul_f32 v[114:115], v[194:195], v[156:157]
	v_pk_mul_f32 v[116:117], v[196:197], v[74:75]
	v_pk_mul_f32 v[118:119], v[198:199], v[158:159]
	v_pk_mul_f32 v[120:121], v[200:201], v[76:77]
	v_pk_mul_f32 v[122:123], v[202:203], v[160:161]
	v_pk_mul_f32 v[124:125], v[204:205], v[78:79]
	v_pk_mul_f32 v[126:127], v[206:207], v[162:163]
	v_pk_mul_f32 v[128:129], v[208:209], v[80:81]
	v_pk_mul_f32 v[114:115], v[10:11], v[114:115]
	v_pk_mul_f32 v[116:117], v[10:11], v[116:117]
	v_pk_mul_f32 v[118:119], v[10:11], v[118:119]
	v_pk_mul_f32 v[120:121], v[10:11], v[120:121]
	v_pk_mul_f32 v[122:123], v[10:11], v[122:123]
	v_pk_mul_f32 v[124:125], v[10:11], v[124:125]
	v_pk_mul_f32 v[126:127], v[10:11], v[126:127]
	v_pk_mul_f32 v[128:129], v[10:11], v[128:129]
	v_pk_fma_f32 v[114:115], v[58:59], s[28:29], v[114:115] op_sel_hi:[1,0,1]
	v_pk_fma_f32 v[116:117], v[60:61], s[28:29], v[116:117] op_sel_hi:[1,0,1]
	v_pk_fma_f32 v[118:119], v[62:63], s[28:29], v[118:119] op_sel_hi:[1,0,1]
	v_pk_fma_f32 v[120:121], v[64:65], s[28:29], v[120:121] op_sel_hi:[1,0,1]
	v_pk_fma_f32 v[122:123], v[66:67], s[28:29], v[122:123] op_sel_hi:[1,0,1]
	v_pk_fma_f32 v[124:125], v[68:69], s[28:29], v[124:125] op_sel_hi:[1,0,1]
	v_pk_fma_f32 v[126:127], v[70:71], s[28:29], v[126:127] op_sel_hi:[1,0,1]
	v_pk_fma_f32 v[128:129], v[72:73], s[28:29], v[128:129] op_sel_hi:[1,0,1]
	v_add_f32_e32 v164, v114, v115
	v_add_f32_e32 v165, v116, v117
	v_add_f32_e32 v166, v118, v119
	v_add_f32_e32 v167, v120, v121
	v_add_f32_e32 v168, v122, v123
	v_add_f32_e32 v169, v124, v125
	v_add_f32_e32 v242, v126, v127
	v_add_f32_e32 v243, v128, v129
	v_add_f32_e32 v164, v164, v165
	v_add_f32_e32 v166, v166, v167
	v_add_f32_e32 v168, v168, v169
	v_add_f32_e32 v242, v242, v243
	v_add_f32_e32 v9, 0, v164
	v_add_f32_e32 v9, v9, v166
	v_add_f32_e32 v9, v9, v168
	v_add_f32_e32 v9, v9, v242
	ds_bpermute_b32 v28, v96, v9
	s_waitcnt lgkmcnt(0)
	v_add_f32_e32 v9, v9, v28
	ds_swizzle_b32 v28, v9 offset:swizzle(SWAP,16)
	s_waitcnt lgkmcnt(0)
	v_add_f32_e32 v9, v9, v28
	ds_swizzle_b32 v28, v9 offset:swizzle(SWAP,8)
	s_waitcnt lgkmcnt(0)
	v_add_f32_e32 v9, v9, v28
	ds_swizzle_b32 v28, v9 offset:swizzle(SWAP,4)
	s_waitcnt lgkmcnt(0)
	v_add_f32_e32 v9, v9, v28
	ds_swizzle_b32 v28, v9 offset:swizzle(SWAP,2)
	s_waitcnt lgkmcnt(0)
	v_add_f32_e32 v9, v9, v28
	ds_swizzle_b32 v28, v9 offset:swizzle(SWAP,1)
	s_waitcnt lgkmcnt(0)
	v_add_f32_e32 v9, v9, v28
	v_fmac_f32_e32 v114, 0xba800000, v9
	v_fmac_f32_e32 v115, 0xba800000, v9
	v_fmac_f32_e32 v116, 0xba800000, v9
	v_fmac_f32_e32 v117, 0xba800000, v9
	v_fmac_f32_e32 v118, 0xba800000, v9
	v_fmac_f32_e32 v119, 0xba800000, v9
	v_fmac_f32_e32 v120, 0xba800000, v9
	v_fmac_f32_e32 v121, 0xba800000, v9
	v_fmac_f32_e32 v122, 0xba800000, v9
	v_fmac_f32_e32 v123, 0xba800000, v9
	v_fmac_f32_e32 v124, 0xba800000, v9
	v_fmac_f32_e32 v125, 0xba800000, v9
	v_fmac_f32_e32 v126, 0xba800000, v9
	v_fmac_f32_e32 v127, 0xba800000, v9
	v_fmac_f32_e32 v128, 0xba800000, v9
	v_fmac_f32_e32 v129, 0xba800000, v9
	v_pk_mul_f32 v[244:245], v[114:115], v[114:115]
	v_pk_mul_f32 v[246:247], v[116:117], v[116:117]
	v_add_f32_e32 v244, v245, v244
	v_add_f32_e32 v246, v246, v247
	v_add_f32_e32 v164, v244, v246
	v_pk_mul_f32 v[244:245], v[118:119], v[118:119]
	v_pk_mul_f32 v[246:247], v[120:121], v[120:121]
	v_add_f32_e32 v244, v245, v244
	v_add_f32_e32 v246, v246, v247
	v_add_f32_e32 v165, v244, v246
	v_mul_f32_e32 v248, v122, v122
	v_mul_f32_e32 v249, v124, v124
	v_fmac_f32_e32 v248, v123, v123
	v_fmac_f32_e32 v249, v125, v125
	v_add_f32_e32 v166, v248, v249
	v_pk_mul_f32 v[244:245], v[126:127], v[126:127]
	v_pk_mul_f32 v[246:247], v[128:129], v[128:129]
	v_add_f32_e32 v244, v244, v245
	v_add_f32_e32 v246, v246, v247
	v_add_f32_e32 v167, v244, v246
	v_add_f32_e32 v164, v164, v165
	v_add_f32_e32 v164, v166, v164
	v_add_f32_e32 v9, v167, v164
	ds_bpermute_b32 v28, v96, v9
	s_waitcnt lgkmcnt(0)
	v_add_f32_e32 v9, v9, v28
	ds_swizzle_b32 v28, v9 offset:swizzle(SWAP,16)
	s_waitcnt lgkmcnt(0)
	v_add_f32_e32 v9, v9, v28
	ds_swizzle_b32 v28, v9 offset:swizzle(SWAP,8)
	s_waitcnt lgkmcnt(0)
	v_add_f32_e32 v9, v9, v28
	ds_swizzle_b32 v28, v9 offset:swizzle(SWAP,4)
	s_waitcnt lgkmcnt(0)
	v_add_f32_e32 v9, v9, v28
	ds_swizzle_b32 v28, v9 offset:swizzle(SWAP,2)
	s_waitcnt lgkmcnt(0)
	v_add_f32_e32 v9, v9, v28
	ds_swizzle_b32 v28, v9 offset:swizzle(SWAP,1)
	s_waitcnt lgkmcnt(0)
	v_add_f32_e32 v9, v9, v28
	v_mov_b32_e32 v28, 0x3727c5ac
	v_fmamk_f32 v9, v9, 0x3a800000, v28
	v_mul_f32_e32 v28, 0x4b800000, v9
	v_cmp_gt_f32_e32 vcc, s37, v9
	s_nop 1
	v_cndmask_b32_e32 v9, v9, v28, vcc
	v_rsq_f32_e32 v9, v9
	s_nop 0
	v_mul_f32_e32 v28, 0x45800000, v9
	v_cndmask_b32_e32 v30, v9, v28, vcc
	v_pk_mul_f32 v[114:115], v[114:115], v[30:31] op_sel_hi:[1,0]
	v_pk_mul_f32 v[116:117], v[116:117], v[30:31] op_sel_hi:[1,0]
	v_pk_fma_f32 v[58:59], v[140:141], v[114:115], v[98:99]
	v_pk_fma_f32 v[60:61], v[142:143], v[116:117], v[100:101]
	global_store_dwordx4 v[86:87], v[58:61], off sc1 nt
	v_pk_fma_f32 v[114:115], v[226:227], v[58:59], v[210:211]
	v_pk_fma_f32 v[116:117], v[228:229], v[60:61], v[212:213]
	s_nop 0
	v_cvt_pk_bf16_f32 v74, v114, v115
	v_cvt_pk_bf16_f32 v75, v116, v117
	global_store_dwordx2 v[88:89], v[74:75], off sc1
	v_pk_mul_f32 v[118:119], v[118:119], v[30:31] op_sel_hi:[1,0]
	v_pk_mul_f32 v[120:121], v[120:121], v[30:31] op_sel_hi:[1,0]
	v_pk_fma_f32 v[62:63], v[144:145], v[118:119], v[102:103]
	v_pk_fma_f32 v[64:65], v[146:147], v[120:121], v[104:105]
	global_store_dwordx4 v[86:87], v[62:65], off offset:1024 sc1 nt
	v_pk_fma_f32 v[118:119], v[230:231], v[62:63], v[214:215]
	v_pk_fma_f32 v[120:121], v[232:233], v[64:65], v[216:217]
	s_nop 0
	v_cvt_pk_bf16_f32 v76, v118, v119
	v_cvt_pk_bf16_f32 v77, v120, v121
	global_store_dwordx2 v[88:89], v[76:77], off offset:512 sc1
	v_pk_mul_f32 v[122:123], v[122:123], v[30:31] op_sel_hi:[1,0]
	v_pk_mul_f32 v[124:125], v[124:125], v[30:31] op_sel_hi:[1,0]
	v_pk_fma_f32 v[66:67], v[148:149], v[122:123], v[106:107]
	v_pk_fma_f32 v[68:69], v[150:151], v[124:125], v[108:109]
	global_store_dwordx4 v[86:87], v[66:69], off offset:2048 sc1 nt
	v_pk_fma_f32 v[122:123], v[234:235], v[66:67], v[218:219]
	v_pk_fma_f32 v[124:125], v[236:237], v[68:69], v[220:221]
	s_nop 0
	v_cvt_pk_bf16_f32 v78, v122, v123
	v_cvt_pk_bf16_f32 v79, v124, v125
	global_store_dwordx2 v[88:89], v[78:79], off offset:1024 sc1
	v_pk_mul_f32 v[126:127], v[126:127], v[30:31] op_sel_hi:[1,0]
	v_pk_mul_f32 v[128:129], v[128:129], v[30:31] op_sel_hi:[1,0]
	v_pk_fma_f32 v[70:71], v[152:153], v[126:127], v[110:111]
	v_pk_fma_f32 v[72:73], v[154:155], v[128:129], v[112:113]
	global_store_dwordx4 v[86:87], v[70:73], off offset:3072 sc1 nt
	v_pk_fma_f32 v[126:127], v[238:239], v[70:71], v[222:223]
	v_pk_fma_f32 v[128:129], v[240:241], v[72:73], v[224:225]
	s_nop 0
	v_cvt_pk_bf16_f32 v80, v126, v127
	v_cvt_pk_bf16_f32 v81, v128, v129
	global_store_dwordx2 v[88:89], v[80:81], off offset:1536 sc1
	v_lshl_add_u64 v[86:87], v[86:87], 0, s[0:1]
	v_lshl_add_u64 v[88:89], v[88:89], 0, s[20:21]
	global_load_dwordx4 v[58:61], v[82:83], off nt
	global_load_dwordx4 v[62:65], v[82:83], off offset:1024 nt
	global_load_dwordx4 v[66:69], v[82:83], off offset:2048 nt
	global_load_dwordx4 v[70:73], v[82:83], off offset:3072 nt
	global_load_dwordx2 v[74:75], v[84:85], off
	global_load_dwordx2 v[76:77], v[84:85], off offset:512
	global_load_dwordx2 v[78:79], v[84:85], off offset:1024
	global_load_dwordx2 v[80:81], v[84:85], off offset:1536
	v_lshl_add_u64 v[82:83], v[82:83], 0, s[0:1]
	v_lshl_add_u64 v[84:85], v[84:85], 0, s[20:21]
	s_waitcnt vmcnt(32)
	v_lshlrev_b32_e32 v156, 16, v12
	v_and_b32_e32 v157, 0xffff0000, v12
	v_lshlrev_b32_e32 v12, 16, v13
	v_and_b32_e32 v13, 0xffff0000, v13
	v_lshlrev_b32_e32 v158, 16, v14
	v_and_b32_e32 v159, 0xffff0000, v14
	v_lshlrev_b32_e32 v14, 16, v15
	v_and_b32_e32 v15, 0xffff0000, v15
	v_lshlrev_b32_e32 v160, 16, v16
	v_and_b32_e32 v161, 0xffff0000, v16
	v_lshlrev_b32_e32 v16, 16, v17
	v_and_b32_e32 v17, 0xffff0000, v17
	v_lshlrev_b32_e32 v162, 16, v18
	v_and_b32_e32 v163, 0xffff0000, v18
	v_lshlrev_b32_e32 v18, 16, v19
	v_and_b32_e32 v19, 0xffff0000, v19
	v_pk_mul_f32 v[114:115], v[194:195], v[156:157]
	v_pk_mul_f32 v[116:117], v[196:197], v[12:13]
	v_pk_mul_f32 v[118:119], v[198:199], v[158:159]
	v_pk_mul_f32 v[120:121], v[200:201], v[14:15]
	v_pk_mul_f32 v[122:123], v[202:203], v[160:161]
	v_pk_mul_f32 v[124:125], v[204:205], v[16:17]
	v_pk_mul_f32 v[126:127], v[206:207], v[162:163]
	v_pk_mul_f32 v[128:129], v[208:209], v[18:19]
	v_pk_mul_f32 v[114:115], v[10:11], v[114:115]
	v_pk_mul_f32 v[116:117], v[10:11], v[116:117]
	v_pk_mul_f32 v[118:119], v[10:11], v[118:119]
	v_pk_mul_f32 v[120:121], v[10:11], v[120:121]
	v_pk_mul_f32 v[122:123], v[10:11], v[122:123]
	v_pk_mul_f32 v[124:125], v[10:11], v[124:125]
	v_pk_mul_f32 v[126:127], v[10:11], v[126:127]
	v_pk_mul_f32 v[128:129], v[10:11], v[128:129]
	v_pk_fma_f32 v[114:115], v[20:21], s[28:29], v[114:115] op_sel_hi:[1,0,1]
	v_pk_fma_f32 v[116:117], v[22:23], s[28:29], v[116:117] op_sel_hi:[1,0,1]
	v_pk_fma_f32 v[118:119], v[24:25], s[28:29], v[118:119] op_sel_hi:[1,0,1]
	v_pk_fma_f32 v[120:121], v[26:27], s[28:29], v[120:121] op_sel_hi:[1,0,1]
	v_pk_fma_f32 v[122:123], v[0:1], s[28:29], v[122:123] op_sel_hi:[1,0,1]
	v_pk_fma_f32 v[124:125], v[2:3], s[28:29], v[124:125] op_sel_hi:[1,0,1]
	v_pk_fma_f32 v[126:127], v[4:5], s[28:29], v[126:127] op_sel_hi:[1,0,1]
	v_pk_fma_f32 v[128:129], v[6:7], s[28:29], v[128:129] op_sel_hi:[1,0,1]
	v_add_f32_e32 v164, v114, v115
	v_add_f32_e32 v165, v116, v117
	v_add_f32_e32 v166, v118, v119
	v_add_f32_e32 v167, v120, v121
	v_add_f32_e32 v168, v122, v123
	v_add_f32_e32 v169, v124, v125
	v_add_f32_e32 v242, v126, v127
	v_add_f32_e32 v243, v128, v129
	v_add_f32_e32 v164, v164, v165
	v_add_f32_e32 v166, v166, v167
	v_add_f32_e32 v168, v168, v169
	v_add_f32_e32 v242, v242, v243
	v_add_f32_e32 v9, 0, v164
	v_add_f32_e32 v9, v9, v166
	v_add_f32_e32 v9, v9, v168
	v_add_f32_e32 v9, v9, v242
	ds_bpermute_b32 v28, v96, v9
	s_waitcnt lgkmcnt(0)
	v_add_f32_e32 v9, v9, v28
	ds_swizzle_b32 v28, v9 offset:swizzle(SWAP,16)
	s_waitcnt lgkmcnt(0)
	v_add_f32_e32 v9, v9, v28
	ds_swizzle_b32 v28, v9 offset:swizzle(SWAP,8)
	s_waitcnt lgkmcnt(0)
	v_add_f32_e32 v9, v9, v28
	ds_swizzle_b32 v28, v9 offset:swizzle(SWAP,4)
	s_waitcnt lgkmcnt(0)
	v_add_f32_e32 v9, v9, v28
	ds_swizzle_b32 v28, v9 offset:swizzle(SWAP,2)
	s_waitcnt lgkmcnt(0)
	v_add_f32_e32 v9, v9, v28
	ds_swizzle_b32 v28, v9 offset:swizzle(SWAP,1)
	s_waitcnt lgkmcnt(0)
	v_add_f32_e32 v9, v9, v28
	v_fmac_f32_e32 v114, 0xba800000, v9
	v_fmac_f32_e32 v115, 0xba800000, v9
	v_fmac_f32_e32 v116, 0xba800000, v9
	v_fmac_f32_e32 v117, 0xba800000, v9
	v_fmac_f32_e32 v118, 0xba800000, v9
	v_fmac_f32_e32 v119, 0xba800000, v9
	v_fmac_f32_e32 v120, 0xba800000, v9
	v_fmac_f32_e32 v121, 0xba800000, v9
	v_fmac_f32_e32 v122, 0xba800000, v9
	v_fmac_f32_e32 v123, 0xba800000, v9
	v_fmac_f32_e32 v124, 0xba800000, v9
	v_fmac_f32_e32 v125, 0xba800000, v9
	v_fmac_f32_e32 v126, 0xba800000, v9
	v_fmac_f32_e32 v127, 0xba800000, v9
	v_fmac_f32_e32 v128, 0xba800000, v9
	v_fmac_f32_e32 v129, 0xba800000, v9
	v_pk_mul_f32 v[244:245], v[114:115], v[114:115]
	v_pk_mul_f32 v[246:247], v[116:117], v[116:117]
	v_add_f32_e32 v244, v245, v244
	v_add_f32_e32 v246, v246, v247
	v_add_f32_e32 v164, v244, v246
	v_pk_mul_f32 v[244:245], v[118:119], v[118:119]
	v_pk_mul_f32 v[246:247], v[120:121], v[120:121]
	v_add_f32_e32 v244, v245, v244
	v_add_f32_e32 v246, v246, v247
	v_add_f32_e32 v165, v244, v246
	v_mul_f32_e32 v248, v122, v122
	v_mul_f32_e32 v249, v124, v124
	v_fmac_f32_e32 v248, v123, v123
	v_fmac_f32_e32 v249, v125, v125
	v_add_f32_e32 v166, v248, v249
	v_pk_mul_f32 v[244:245], v[126:127], v[126:127]
	v_pk_mul_f32 v[246:247], v[128:129], v[128:129]
	v_add_f32_e32 v244, v244, v245
	v_add_f32_e32 v246, v246, v247
	v_add_f32_e32 v167, v244, v246
	v_add_f32_e32 v164, v164, v165
	v_add_f32_e32 v164, v166, v164
	v_add_f32_e32 v9, v167, v164
	ds_bpermute_b32 v28, v96, v9
	s_waitcnt lgkmcnt(0)
	v_add_f32_e32 v9, v9, v28
	ds_swizzle_b32 v28, v9 offset:swizzle(SWAP,16)
	s_waitcnt lgkmcnt(0)
	v_add_f32_e32 v9, v9, v28
	ds_swizzle_b32 v28, v9 offset:swizzle(SWAP,8)
	s_waitcnt lgkmcnt(0)
	v_add_f32_e32 v9, v9, v28
	ds_swizzle_b32 v28, v9 offset:swizzle(SWAP,4)
	s_waitcnt lgkmcnt(0)
	v_add_f32_e32 v9, v9, v28
	ds_swizzle_b32 v28, v9 offset:swizzle(SWAP,2)
	s_waitcnt lgkmcnt(0)
	v_add_f32_e32 v9, v9, v28
	ds_swizzle_b32 v28, v9 offset:swizzle(SWAP,1)
	s_waitcnt lgkmcnt(0)
	v_add_f32_e32 v9, v9, v28
	v_mov_b32_e32 v28, 0x3727c5ac
	v_fmamk_f32 v9, v9, 0x3a800000, v28
	v_mul_f32_e32 v28, 0x4b800000, v9
	v_cmp_gt_f32_e32 vcc, s37, v9
	s_nop 1
	v_cndmask_b32_e32 v9, v9, v28, vcc
	v_rsq_f32_e32 v9, v9
	s_nop 0
	v_mul_f32_e32 v28, 0x45800000, v9
	v_cndmask_b32_e32 v30, v9, v28, vcc
	v_pk_mul_f32 v[114:115], v[114:115], v[30:31] op_sel_hi:[1,0]
	v_pk_mul_f32 v[116:117], v[116:117], v[30:31] op_sel_hi:[1,0]
	v_pk_fma_f32 v[20:21], v[140:141], v[114:115], v[98:99]
	v_pk_fma_f32 v[22:23], v[142:143], v[116:117], v[100:101]
	global_store_dwordx4 v[86:87], v[20:23], off sc1 nt
	v_pk_fma_f32 v[114:115], v[226:227], v[20:21], v[210:211]
	v_pk_fma_f32 v[116:117], v[228:229], v[22:23], v[212:213]
	s_nop 0
	v_cvt_pk_bf16_f32 v12, v114, v115
	v_cvt_pk_bf16_f32 v13, v116, v117
	global_store_dwordx2 v[88:89], v[12:13], off sc1
	v_pk_mul_f32 v[118:119], v[118:119], v[30:31] op_sel_hi:[1,0]
	v_pk_mul_f32 v[120:121], v[120:121], v[30:31] op_sel_hi:[1,0]
	v_pk_fma_f32 v[24:25], v[144:145], v[118:119], v[102:103]
	v_pk_fma_f32 v[26:27], v[146:147], v[120:121], v[104:105]
	global_store_dwordx4 v[86:87], v[24:27], off offset:1024 sc1 nt
	v_pk_fma_f32 v[118:119], v[230:231], v[24:25], v[214:215]
	v_pk_fma_f32 v[120:121], v[232:233], v[26:27], v[216:217]
	s_nop 0
	v_cvt_pk_bf16_f32 v14, v118, v119
	v_cvt_pk_bf16_f32 v15, v120, v121
	global_store_dwordx2 v[88:89], v[14:15], off offset:512 sc1
	v_pk_mul_f32 v[122:123], v[122:123], v[30:31] op_sel_hi:[1,0]
	v_pk_mul_f32 v[124:125], v[124:125], v[30:31] op_sel_hi:[1,0]
	v_pk_fma_f32 v[0:1], v[148:149], v[122:123], v[106:107]
	v_pk_fma_f32 v[2:3], v[150:151], v[124:125], v[108:109]
	global_store_dwordx4 v[86:87], v[0:3], off offset:2048 sc1 nt
	v_pk_fma_f32 v[122:123], v[234:235], v[0:1], v[218:219]
	v_pk_fma_f32 v[124:125], v[236:237], v[2:3], v[220:221]
	s_nop 0
	v_cvt_pk_bf16_f32 v16, v122, v123
	v_cvt_pk_bf16_f32 v17, v124, v125
	global_store_dwordx2 v[88:89], v[16:17], off offset:1024 sc1
	v_pk_mul_f32 v[126:127], v[126:127], v[30:31] op_sel_hi:[1,0]
	v_pk_mul_f32 v[128:129], v[128:129], v[30:31] op_sel_hi:[1,0]
	v_pk_fma_f32 v[4:5], v[152:153], v[126:127], v[110:111]
	v_pk_fma_f32 v[6:7], v[154:155], v[128:129], v[112:113]
	global_store_dwordx4 v[86:87], v[4:7], off offset:3072 sc1 nt
	v_pk_fma_f32 v[126:127], v[238:239], v[4:5], v[222:223]
	v_pk_fma_f32 v[128:129], v[240:241], v[6:7], v[224:225]
	s_nop 0
	v_cvt_pk_bf16_f32 v18, v126, v127
	v_cvt_pk_bf16_f32 v19, v128, v129
	global_store_dwordx2 v[88:89], v[18:19], off offset:1536 sc1
	v_lshl_add_u64 v[86:87], v[86:87], 0, s[0:1]
	v_lshl_add_u64 v[88:89], v[88:89], 0, s[20:21]
	global_load_dwordx4 v[20:23], v[82:83], off nt
	global_load_dwordx4 v[24:27], v[82:83], off offset:1024 nt
	global_load_dwordx4 v[0:3], v[82:83], off offset:2048 nt
	global_load_dwordx4 v[4:7], v[82:83], off offset:3072 nt
	global_load_dwordx2 v[12:13], v[84:85], off
	global_load_dwordx2 v[14:15], v[84:85], off offset:512
	global_load_dwordx2 v[16:17], v[84:85], off offset:1024
	global_load_dwordx2 v[18:19], v[84:85], off offset:1536
	v_lshl_add_u64 v[82:83], v[82:83], 0, s[0:1]
	v_lshl_add_u64 v[84:85], v[84:85], 0, s[20:21]
	s_waitcnt vmcnt(32)
	v_lshlrev_b32_e32 v156, 16, v50
	v_and_b32_e32 v157, 0xffff0000, v50
	v_lshlrev_b32_e32 v50, 16, v51
	v_and_b32_e32 v51, 0xffff0000, v51
	v_lshlrev_b32_e32 v158, 16, v52
	v_and_b32_e32 v159, 0xffff0000, v52
	v_lshlrev_b32_e32 v52, 16, v53
	v_and_b32_e32 v53, 0xffff0000, v53
	v_lshlrev_b32_e32 v160, 16, v54
	v_and_b32_e32 v161, 0xffff0000, v54
	v_lshlrev_b32_e32 v54, 16, v55
	v_and_b32_e32 v55, 0xffff0000, v55
	v_lshlrev_b32_e32 v162, 16, v56
	v_and_b32_e32 v163, 0xffff0000, v56
	v_lshlrev_b32_e32 v56, 16, v57
	v_and_b32_e32 v57, 0xffff0000, v57
	v_pk_mul_f32 v[114:115], v[194:195], v[156:157]
	v_pk_mul_f32 v[116:117], v[196:197], v[50:51]
	v_pk_mul_f32 v[118:119], v[198:199], v[158:159]
	v_pk_mul_f32 v[120:121], v[200:201], v[52:53]
	v_pk_mul_f32 v[122:123], v[202:203], v[160:161]
	v_pk_mul_f32 v[124:125], v[204:205], v[54:55]
	v_pk_mul_f32 v[126:127], v[206:207], v[162:163]
	v_pk_mul_f32 v[128:129], v[208:209], v[56:57]
	v_pk_mul_f32 v[114:115], v[10:11], v[114:115]
	v_pk_mul_f32 v[116:117], v[10:11], v[116:117]
	v_pk_mul_f32 v[118:119], v[10:11], v[118:119]
	v_pk_mul_f32 v[120:121], v[10:11], v[120:121]
	v_pk_mul_f32 v[122:123], v[10:11], v[122:123]
	v_pk_mul_f32 v[124:125], v[10:11], v[124:125]
	v_pk_mul_f32 v[126:127], v[10:11], v[126:127]
	v_pk_mul_f32 v[128:129], v[10:11], v[128:129]
	v_pk_fma_f32 v[114:115], v[34:35], s[28:29], v[114:115] op_sel_hi:[1,0,1]
	v_pk_fma_f32 v[116:117], v[36:37], s[28:29], v[116:117] op_sel_hi:[1,0,1]
	v_pk_fma_f32 v[118:119], v[38:39], s[28:29], v[118:119] op_sel_hi:[1,0,1]
	v_pk_fma_f32 v[120:121], v[40:41], s[28:29], v[120:121] op_sel_hi:[1,0,1]
	v_pk_fma_f32 v[122:123], v[42:43], s[28:29], v[122:123] op_sel_hi:[1,0,1]
	v_pk_fma_f32 v[124:125], v[44:45], s[28:29], v[124:125] op_sel_hi:[1,0,1]
	v_pk_fma_f32 v[126:127], v[46:47], s[28:29], v[126:127] op_sel_hi:[1,0,1]
	v_pk_fma_f32 v[128:129], v[48:49], s[28:29], v[128:129] op_sel_hi:[1,0,1]
	v_add_f32_e32 v164, v114, v115
	v_add_f32_e32 v165, v116, v117
	v_add_f32_e32 v166, v118, v119
	v_add_f32_e32 v167, v120, v121
	v_add_f32_e32 v168, v122, v123
	v_add_f32_e32 v169, v124, v125
	v_add_f32_e32 v242, v126, v127
	v_add_f32_e32 v243, v128, v129
	v_add_f32_e32 v164, v164, v165
	v_add_f32_e32 v166, v166, v167
	v_add_f32_e32 v168, v168, v169
	v_add_f32_e32 v242, v242, v243
	v_add_f32_e32 v9, 0, v164
	v_add_f32_e32 v9, v9, v166
	v_add_f32_e32 v9, v9, v168
	v_add_f32_e32 v9, v9, v242
	ds_bpermute_b32 v28, v96, v9
	s_waitcnt lgkmcnt(0)
	v_add_f32_e32 v9, v9, v28
	ds_swizzle_b32 v28, v9 offset:swizzle(SWAP,16)
	s_waitcnt lgkmcnt(0)
	v_add_f32_e32 v9, v9, v28
	ds_swizzle_b32 v28, v9 offset:swizzle(SWAP,8)
	s_waitcnt lgkmcnt(0)
	v_add_f32_e32 v9, v9, v28
	ds_swizzle_b32 v28, v9 offset:swizzle(SWAP,4)
	s_waitcnt lgkmcnt(0)
	v_add_f32_e32 v9, v9, v28
	ds_swizzle_b32 v28, v9 offset:swizzle(SWAP,2)
	s_waitcnt lgkmcnt(0)
	v_add_f32_e32 v9, v9, v28
	ds_swizzle_b32 v28, v9 offset:swizzle(SWAP,1)
	s_waitcnt lgkmcnt(0)
	v_add_f32_e32 v9, v9, v28
	v_fmac_f32_e32 v114, 0xba800000, v9
	v_fmac_f32_e32 v115, 0xba800000, v9
	v_fmac_f32_e32 v116, 0xba800000, v9
	v_fmac_f32_e32 v117, 0xba800000, v9
	v_fmac_f32_e32 v118, 0xba800000, v9
	v_fmac_f32_e32 v119, 0xba800000, v9
	v_fmac_f32_e32 v120, 0xba800000, v9
	v_fmac_f32_e32 v121, 0xba800000, v9
	v_fmac_f32_e32 v122, 0xba800000, v9
	v_fmac_f32_e32 v123, 0xba800000, v9
	v_fmac_f32_e32 v124, 0xba800000, v9
	v_fmac_f32_e32 v125, 0xba800000, v9
	v_fmac_f32_e32 v126, 0xba800000, v9
	v_fmac_f32_e32 v127, 0xba800000, v9
	v_fmac_f32_e32 v128, 0xba800000, v9
	v_fmac_f32_e32 v129, 0xba800000, v9
	v_pk_mul_f32 v[244:245], v[114:115], v[114:115]
	v_pk_mul_f32 v[246:247], v[116:117], v[116:117]
	v_add_f32_e32 v244, v245, v244
	v_add_f32_e32 v246, v246, v247
	v_add_f32_e32 v164, v244, v246
	v_pk_mul_f32 v[244:245], v[118:119], v[118:119]
	v_pk_mul_f32 v[246:247], v[120:121], v[120:121]
	v_add_f32_e32 v244, v245, v244
	v_add_f32_e32 v246, v246, v247
	v_add_f32_e32 v165, v244, v246
	v_mul_f32_e32 v248, v122, v122
	v_mul_f32_e32 v249, v124, v124
	v_fmac_f32_e32 v248, v123, v123
	v_fmac_f32_e32 v249, v125, v125
	v_add_f32_e32 v166, v248, v249
	v_pk_mul_f32 v[244:245], v[126:127], v[126:127]
	v_pk_mul_f32 v[246:247], v[128:129], v[128:129]
	v_add_f32_e32 v244, v244, v245
	v_add_f32_e32 v246, v246, v247
	v_add_f32_e32 v167, v244, v246
	v_add_f32_e32 v164, v164, v165
	v_add_f32_e32 v164, v166, v164
	v_add_f32_e32 v9, v167, v164
	ds_bpermute_b32 v28, v96, v9
	s_waitcnt lgkmcnt(0)
	v_add_f32_e32 v9, v9, v28
	ds_swizzle_b32 v28, v9 offset:swizzle(SWAP,16)
	s_waitcnt lgkmcnt(0)
	v_add_f32_e32 v9, v9, v28
	ds_swizzle_b32 v28, v9 offset:swizzle(SWAP,8)
	s_waitcnt lgkmcnt(0)
	v_add_f32_e32 v9, v9, v28
	ds_swizzle_b32 v28, v9 offset:swizzle(SWAP,4)
	s_waitcnt lgkmcnt(0)
	v_add_f32_e32 v9, v9, v28
	ds_swizzle_b32 v28, v9 offset:swizzle(SWAP,2)
	s_waitcnt lgkmcnt(0)
	v_add_f32_e32 v9, v9, v28
	ds_swizzle_b32 v28, v9 offset:swizzle(SWAP,1)
	s_waitcnt lgkmcnt(0)
	v_add_f32_e32 v9, v9, v28
	v_mov_b32_e32 v28, 0x3727c5ac
	v_fmamk_f32 v9, v9, 0x3a800000, v28
	v_mul_f32_e32 v28, 0x4b800000, v9
	v_cmp_gt_f32_e32 vcc, s37, v9
	s_nop 1
	v_cndmask_b32_e32 v9, v9, v28, vcc
	v_rsq_f32_e32 v9, v9
	s_nop 0
	v_mul_f32_e32 v28, 0x45800000, v9
	v_cndmask_b32_e32 v30, v9, v28, vcc
	v_pk_mul_f32 v[114:115], v[114:115], v[30:31] op_sel_hi:[1,0]
	v_pk_mul_f32 v[116:117], v[116:117], v[30:31] op_sel_hi:[1,0]
	v_pk_fma_f32 v[34:35], v[140:141], v[114:115], v[98:99]
	v_pk_fma_f32 v[36:37], v[142:143], v[116:117], v[100:101]
	global_store_dwordx4 v[86:87], v[34:37], off sc1 nt
	v_pk_fma_f32 v[114:115], v[226:227], v[34:35], v[210:211]
	v_pk_fma_f32 v[116:117], v[228:229], v[36:37], v[212:213]
	s_nop 0
	v_cvt_pk_bf16_f32 v50, v114, v115
	v_cvt_pk_bf16_f32 v51, v116, v117
	global_store_dwordx2 v[88:89], v[50:51], off sc1
	v_pk_mul_f32 v[118:119], v[118:119], v[30:31] op_sel_hi:[1,0]
	v_pk_mul_f32 v[120:121], v[120:121], v[30:31] op_sel_hi:[1,0]
	v_pk_fma_f32 v[38:39], v[144:145], v[118:119], v[102:103]
	v_pk_fma_f32 v[40:41], v[146:147], v[120:121], v[104:105]
	global_store_dwordx4 v[86:87], v[38:41], off offset:1024 sc1 nt
	v_pk_fma_f32 v[118:119], v[230:231], v[38:39], v[214:215]
	v_pk_fma_f32 v[120:121], v[232:233], v[40:41], v[216:217]
	s_nop 0
	v_cvt_pk_bf16_f32 v52, v118, v119
	v_cvt_pk_bf16_f32 v53, v120, v121
	global_store_dwordx2 v[88:89], v[52:53], off offset:512 sc1
	v_pk_mul_f32 v[122:123], v[122:123], v[30:31] op_sel_hi:[1,0]
	v_pk_mul_f32 v[124:125], v[124:125], v[30:31] op_sel_hi:[1,0]
	v_pk_fma_f32 v[42:43], v[148:149], v[122:123], v[106:107]
	v_pk_fma_f32 v[44:45], v[150:151], v[124:125], v[108:109]
	global_store_dwordx4 v[86:87], v[42:45], off offset:2048 sc1 nt
	v_pk_fma_f32 v[122:123], v[234:235], v[42:43], v[218:219]
	v_pk_fma_f32 v[124:125], v[236:237], v[44:45], v[220:221]
	s_nop 0
	v_cvt_pk_bf16_f32 v54, v122, v123
	v_cvt_pk_bf16_f32 v55, v124, v125
	global_store_dwordx2 v[88:89], v[54:55], off offset:1024 sc1
	v_pk_mul_f32 v[126:127], v[126:127], v[30:31] op_sel_hi:[1,0]
	v_pk_mul_f32 v[128:129], v[128:129], v[30:31] op_sel_hi:[1,0]
	v_pk_fma_f32 v[46:47], v[152:153], v[126:127], v[110:111]
	v_pk_fma_f32 v[48:49], v[154:155], v[128:129], v[112:113]
	global_store_dwordx4 v[86:87], v[46:49], off offset:3072 sc1 nt
	v_pk_fma_f32 v[126:127], v[238:239], v[46:47], v[222:223]
	v_pk_fma_f32 v[128:129], v[240:241], v[48:49], v[224:225]
	s_nop 0
	v_cvt_pk_bf16_f32 v56, v126, v127
	v_cvt_pk_bf16_f32 v57, v128, v129
	global_store_dwordx2 v[88:89], v[56:57], off offset:1536 sc1
	v_lshl_add_u64 v[86:87], v[86:87], 0, s[0:1]
	v_lshl_add_u64 v[88:89], v[88:89], 0, s[20:21]
	global_load_dwordx4 v[34:37], v[82:83], off nt
	global_load_dwordx4 v[38:41], v[82:83], off offset:1024 nt
	global_load_dwordx4 v[42:45], v[82:83], off offset:2048 nt
	global_load_dwordx4 v[46:49], v[82:83], off offset:3072 nt
	global_load_dwordx2 v[50:51], v[84:85], off
	global_load_dwordx2 v[52:53], v[84:85], off offset:512
	global_load_dwordx2 v[54:55], v[84:85], off offset:1024
	global_load_dwordx2 v[56:57], v[84:85], off offset:1536
	v_lshl_add_u64 v[82:83], v[82:83], 0, s[0:1]
	v_lshl_add_u64 v[84:85], v[84:85], 0, s[20:21]
	s_waitcnt vmcnt(32)
	v_lshlrev_b32_e32 v156, 16, v74
	v_and_b32_e32 v157, 0xffff0000, v74
	v_lshlrev_b32_e32 v74, 16, v75
	v_and_b32_e32 v75, 0xffff0000, v75
	v_lshlrev_b32_e32 v158, 16, v76
	v_and_b32_e32 v159, 0xffff0000, v76
	v_lshlrev_b32_e32 v76, 16, v77
	v_and_b32_e32 v77, 0xffff0000, v77
	v_lshlrev_b32_e32 v160, 16, v78
	v_and_b32_e32 v161, 0xffff0000, v78
	v_lshlrev_b32_e32 v78, 16, v79
	v_and_b32_e32 v79, 0xffff0000, v79
	v_lshlrev_b32_e32 v162, 16, v80
	v_and_b32_e32 v163, 0xffff0000, v80
	v_lshlrev_b32_e32 v80, 16, v81
	v_and_b32_e32 v81, 0xffff0000, v81
	v_pk_mul_f32 v[114:115], v[194:195], v[156:157]
	v_pk_mul_f32 v[116:117], v[196:197], v[74:75]
	v_pk_mul_f32 v[118:119], v[198:199], v[158:159]
	v_pk_mul_f32 v[120:121], v[200:201], v[76:77]
	v_pk_mul_f32 v[122:123], v[202:203], v[160:161]
	v_pk_mul_f32 v[124:125], v[204:205], v[78:79]
	v_pk_mul_f32 v[126:127], v[206:207], v[162:163]
	v_pk_mul_f32 v[128:129], v[208:209], v[80:81]
	v_pk_mul_f32 v[114:115], v[10:11], v[114:115]
	v_pk_mul_f32 v[116:117], v[10:11], v[116:117]
	v_pk_mul_f32 v[118:119], v[10:11], v[118:119]
	v_pk_mul_f32 v[120:121], v[10:11], v[120:121]
	v_pk_mul_f32 v[122:123], v[10:11], v[122:123]
	v_pk_mul_f32 v[124:125], v[10:11], v[124:125]
	v_pk_mul_f32 v[126:127], v[10:11], v[126:127]
	v_pk_mul_f32 v[128:129], v[10:11], v[128:129]
	v_pk_fma_f32 v[114:115], v[58:59], s[28:29], v[114:115] op_sel_hi:[1,0,1]
	v_pk_fma_f32 v[116:117], v[60:61], s[28:29], v[116:117] op_sel_hi:[1,0,1]
	v_pk_fma_f32 v[118:119], v[62:63], s[28:29], v[118:119] op_sel_hi:[1,0,1]
	v_pk_fma_f32 v[120:121], v[64:65], s[28:29], v[120:121] op_sel_hi:[1,0,1]
	v_pk_fma_f32 v[122:123], v[66:67], s[28:29], v[122:123] op_sel_hi:[1,0,1]
	v_pk_fma_f32 v[124:125], v[68:69], s[28:29], v[124:125] op_sel_hi:[1,0,1]
	v_pk_fma_f32 v[126:127], v[70:71], s[28:29], v[126:127] op_sel_hi:[1,0,1]
	v_pk_fma_f32 v[128:129], v[72:73], s[28:29], v[128:129] op_sel_hi:[1,0,1]
	v_add_f32_e32 v164, v114, v115
	v_add_f32_e32 v165, v116, v117
	v_add_f32_e32 v166, v118, v119
	v_add_f32_e32 v167, v120, v121
	v_add_f32_e32 v168, v122, v123
	v_add_f32_e32 v169, v124, v125
	v_add_f32_e32 v242, v126, v127
	v_add_f32_e32 v243, v128, v129
	v_add_f32_e32 v164, v164, v165
	v_add_f32_e32 v166, v166, v167
	v_add_f32_e32 v168, v168, v169
	v_add_f32_e32 v242, v242, v243
	v_add_f32_e32 v9, 0, v164
	v_add_f32_e32 v9, v9, v166
	v_add_f32_e32 v9, v9, v168
	v_add_f32_e32 v9, v9, v242
	ds_bpermute_b32 v28, v96, v9
	s_waitcnt lgkmcnt(0)
	v_add_f32_e32 v9, v9, v28
	ds_swizzle_b32 v28, v9 offset:swizzle(SWAP,16)
	s_waitcnt lgkmcnt(0)
	v_add_f32_e32 v9, v9, v28
	ds_swizzle_b32 v28, v9 offset:swizzle(SWAP,8)
	s_waitcnt lgkmcnt(0)
	v_add_f32_e32 v9, v9, v28
	ds_swizzle_b32 v28, v9 offset:swizzle(SWAP,4)
	s_waitcnt lgkmcnt(0)
	v_add_f32_e32 v9, v9, v28
	ds_swizzle_b32 v28, v9 offset:swizzle(SWAP,2)
	s_waitcnt lgkmcnt(0)
	v_add_f32_e32 v9, v9, v28
	ds_swizzle_b32 v28, v9 offset:swizzle(SWAP,1)
	s_waitcnt lgkmcnt(0)
	v_add_f32_e32 v9, v9, v28
	v_fmac_f32_e32 v114, 0xba800000, v9
	v_fmac_f32_e32 v115, 0xba800000, v9
	v_fmac_f32_e32 v116, 0xba800000, v9
	v_fmac_f32_e32 v117, 0xba800000, v9
	v_fmac_f32_e32 v118, 0xba800000, v9
	v_fmac_f32_e32 v119, 0xba800000, v9
	v_fmac_f32_e32 v120, 0xba800000, v9
	v_fmac_f32_e32 v121, 0xba800000, v9
	v_fmac_f32_e32 v122, 0xba800000, v9
	v_fmac_f32_e32 v123, 0xba800000, v9
	v_fmac_f32_e32 v124, 0xba800000, v9
	v_fmac_f32_e32 v125, 0xba800000, v9
	v_fmac_f32_e32 v126, 0xba800000, v9
	v_fmac_f32_e32 v127, 0xba800000, v9
	v_fmac_f32_e32 v128, 0xba800000, v9
	v_fmac_f32_e32 v129, 0xba800000, v9
	v_pk_mul_f32 v[244:245], v[114:115], v[114:115]
	v_pk_mul_f32 v[246:247], v[116:117], v[116:117]
	v_add_f32_e32 v244, v245, v244
	v_add_f32_e32 v246, v246, v247
	v_add_f32_e32 v164, v244, v246
	v_pk_mul_f32 v[244:245], v[118:119], v[118:119]
	v_pk_mul_f32 v[246:247], v[120:121], v[120:121]
	v_add_f32_e32 v244, v245, v244
	v_add_f32_e32 v246, v246, v247
	v_add_f32_e32 v165, v244, v246
	v_mul_f32_e32 v248, v122, v122
	v_mul_f32_e32 v249, v124, v124
	v_fmac_f32_e32 v248, v123, v123
	v_fmac_f32_e32 v249, v125, v125
	v_add_f32_e32 v166, v248, v249
	v_pk_mul_f32 v[244:245], v[126:127], v[126:127]
	v_pk_mul_f32 v[246:247], v[128:129], v[128:129]
	v_add_f32_e32 v244, v244, v245
	v_add_f32_e32 v246, v246, v247
	v_add_f32_e32 v167, v244, v246
	v_add_f32_e32 v164, v164, v165
	v_add_f32_e32 v164, v166, v164
	v_add_f32_e32 v9, v167, v164
	ds_bpermute_b32 v28, v96, v9
	s_waitcnt lgkmcnt(0)
	v_add_f32_e32 v9, v9, v28
	ds_swizzle_b32 v28, v9 offset:swizzle(SWAP,16)
	s_waitcnt lgkmcnt(0)
	v_add_f32_e32 v9, v9, v28
	ds_swizzle_b32 v28, v9 offset:swizzle(SWAP,8)
	s_waitcnt lgkmcnt(0)
	v_add_f32_e32 v9, v9, v28
	ds_swizzle_b32 v28, v9 offset:swizzle(SWAP,4)
	s_waitcnt lgkmcnt(0)
	v_add_f32_e32 v9, v9, v28
	ds_swizzle_b32 v28, v9 offset:swizzle(SWAP,2)
	s_waitcnt lgkmcnt(0)
	v_add_f32_e32 v9, v9, v28
	ds_swizzle_b32 v28, v9 offset:swizzle(SWAP,1)
	s_waitcnt lgkmcnt(0)
	v_add_f32_e32 v9, v9, v28
	v_mov_b32_e32 v28, 0x3727c5ac
	v_fmamk_f32 v9, v9, 0x3a800000, v28
	v_mul_f32_e32 v28, 0x4b800000, v9
	v_cmp_gt_f32_e32 vcc, s37, v9
	s_nop 1
	v_cndmask_b32_e32 v9, v9, v28, vcc
	v_rsq_f32_e32 v9, v9
	s_nop 0
	v_mul_f32_e32 v28, 0x45800000, v9
	v_cndmask_b32_e32 v30, v9, v28, vcc
	v_pk_mul_f32 v[114:115], v[114:115], v[30:31] op_sel_hi:[1,0]
	v_pk_mul_f32 v[116:117], v[116:117], v[30:31] op_sel_hi:[1,0]
	v_pk_fma_f32 v[58:59], v[140:141], v[114:115], v[98:99]
	v_pk_fma_f32 v[60:61], v[142:143], v[116:117], v[100:101]
	global_store_dwordx4 v[86:87], v[58:61], off sc1 nt
	v_pk_fma_f32 v[114:115], v[226:227], v[58:59], v[210:211]
	v_pk_fma_f32 v[116:117], v[228:229], v[60:61], v[212:213]
	s_nop 0
	v_cvt_pk_bf16_f32 v74, v114, v115
	v_cvt_pk_bf16_f32 v75, v116, v117
	global_store_dwordx2 v[88:89], v[74:75], off sc1
	v_pk_mul_f32 v[118:119], v[118:119], v[30:31] op_sel_hi:[1,0]
	v_pk_mul_f32 v[120:121], v[120:121], v[30:31] op_sel_hi:[1,0]
	v_pk_fma_f32 v[62:63], v[144:145], v[118:119], v[102:103]
	v_pk_fma_f32 v[64:65], v[146:147], v[120:121], v[104:105]
	global_store_dwordx4 v[86:87], v[62:65], off offset:1024 sc1 nt
	v_pk_fma_f32 v[118:119], v[230:231], v[62:63], v[214:215]
	v_pk_fma_f32 v[120:121], v[232:233], v[64:65], v[216:217]
	s_nop 0
	v_cvt_pk_bf16_f32 v76, v118, v119
	v_cvt_pk_bf16_f32 v77, v120, v121
	global_store_dwordx2 v[88:89], v[76:77], off offset:512 sc1
	v_pk_mul_f32 v[122:123], v[122:123], v[30:31] op_sel_hi:[1,0]
	v_pk_mul_f32 v[124:125], v[124:125], v[30:31] op_sel_hi:[1,0]
	v_pk_fma_f32 v[66:67], v[148:149], v[122:123], v[106:107]
	v_pk_fma_f32 v[68:69], v[150:151], v[124:125], v[108:109]
	global_store_dwordx4 v[86:87], v[66:69], off offset:2048 sc1 nt
	v_pk_fma_f32 v[122:123], v[234:235], v[66:67], v[218:219]
	v_pk_fma_f32 v[124:125], v[236:237], v[68:69], v[220:221]
	s_nop 0
	v_cvt_pk_bf16_f32 v78, v122, v123
	v_cvt_pk_bf16_f32 v79, v124, v125
	global_store_dwordx2 v[88:89], v[78:79], off offset:1024 sc1
	v_pk_mul_f32 v[126:127], v[126:127], v[30:31] op_sel_hi:[1,0]
	v_pk_mul_f32 v[128:129], v[128:129], v[30:31] op_sel_hi:[1,0]
	v_pk_fma_f32 v[70:71], v[152:153], v[126:127], v[110:111]
	v_pk_fma_f32 v[72:73], v[154:155], v[128:129], v[112:113]
	global_store_dwordx4 v[86:87], v[70:73], off offset:3072 sc1 nt
	v_pk_fma_f32 v[126:127], v[238:239], v[70:71], v[222:223]
	v_pk_fma_f32 v[128:129], v[240:241], v[72:73], v[224:225]
	s_nop 0
	v_cvt_pk_bf16_f32 v80, v126, v127
	v_cvt_pk_bf16_f32 v81, v128, v129
	global_store_dwordx2 v[88:89], v[80:81], off offset:1536 sc1
	v_lshl_add_u64 v[86:87], v[86:87], 0, s[0:1]
	v_lshl_add_u64 v[88:89], v[88:89], 0, s[20:21]
	global_load_dwordx4 v[58:61], v[82:83], off nt
	global_load_dwordx4 v[62:65], v[82:83], off offset:1024 nt
	global_load_dwordx4 v[66:69], v[82:83], off offset:2048 nt
	global_load_dwordx4 v[70:73], v[82:83], off offset:3072 nt
	global_load_dwordx2 v[74:75], v[84:85], off
	global_load_dwordx2 v[76:77], v[84:85], off offset:512
	global_load_dwordx2 v[78:79], v[84:85], off offset:1024
	global_load_dwordx2 v[80:81], v[84:85], off offset:1536
	v_lshl_add_u64 v[82:83], v[82:83], 0, s[0:1]
	v_lshl_add_u64 v[84:85], v[84:85], 0, s[20:21]
	s_waitcnt vmcnt(32)
	v_lshlrev_b32_e32 v156, 16, v12
	v_and_b32_e32 v157, 0xffff0000, v12
	v_lshlrev_b32_e32 v12, 16, v13
	v_and_b32_e32 v13, 0xffff0000, v13
	v_lshlrev_b32_e32 v158, 16, v14
	v_and_b32_e32 v159, 0xffff0000, v14
	v_lshlrev_b32_e32 v14, 16, v15
	v_and_b32_e32 v15, 0xffff0000, v15
	v_lshlrev_b32_e32 v160, 16, v16
	v_and_b32_e32 v161, 0xffff0000, v16
	v_lshlrev_b32_e32 v16, 16, v17
	v_and_b32_e32 v17, 0xffff0000, v17
	v_lshlrev_b32_e32 v162, 16, v18
	v_and_b32_e32 v163, 0xffff0000, v18
	v_lshlrev_b32_e32 v18, 16, v19
	v_and_b32_e32 v19, 0xffff0000, v19
	v_pk_mul_f32 v[114:115], v[194:195], v[156:157]
	v_pk_mul_f32 v[116:117], v[196:197], v[12:13]
	v_pk_mul_f32 v[118:119], v[198:199], v[158:159]
	v_pk_mul_f32 v[120:121], v[200:201], v[14:15]
	v_pk_mul_f32 v[122:123], v[202:203], v[160:161]
	v_pk_mul_f32 v[124:125], v[204:205], v[16:17]
	v_pk_mul_f32 v[126:127], v[206:207], v[162:163]
	v_pk_mul_f32 v[128:129], v[208:209], v[18:19]
	v_pk_mul_f32 v[114:115], v[10:11], v[114:115]
	v_pk_mul_f32 v[116:117], v[10:11], v[116:117]
	v_pk_mul_f32 v[118:119], v[10:11], v[118:119]
	v_pk_mul_f32 v[120:121], v[10:11], v[120:121]
	v_pk_mul_f32 v[122:123], v[10:11], v[122:123]
	v_pk_mul_f32 v[124:125], v[10:11], v[124:125]
	v_pk_mul_f32 v[126:127], v[10:11], v[126:127]
	v_pk_mul_f32 v[128:129], v[10:11], v[128:129]
	v_pk_fma_f32 v[114:115], v[20:21], s[28:29], v[114:115] op_sel_hi:[1,0,1]
	v_pk_fma_f32 v[116:117], v[22:23], s[28:29], v[116:117] op_sel_hi:[1,0,1]
	v_pk_fma_f32 v[118:119], v[24:25], s[28:29], v[118:119] op_sel_hi:[1,0,1]
	v_pk_fma_f32 v[120:121], v[26:27], s[28:29], v[120:121] op_sel_hi:[1,0,1]
	v_pk_fma_f32 v[122:123], v[0:1], s[28:29], v[122:123] op_sel_hi:[1,0,1]
	v_pk_fma_f32 v[124:125], v[2:3], s[28:29], v[124:125] op_sel_hi:[1,0,1]
	v_pk_fma_f32 v[126:127], v[4:5], s[28:29], v[126:127] op_sel_hi:[1,0,1]
	v_pk_fma_f32 v[128:129], v[6:7], s[28:29], v[128:129] op_sel_hi:[1,0,1]
	v_add_f32_e32 v164, v114, v115
	v_add_f32_e32 v165, v116, v117
	v_add_f32_e32 v166, v118, v119
	v_add_f32_e32 v167, v120, v121
	v_add_f32_e32 v168, v122, v123
	v_add_f32_e32 v169, v124, v125
	v_add_f32_e32 v242, v126, v127
	v_add_f32_e32 v243, v128, v129
	v_add_f32_e32 v164, v164, v165
	v_add_f32_e32 v166, v166, v167
	v_add_f32_e32 v168, v168, v169
	v_add_f32_e32 v242, v242, v243
	v_add_f32_e32 v9, 0, v164
	v_add_f32_e32 v9, v9, v166
	v_add_f32_e32 v9, v9, v168
	v_add_f32_e32 v9, v9, v242
	ds_bpermute_b32 v28, v96, v9
	s_waitcnt lgkmcnt(0)
	v_add_f32_e32 v9, v9, v28
	ds_swizzle_b32 v28, v9 offset:swizzle(SWAP,16)
	s_waitcnt lgkmcnt(0)
	v_add_f32_e32 v9, v9, v28
	ds_swizzle_b32 v28, v9 offset:swizzle(SWAP,8)
	s_waitcnt lgkmcnt(0)
	v_add_f32_e32 v9, v9, v28
	ds_swizzle_b32 v28, v9 offset:swizzle(SWAP,4)
	s_waitcnt lgkmcnt(0)
	v_add_f32_e32 v9, v9, v28
	ds_swizzle_b32 v28, v9 offset:swizzle(SWAP,2)
	s_waitcnt lgkmcnt(0)
	v_add_f32_e32 v9, v9, v28
	ds_swizzle_b32 v28, v9 offset:swizzle(SWAP,1)
	s_waitcnt lgkmcnt(0)
	v_add_f32_e32 v9, v9, v28
	v_fmac_f32_e32 v114, 0xba800000, v9
	v_fmac_f32_e32 v115, 0xba800000, v9
	v_fmac_f32_e32 v116, 0xba800000, v9
	v_fmac_f32_e32 v117, 0xba800000, v9
	v_fmac_f32_e32 v118, 0xba800000, v9
	v_fmac_f32_e32 v119, 0xba800000, v9
	v_fmac_f32_e32 v120, 0xba800000, v9
	v_fmac_f32_e32 v121, 0xba800000, v9
	v_fmac_f32_e32 v122, 0xba800000, v9
	v_fmac_f32_e32 v123, 0xba800000, v9
	v_fmac_f32_e32 v124, 0xba800000, v9
	v_fmac_f32_e32 v125, 0xba800000, v9
	v_fmac_f32_e32 v126, 0xba800000, v9
	v_fmac_f32_e32 v127, 0xba800000, v9
	v_fmac_f32_e32 v128, 0xba800000, v9
	v_fmac_f32_e32 v129, 0xba800000, v9
	v_pk_mul_f32 v[244:245], v[114:115], v[114:115]
	v_pk_mul_f32 v[246:247], v[116:117], v[116:117]
	v_add_f32_e32 v244, v245, v244
	v_add_f32_e32 v246, v246, v247
	v_add_f32_e32 v164, v244, v246
	v_pk_mul_f32 v[244:245], v[118:119], v[118:119]
	v_pk_mul_f32 v[246:247], v[120:121], v[120:121]
	v_add_f32_e32 v244, v245, v244
	v_add_f32_e32 v246, v246, v247
	v_add_f32_e32 v165, v244, v246
	v_mul_f32_e32 v248, v122, v122
	v_mul_f32_e32 v249, v124, v124
	v_fmac_f32_e32 v248, v123, v123
	v_fmac_f32_e32 v249, v125, v125
	v_add_f32_e32 v166, v248, v249
	v_pk_mul_f32 v[244:245], v[126:127], v[126:127]
	v_pk_mul_f32 v[246:247], v[128:129], v[128:129]
	v_add_f32_e32 v244, v244, v245
	v_add_f32_e32 v246, v246, v247
	v_add_f32_e32 v167, v244, v246
	v_add_f32_e32 v164, v164, v165
	v_add_f32_e32 v164, v166, v164
	v_add_f32_e32 v9, v167, v164
	ds_bpermute_b32 v28, v96, v9
	s_waitcnt lgkmcnt(0)
	v_add_f32_e32 v9, v9, v28
	ds_swizzle_b32 v28, v9 offset:swizzle(SWAP,16)
	s_waitcnt lgkmcnt(0)
	v_add_f32_e32 v9, v9, v28
	ds_swizzle_b32 v28, v9 offset:swizzle(SWAP,8)
	s_waitcnt lgkmcnt(0)
	v_add_f32_e32 v9, v9, v28
	ds_swizzle_b32 v28, v9 offset:swizzle(SWAP,4)
	s_waitcnt lgkmcnt(0)
	v_add_f32_e32 v9, v9, v28
	ds_swizzle_b32 v28, v9 offset:swizzle(SWAP,2)
	s_waitcnt lgkmcnt(0)
	v_add_f32_e32 v9, v9, v28
	ds_swizzle_b32 v28, v9 offset:swizzle(SWAP,1)
	s_waitcnt lgkmcnt(0)
	v_add_f32_e32 v9, v9, v28
	v_mov_b32_e32 v28, 0x3727c5ac
	v_fmamk_f32 v9, v9, 0x3a800000, v28
	v_mul_f32_e32 v28, 0x4b800000, v9
	v_cmp_gt_f32_e32 vcc, s37, v9
	s_nop 1
	v_cndmask_b32_e32 v9, v9, v28, vcc
	v_rsq_f32_e32 v9, v9
	s_nop 0
	v_mul_f32_e32 v28, 0x45800000, v9
	v_cndmask_b32_e32 v30, v9, v28, vcc
	v_pk_mul_f32 v[114:115], v[114:115], v[30:31] op_sel_hi:[1,0]
	v_pk_mul_f32 v[116:117], v[116:117], v[30:31] op_sel_hi:[1,0]
	v_pk_fma_f32 v[20:21], v[140:141], v[114:115], v[98:99]
	v_pk_fma_f32 v[22:23], v[142:143], v[116:117], v[100:101]
	global_store_dwordx4 v[86:87], v[20:23], off sc1 nt
	v_pk_fma_f32 v[114:115], v[226:227], v[20:21], v[210:211]
	v_pk_fma_f32 v[116:117], v[228:229], v[22:23], v[212:213]
	s_nop 0
	v_cvt_pk_bf16_f32 v12, v114, v115
	v_cvt_pk_bf16_f32 v13, v116, v117
	global_store_dwordx2 v[88:89], v[12:13], off sc1
	v_pk_mul_f32 v[118:119], v[118:119], v[30:31] op_sel_hi:[1,0]
	v_pk_mul_f32 v[120:121], v[120:121], v[30:31] op_sel_hi:[1,0]
	v_pk_fma_f32 v[24:25], v[144:145], v[118:119], v[102:103]
	v_pk_fma_f32 v[26:27], v[146:147], v[120:121], v[104:105]
	global_store_dwordx4 v[86:87], v[24:27], off offset:1024 sc1 nt
	v_pk_fma_f32 v[118:119], v[230:231], v[24:25], v[214:215]
	v_pk_fma_f32 v[120:121], v[232:233], v[26:27], v[216:217]
	s_nop 0
	v_cvt_pk_bf16_f32 v14, v118, v119
	v_cvt_pk_bf16_f32 v15, v120, v121
	global_store_dwordx2 v[88:89], v[14:15], off offset:512 sc1
	v_pk_mul_f32 v[122:123], v[122:123], v[30:31] op_sel_hi:[1,0]
	v_pk_mul_f32 v[124:125], v[124:125], v[30:31] op_sel_hi:[1,0]
	v_pk_fma_f32 v[0:1], v[148:149], v[122:123], v[106:107]
	v_pk_fma_f32 v[2:3], v[150:151], v[124:125], v[108:109]
	global_store_dwordx4 v[86:87], v[0:3], off offset:2048 sc1 nt
	v_pk_fma_f32 v[122:123], v[234:235], v[0:1], v[218:219]
	v_pk_fma_f32 v[124:125], v[236:237], v[2:3], v[220:221]
	s_nop 0
	v_cvt_pk_bf16_f32 v16, v122, v123
	v_cvt_pk_bf16_f32 v17, v124, v125
	global_store_dwordx2 v[88:89], v[16:17], off offset:1024 sc1
	v_pk_mul_f32 v[126:127], v[126:127], v[30:31] op_sel_hi:[1,0]
	v_pk_mul_f32 v[128:129], v[128:129], v[30:31] op_sel_hi:[1,0]
	v_pk_fma_f32 v[4:5], v[152:153], v[126:127], v[110:111]
	v_pk_fma_f32 v[6:7], v[154:155], v[128:129], v[112:113]
	global_store_dwordx4 v[86:87], v[4:7], off offset:3072 sc1 nt
	v_pk_fma_f32 v[126:127], v[238:239], v[4:5], v[222:223]
	v_pk_fma_f32 v[128:129], v[240:241], v[6:7], v[224:225]
	s_nop 0
	v_cvt_pk_bf16_f32 v18, v126, v127
	v_cvt_pk_bf16_f32 v19, v128, v129
	global_store_dwordx2 v[88:89], v[18:19], off offset:1536 sc1
	v_lshl_add_u64 v[86:87], v[86:87], 0, s[0:1]
	v_lshl_add_u64 v[88:89], v[88:89], 0, s[20:21]
	global_load_dwordx4 v[20:23], v[82:83], off nt
	global_load_dwordx4 v[24:27], v[82:83], off offset:1024 nt
	global_load_dwordx4 v[0:3], v[82:83], off offset:2048 nt
	global_load_dwordx4 v[4:7], v[82:83], off offset:3072 nt
	global_load_dwordx2 v[12:13], v[84:85], off
	global_load_dwordx2 v[14:15], v[84:85], off offset:512
	global_load_dwordx2 v[16:17], v[84:85], off offset:1024
	global_load_dwordx2 v[18:19], v[84:85], off offset:1536
	v_lshl_add_u64 v[82:83], v[82:83], 0, s[0:1]
	v_lshl_add_u64 v[84:85], v[84:85], 0, s[20:21]
	s_waitcnt vmcnt(32)
	v_lshlrev_b32_e32 v156, 16, v50
	v_and_b32_e32 v157, 0xffff0000, v50
	v_lshlrev_b32_e32 v50, 16, v51
	v_and_b32_e32 v51, 0xffff0000, v51
	v_lshlrev_b32_e32 v158, 16, v52
	v_and_b32_e32 v159, 0xffff0000, v52
	v_lshlrev_b32_e32 v52, 16, v53
	v_and_b32_e32 v53, 0xffff0000, v53
	v_lshlrev_b32_e32 v160, 16, v54
	v_and_b32_e32 v161, 0xffff0000, v54
	v_lshlrev_b32_e32 v54, 16, v55
	v_and_b32_e32 v55, 0xffff0000, v55
	v_lshlrev_b32_e32 v162, 16, v56
	v_and_b32_e32 v163, 0xffff0000, v56
	v_lshlrev_b32_e32 v56, 16, v57
	v_and_b32_e32 v57, 0xffff0000, v57
	v_pk_mul_f32 v[114:115], v[194:195], v[156:157]
	v_pk_mul_f32 v[116:117], v[196:197], v[50:51]
	v_pk_mul_f32 v[118:119], v[198:199], v[158:159]
	v_pk_mul_f32 v[120:121], v[200:201], v[52:53]
	v_pk_mul_f32 v[122:123], v[202:203], v[160:161]
	v_pk_mul_f32 v[124:125], v[204:205], v[54:55]
	v_pk_mul_f32 v[126:127], v[206:207], v[162:163]
	v_pk_mul_f32 v[128:129], v[208:209], v[56:57]
	v_pk_mul_f32 v[114:115], v[10:11], v[114:115]
	v_pk_mul_f32 v[116:117], v[10:11], v[116:117]
	v_pk_mul_f32 v[118:119], v[10:11], v[118:119]
	v_pk_mul_f32 v[120:121], v[10:11], v[120:121]
	v_pk_mul_f32 v[122:123], v[10:11], v[122:123]
	v_pk_mul_f32 v[124:125], v[10:11], v[124:125]
	v_pk_mul_f32 v[126:127], v[10:11], v[126:127]
	v_pk_mul_f32 v[128:129], v[10:11], v[128:129]
	v_pk_fma_f32 v[114:115], v[34:35], s[28:29], v[114:115] op_sel_hi:[1,0,1]
	v_pk_fma_f32 v[116:117], v[36:37], s[28:29], v[116:117] op_sel_hi:[1,0,1]
	v_pk_fma_f32 v[118:119], v[38:39], s[28:29], v[118:119] op_sel_hi:[1,0,1]
	v_pk_fma_f32 v[120:121], v[40:41], s[28:29], v[120:121] op_sel_hi:[1,0,1]
	v_pk_fma_f32 v[122:123], v[42:43], s[28:29], v[122:123] op_sel_hi:[1,0,1]
	v_pk_fma_f32 v[124:125], v[44:45], s[28:29], v[124:125] op_sel_hi:[1,0,1]
	v_pk_fma_f32 v[126:127], v[46:47], s[28:29], v[126:127] op_sel_hi:[1,0,1]
	v_pk_fma_f32 v[128:129], v[48:49], s[28:29], v[128:129] op_sel_hi:[1,0,1]
	v_add_f32_e32 v164, v114, v115
	v_add_f32_e32 v165, v116, v117
	v_add_f32_e32 v166, v118, v119
	v_add_f32_e32 v167, v120, v121
	v_add_f32_e32 v168, v122, v123
	v_add_f32_e32 v169, v124, v125
	v_add_f32_e32 v242, v126, v127
	v_add_f32_e32 v243, v128, v129
	v_add_f32_e32 v164, v164, v165
	v_add_f32_e32 v166, v166, v167
	v_add_f32_e32 v168, v168, v169
	v_add_f32_e32 v242, v242, v243
	v_add_f32_e32 v9, 0, v164
	v_add_f32_e32 v9, v9, v166
	v_add_f32_e32 v9, v9, v168
	v_add_f32_e32 v9, v9, v242
	ds_bpermute_b32 v28, v96, v9
	s_waitcnt lgkmcnt(0)
	v_add_f32_e32 v9, v9, v28
	ds_swizzle_b32 v28, v9 offset:swizzle(SWAP,16)
	s_waitcnt lgkmcnt(0)
	v_add_f32_e32 v9, v9, v28
	ds_swizzle_b32 v28, v9 offset:swizzle(SWAP,8)
	s_waitcnt lgkmcnt(0)
	v_add_f32_e32 v9, v9, v28
	ds_swizzle_b32 v28, v9 offset:swizzle(SWAP,4)
	s_waitcnt lgkmcnt(0)
	v_add_f32_e32 v9, v9, v28
	ds_swizzle_b32 v28, v9 offset:swizzle(SWAP,2)
	s_waitcnt lgkmcnt(0)
	v_add_f32_e32 v9, v9, v28
	ds_swizzle_b32 v28, v9 offset:swizzle(SWAP,1)
	s_waitcnt lgkmcnt(0)
	v_add_f32_e32 v9, v9, v28
	v_fmac_f32_e32 v114, 0xba800000, v9
	v_fmac_f32_e32 v115, 0xba800000, v9
	v_fmac_f32_e32 v116, 0xba800000, v9
	v_fmac_f32_e32 v117, 0xba800000, v9
	v_fmac_f32_e32 v118, 0xba800000, v9
	v_fmac_f32_e32 v119, 0xba800000, v9
	v_fmac_f32_e32 v120, 0xba800000, v9
	v_fmac_f32_e32 v121, 0xba800000, v9
	v_fmac_f32_e32 v122, 0xba800000, v9
	v_fmac_f32_e32 v123, 0xba800000, v9
	v_fmac_f32_e32 v124, 0xba800000, v9
	v_fmac_f32_e32 v125, 0xba800000, v9
	v_fmac_f32_e32 v126, 0xba800000, v9
	v_fmac_f32_e32 v127, 0xba800000, v9
	v_fmac_f32_e32 v128, 0xba800000, v9
	v_fmac_f32_e32 v129, 0xba800000, v9
	v_pk_mul_f32 v[244:245], v[114:115], v[114:115]
	v_pk_mul_f32 v[246:247], v[116:117], v[116:117]
	v_add_f32_e32 v244, v245, v244
	v_add_f32_e32 v246, v246, v247
	v_add_f32_e32 v164, v244, v246
	v_pk_mul_f32 v[244:245], v[118:119], v[118:119]
	v_pk_mul_f32 v[246:247], v[120:121], v[120:121]
	v_add_f32_e32 v244, v245, v244
	v_add_f32_e32 v246, v246, v247
	v_add_f32_e32 v165, v244, v246
	v_mul_f32_e32 v248, v122, v122
	v_mul_f32_e32 v249, v124, v124
	v_fmac_f32_e32 v248, v123, v123
	v_fmac_f32_e32 v249, v125, v125
	v_add_f32_e32 v166, v248, v249
	v_pk_mul_f32 v[244:245], v[126:127], v[126:127]
	v_pk_mul_f32 v[246:247], v[128:129], v[128:129]
	v_add_f32_e32 v244, v244, v245
	v_add_f32_e32 v246, v246, v247
	v_add_f32_e32 v167, v244, v246
	v_add_f32_e32 v164, v164, v165
	v_add_f32_e32 v164, v166, v164
	v_add_f32_e32 v9, v167, v164
	ds_bpermute_b32 v28, v96, v9
	s_waitcnt lgkmcnt(0)
	v_add_f32_e32 v9, v9, v28
	ds_swizzle_b32 v28, v9 offset:swizzle(SWAP,16)
	s_waitcnt lgkmcnt(0)
	v_add_f32_e32 v9, v9, v28
	ds_swizzle_b32 v28, v9 offset:swizzle(SWAP,8)
	s_waitcnt lgkmcnt(0)
	v_add_f32_e32 v9, v9, v28
	ds_swizzle_b32 v28, v9 offset:swizzle(SWAP,4)
	s_waitcnt lgkmcnt(0)
	v_add_f32_e32 v9, v9, v28
	ds_swizzle_b32 v28, v9 offset:swizzle(SWAP,2)
	s_waitcnt lgkmcnt(0)
	v_add_f32_e32 v9, v9, v28
	ds_swizzle_b32 v28, v9 offset:swizzle(SWAP,1)
	s_waitcnt lgkmcnt(0)
	v_add_f32_e32 v9, v9, v28
	v_mov_b32_e32 v28, 0x3727c5ac
	v_fmamk_f32 v9, v9, 0x3a800000, v28
	v_mul_f32_e32 v28, 0x4b800000, v9
	v_cmp_gt_f32_e32 vcc, s37, v9
	s_nop 1
	v_cndmask_b32_e32 v9, v9, v28, vcc
	v_rsq_f32_e32 v9, v9
	s_nop 0
	v_mul_f32_e32 v28, 0x45800000, v9
	v_cndmask_b32_e32 v30, v9, v28, vcc
	v_pk_mul_f32 v[114:115], v[114:115], v[30:31] op_sel_hi:[1,0]
	v_pk_mul_f32 v[116:117], v[116:117], v[30:31] op_sel_hi:[1,0]
	v_pk_fma_f32 v[34:35], v[140:141], v[114:115], v[98:99]
	v_pk_fma_f32 v[36:37], v[142:143], v[116:117], v[100:101]
	global_store_dwordx4 v[86:87], v[34:37], off sc1 nt
	v_pk_fma_f32 v[114:115], v[226:227], v[34:35], v[210:211]
	v_pk_fma_f32 v[116:117], v[228:229], v[36:37], v[212:213]
	s_nop 0
	v_cvt_pk_bf16_f32 v50, v114, v115
	v_cvt_pk_bf16_f32 v51, v116, v117
	global_store_dwordx2 v[88:89], v[50:51], off sc1
	v_pk_mul_f32 v[118:119], v[118:119], v[30:31] op_sel_hi:[1,0]
	v_pk_mul_f32 v[120:121], v[120:121], v[30:31] op_sel_hi:[1,0]
	v_pk_fma_f32 v[38:39], v[144:145], v[118:119], v[102:103]
	v_pk_fma_f32 v[40:41], v[146:147], v[120:121], v[104:105]
	global_store_dwordx4 v[86:87], v[38:41], off offset:1024 sc1 nt
	v_pk_fma_f32 v[118:119], v[230:231], v[38:39], v[214:215]
	v_pk_fma_f32 v[120:121], v[232:233], v[40:41], v[216:217]
	s_nop 0
	v_cvt_pk_bf16_f32 v52, v118, v119
	v_cvt_pk_bf16_f32 v53, v120, v121
	global_store_dwordx2 v[88:89], v[52:53], off offset:512 sc1
	v_pk_mul_f32 v[122:123], v[122:123], v[30:31] op_sel_hi:[1,0]
	v_pk_mul_f32 v[124:125], v[124:125], v[30:31] op_sel_hi:[1,0]
	v_pk_fma_f32 v[42:43], v[148:149], v[122:123], v[106:107]
	v_pk_fma_f32 v[44:45], v[150:151], v[124:125], v[108:109]
	global_store_dwordx4 v[86:87], v[42:45], off offset:2048 sc1 nt
	v_pk_fma_f32 v[122:123], v[234:235], v[42:43], v[218:219]
	v_pk_fma_f32 v[124:125], v[236:237], v[44:45], v[220:221]
	s_nop 0
	v_cvt_pk_bf16_f32 v54, v122, v123
	v_cvt_pk_bf16_f32 v55, v124, v125
	global_store_dwordx2 v[88:89], v[54:55], off offset:1024 sc1
	v_pk_mul_f32 v[126:127], v[126:127], v[30:31] op_sel_hi:[1,0]
	v_pk_mul_f32 v[128:129], v[128:129], v[30:31] op_sel_hi:[1,0]
	v_pk_fma_f32 v[46:47], v[152:153], v[126:127], v[110:111]
	v_pk_fma_f32 v[48:49], v[154:155], v[128:129], v[112:113]
	global_store_dwordx4 v[86:87], v[46:49], off offset:3072 sc1 nt
	v_pk_fma_f32 v[126:127], v[238:239], v[46:47], v[222:223]
	v_pk_fma_f32 v[128:129], v[240:241], v[48:49], v[224:225]
	s_nop 0
	v_cvt_pk_bf16_f32 v56, v126, v127
	v_cvt_pk_bf16_f32 v57, v128, v129
	global_store_dwordx2 v[88:89], v[56:57], off offset:1536 sc1
	v_lshl_add_u64 v[86:87], v[86:87], 0, s[0:1]
	v_lshl_add_u64 v[88:89], v[88:89], 0, s[20:21]
	global_load_dwordx4 v[34:37], v[82:83], off nt
	global_load_dwordx4 v[38:41], v[82:83], off offset:1024 nt
	global_load_dwordx4 v[42:45], v[82:83], off offset:2048 nt
	global_load_dwordx4 v[46:49], v[82:83], off offset:3072 nt
	global_load_dwordx2 v[50:51], v[84:85], off
	global_load_dwordx2 v[52:53], v[84:85], off offset:512
	global_load_dwordx2 v[54:55], v[84:85], off offset:1024
	global_load_dwordx2 v[56:57], v[84:85], off offset:1536
	v_lshl_add_u64 v[82:83], v[82:83], 0, s[0:1]
	v_lshl_add_u64 v[84:85], v[84:85], 0, s[20:21]
	s_waitcnt vmcnt(32)
	v_lshlrev_b32_e32 v156, 16, v74
	v_and_b32_e32 v157, 0xffff0000, v74
	v_lshlrev_b32_e32 v74, 16, v75
	v_and_b32_e32 v75, 0xffff0000, v75
	v_lshlrev_b32_e32 v158, 16, v76
	v_and_b32_e32 v159, 0xffff0000, v76
	v_lshlrev_b32_e32 v76, 16, v77
	v_and_b32_e32 v77, 0xffff0000, v77
	v_lshlrev_b32_e32 v160, 16, v78
	v_and_b32_e32 v161, 0xffff0000, v78
	v_lshlrev_b32_e32 v78, 16, v79
	v_and_b32_e32 v79, 0xffff0000, v79
	v_lshlrev_b32_e32 v162, 16, v80
	v_and_b32_e32 v163, 0xffff0000, v80
	v_lshlrev_b32_e32 v80, 16, v81
	v_and_b32_e32 v81, 0xffff0000, v81
	v_pk_mul_f32 v[114:115], v[194:195], v[156:157]
	v_pk_mul_f32 v[116:117], v[196:197], v[74:75]
	v_pk_mul_f32 v[118:119], v[198:199], v[158:159]
	v_pk_mul_f32 v[120:121], v[200:201], v[76:77]
	v_pk_mul_f32 v[122:123], v[202:203], v[160:161]
	v_pk_mul_f32 v[124:125], v[204:205], v[78:79]
	v_pk_mul_f32 v[126:127], v[206:207], v[162:163]
	v_pk_mul_f32 v[128:129], v[208:209], v[80:81]
	v_pk_mul_f32 v[114:115], v[10:11], v[114:115]
	v_pk_mul_f32 v[116:117], v[10:11], v[116:117]
	v_pk_mul_f32 v[118:119], v[10:11], v[118:119]
	v_pk_mul_f32 v[120:121], v[10:11], v[120:121]
	v_pk_mul_f32 v[122:123], v[10:11], v[122:123]
	v_pk_mul_f32 v[124:125], v[10:11], v[124:125]
	v_pk_mul_f32 v[126:127], v[10:11], v[126:127]
	v_pk_mul_f32 v[128:129], v[10:11], v[128:129]
	v_pk_fma_f32 v[114:115], v[58:59], s[28:29], v[114:115] op_sel_hi:[1,0,1]
	v_pk_fma_f32 v[116:117], v[60:61], s[28:29], v[116:117] op_sel_hi:[1,0,1]
	v_pk_fma_f32 v[118:119], v[62:63], s[28:29], v[118:119] op_sel_hi:[1,0,1]
	v_pk_fma_f32 v[120:121], v[64:65], s[28:29], v[120:121] op_sel_hi:[1,0,1]
	v_pk_fma_f32 v[122:123], v[66:67], s[28:29], v[122:123] op_sel_hi:[1,0,1]
	v_pk_fma_f32 v[124:125], v[68:69], s[28:29], v[124:125] op_sel_hi:[1,0,1]
	v_pk_fma_f32 v[126:127], v[70:71], s[28:29], v[126:127] op_sel_hi:[1,0,1]
	v_pk_fma_f32 v[128:129], v[72:73], s[28:29], v[128:129] op_sel_hi:[1,0,1]
	v_add_f32_e32 v164, v114, v115
	v_add_f32_e32 v165, v116, v117
	v_add_f32_e32 v166, v118, v119
	v_add_f32_e32 v167, v120, v121
	v_add_f32_e32 v168, v122, v123
	v_add_f32_e32 v169, v124, v125
	v_add_f32_e32 v242, v126, v127
	v_add_f32_e32 v243, v128, v129
	v_add_f32_e32 v164, v164, v165
	v_add_f32_e32 v166, v166, v167
	v_add_f32_e32 v168, v168, v169
	v_add_f32_e32 v242, v242, v243
	v_add_f32_e32 v9, 0, v164
	v_add_f32_e32 v9, v9, v166
	v_add_f32_e32 v9, v9, v168
	v_add_f32_e32 v9, v9, v242
	ds_bpermute_b32 v28, v96, v9
	s_waitcnt lgkmcnt(0)
	v_add_f32_e32 v9, v9, v28
	ds_swizzle_b32 v28, v9 offset:swizzle(SWAP,16)
	s_waitcnt lgkmcnt(0)
	v_add_f32_e32 v9, v9, v28
	ds_swizzle_b32 v28, v9 offset:swizzle(SWAP,8)
	s_waitcnt lgkmcnt(0)
	v_add_f32_e32 v9, v9, v28
	ds_swizzle_b32 v28, v9 offset:swizzle(SWAP,4)
	s_waitcnt lgkmcnt(0)
	v_add_f32_e32 v9, v9, v28
	ds_swizzle_b32 v28, v9 offset:swizzle(SWAP,2)
	s_waitcnt lgkmcnt(0)
	v_add_f32_e32 v9, v9, v28
	ds_swizzle_b32 v28, v9 offset:swizzle(SWAP,1)
	s_waitcnt lgkmcnt(0)
	v_add_f32_e32 v9, v9, v28
	v_fmac_f32_e32 v114, 0xba800000, v9
	v_fmac_f32_e32 v115, 0xba800000, v9
	v_fmac_f32_e32 v116, 0xba800000, v9
	v_fmac_f32_e32 v117, 0xba800000, v9
	v_fmac_f32_e32 v118, 0xba800000, v9
	v_fmac_f32_e32 v119, 0xba800000, v9
	v_fmac_f32_e32 v120, 0xba800000, v9
	v_fmac_f32_e32 v121, 0xba800000, v9
	v_fmac_f32_e32 v122, 0xba800000, v9
	v_fmac_f32_e32 v123, 0xba800000, v9
	v_fmac_f32_e32 v124, 0xba800000, v9
	v_fmac_f32_e32 v125, 0xba800000, v9
	v_fmac_f32_e32 v126, 0xba800000, v9
	v_fmac_f32_e32 v127, 0xba800000, v9
	v_fmac_f32_e32 v128, 0xba800000, v9
	v_fmac_f32_e32 v129, 0xba800000, v9
	v_pk_mul_f32 v[244:245], v[114:115], v[114:115]
	v_pk_mul_f32 v[246:247], v[116:117], v[116:117]
	v_add_f32_e32 v244, v245, v244
	v_add_f32_e32 v246, v246, v247
	v_add_f32_e32 v164, v244, v246
	v_pk_mul_f32 v[244:245], v[118:119], v[118:119]
	v_pk_mul_f32 v[246:247], v[120:121], v[120:121]
	v_add_f32_e32 v244, v245, v244
	v_add_f32_e32 v246, v246, v247
	v_add_f32_e32 v165, v244, v246
	v_mul_f32_e32 v248, v122, v122
	v_mul_f32_e32 v249, v124, v124
	v_fmac_f32_e32 v248, v123, v123
	v_fmac_f32_e32 v249, v125, v125
	v_add_f32_e32 v166, v248, v249
	v_pk_mul_f32 v[244:245], v[126:127], v[126:127]
	v_pk_mul_f32 v[246:247], v[128:129], v[128:129]
	v_add_f32_e32 v244, v244, v245
	v_add_f32_e32 v246, v246, v247
	v_add_f32_e32 v167, v244, v246
	v_add_f32_e32 v164, v164, v165
	v_add_f32_e32 v164, v166, v164
	v_add_f32_e32 v9, v167, v164
	ds_bpermute_b32 v28, v96, v9
	s_waitcnt lgkmcnt(0)
	v_add_f32_e32 v9, v9, v28
	ds_swizzle_b32 v28, v9 offset:swizzle(SWAP,16)
	s_waitcnt lgkmcnt(0)
	v_add_f32_e32 v9, v9, v28
	ds_swizzle_b32 v28, v9 offset:swizzle(SWAP,8)
	s_waitcnt lgkmcnt(0)
	v_add_f32_e32 v9, v9, v28
	ds_swizzle_b32 v28, v9 offset:swizzle(SWAP,4)
	s_waitcnt lgkmcnt(0)
	v_add_f32_e32 v9, v9, v28
	ds_swizzle_b32 v28, v9 offset:swizzle(SWAP,2)
	s_waitcnt lgkmcnt(0)
	v_add_f32_e32 v9, v9, v28
	ds_swizzle_b32 v28, v9 offset:swizzle(SWAP,1)
	s_waitcnt lgkmcnt(0)
	v_add_f32_e32 v9, v9, v28
	v_mov_b32_e32 v28, 0x3727c5ac
	v_fmamk_f32 v9, v9, 0x3a800000, v28
	v_mul_f32_e32 v28, 0x4b800000, v9
	v_cmp_gt_f32_e32 vcc, s37, v9
	s_nop 1
	v_cndmask_b32_e32 v9, v9, v28, vcc
	v_rsq_f32_e32 v9, v9
	s_nop 0
	v_mul_f32_e32 v28, 0x45800000, v9
	v_cndmask_b32_e32 v30, v9, v28, vcc
	v_pk_mul_f32 v[114:115], v[114:115], v[30:31] op_sel_hi:[1,0]
	v_pk_mul_f32 v[116:117], v[116:117], v[30:31] op_sel_hi:[1,0]
	v_pk_fma_f32 v[58:59], v[140:141], v[114:115], v[98:99]
	v_pk_fma_f32 v[60:61], v[142:143], v[116:117], v[100:101]
	global_store_dwordx4 v[86:87], v[58:61], off sc1 nt
	v_pk_fma_f32 v[114:115], v[226:227], v[58:59], v[210:211]
	v_pk_fma_f32 v[116:117], v[228:229], v[60:61], v[212:213]
	s_nop 0
	v_cvt_pk_bf16_f32 v74, v114, v115
	v_cvt_pk_bf16_f32 v75, v116, v117
	global_store_dwordx2 v[88:89], v[74:75], off sc1
	v_pk_mul_f32 v[118:119], v[118:119], v[30:31] op_sel_hi:[1,0]
	v_pk_mul_f32 v[120:121], v[120:121], v[30:31] op_sel_hi:[1,0]
	v_pk_fma_f32 v[62:63], v[144:145], v[118:119], v[102:103]
	v_pk_fma_f32 v[64:65], v[146:147], v[120:121], v[104:105]
	global_store_dwordx4 v[86:87], v[62:65], off offset:1024 sc1 nt
	v_pk_fma_f32 v[118:119], v[230:231], v[62:63], v[214:215]
	v_pk_fma_f32 v[120:121], v[232:233], v[64:65], v[216:217]
	s_nop 0
	v_cvt_pk_bf16_f32 v76, v118, v119
	v_cvt_pk_bf16_f32 v77, v120, v121
	global_store_dwordx2 v[88:89], v[76:77], off offset:512 sc1
	v_pk_mul_f32 v[122:123], v[122:123], v[30:31] op_sel_hi:[1,0]
	v_pk_mul_f32 v[124:125], v[124:125], v[30:31] op_sel_hi:[1,0]
	v_pk_fma_f32 v[66:67], v[148:149], v[122:123], v[106:107]
	v_pk_fma_f32 v[68:69], v[150:151], v[124:125], v[108:109]
	global_store_dwordx4 v[86:87], v[66:69], off offset:2048 sc1 nt
	v_pk_fma_f32 v[122:123], v[234:235], v[66:67], v[218:219]
	v_pk_fma_f32 v[124:125], v[236:237], v[68:69], v[220:221]
	s_nop 0
	v_cvt_pk_bf16_f32 v78, v122, v123
	v_cvt_pk_bf16_f32 v79, v124, v125
	global_store_dwordx2 v[88:89], v[78:79], off offset:1024 sc1
	v_pk_mul_f32 v[126:127], v[126:127], v[30:31] op_sel_hi:[1,0]
	v_pk_mul_f32 v[128:129], v[128:129], v[30:31] op_sel_hi:[1,0]
	v_pk_fma_f32 v[70:71], v[152:153], v[126:127], v[110:111]
	v_pk_fma_f32 v[72:73], v[154:155], v[128:129], v[112:113]
	global_store_dwordx4 v[86:87], v[70:73], off offset:3072 sc1 nt
	v_pk_fma_f32 v[126:127], v[238:239], v[70:71], v[222:223]
	v_pk_fma_f32 v[128:129], v[240:241], v[72:73], v[224:225]
	s_nop 0
	v_cvt_pk_bf16_f32 v80, v126, v127
	v_cvt_pk_bf16_f32 v81, v128, v129
	global_store_dwordx2 v[88:89], v[80:81], off offset:1536 sc1
	v_lshl_add_u64 v[86:87], v[86:87], 0, s[0:1]
	v_lshl_add_u64 v[88:89], v[88:89], 0, s[20:21]
	global_load_dwordx4 v[58:61], v[82:83], off nt
	global_load_dwordx4 v[62:65], v[82:83], off offset:1024 nt
	global_load_dwordx4 v[66:69], v[82:83], off offset:2048 nt
	global_load_dwordx4 v[70:73], v[82:83], off offset:3072 nt
	global_load_dwordx2 v[74:75], v[84:85], off
	global_load_dwordx2 v[76:77], v[84:85], off offset:512
	global_load_dwordx2 v[78:79], v[84:85], off offset:1024
	global_load_dwordx2 v[80:81], v[84:85], off offset:1536
	v_lshl_add_u64 v[82:83], v[82:83], 0, s[0:1]
	v_lshl_add_u64 v[84:85], v[84:85], 0, s[20:21]
	s_waitcnt vmcnt(32)
	v_lshlrev_b32_e32 v156, 16, v12
	v_and_b32_e32 v157, 0xffff0000, v12
	v_lshlrev_b32_e32 v12, 16, v13
	v_and_b32_e32 v13, 0xffff0000, v13
	v_lshlrev_b32_e32 v158, 16, v14
	v_and_b32_e32 v159, 0xffff0000, v14
	v_lshlrev_b32_e32 v14, 16, v15
	v_and_b32_e32 v15, 0xffff0000, v15
	v_lshlrev_b32_e32 v160, 16, v16
	v_and_b32_e32 v161, 0xffff0000, v16
	v_lshlrev_b32_e32 v16, 16, v17
	v_and_b32_e32 v17, 0xffff0000, v17
	v_lshlrev_b32_e32 v162, 16, v18
	v_and_b32_e32 v163, 0xffff0000, v18
	v_lshlrev_b32_e32 v18, 16, v19
	v_and_b32_e32 v19, 0xffff0000, v19
	v_pk_mul_f32 v[114:115], v[194:195], v[156:157]
	v_pk_mul_f32 v[116:117], v[196:197], v[12:13]
	v_pk_mul_f32 v[118:119], v[198:199], v[158:159]
	v_pk_mul_f32 v[120:121], v[200:201], v[14:15]
	v_pk_mul_f32 v[122:123], v[202:203], v[160:161]
	v_pk_mul_f32 v[124:125], v[204:205], v[16:17]
	v_pk_mul_f32 v[126:127], v[206:207], v[162:163]
	v_pk_mul_f32 v[128:129], v[208:209], v[18:19]
	v_pk_mul_f32 v[114:115], v[10:11], v[114:115]
	v_pk_mul_f32 v[116:117], v[10:11], v[116:117]
	v_pk_mul_f32 v[118:119], v[10:11], v[118:119]
	v_pk_mul_f32 v[120:121], v[10:11], v[120:121]
	v_pk_mul_f32 v[122:123], v[10:11], v[122:123]
	v_pk_mul_f32 v[124:125], v[10:11], v[124:125]
	v_pk_mul_f32 v[126:127], v[10:11], v[126:127]
	v_pk_mul_f32 v[128:129], v[10:11], v[128:129]
	v_pk_fma_f32 v[114:115], v[20:21], s[28:29], v[114:115] op_sel_hi:[1,0,1]
	v_pk_fma_f32 v[116:117], v[22:23], s[28:29], v[116:117] op_sel_hi:[1,0,1]
	v_pk_fma_f32 v[118:119], v[24:25], s[28:29], v[118:119] op_sel_hi:[1,0,1]
	v_pk_fma_f32 v[120:121], v[26:27], s[28:29], v[120:121] op_sel_hi:[1,0,1]
	v_pk_fma_f32 v[122:123], v[0:1], s[28:29], v[122:123] op_sel_hi:[1,0,1]
	v_pk_fma_f32 v[124:125], v[2:3], s[28:29], v[124:125] op_sel_hi:[1,0,1]
	v_pk_fma_f32 v[126:127], v[4:5], s[28:29], v[126:127] op_sel_hi:[1,0,1]
	v_pk_fma_f32 v[128:129], v[6:7], s[28:29], v[128:129] op_sel_hi:[1,0,1]
	v_add_f32_e32 v164, v114, v115
	v_add_f32_e32 v165, v116, v117
	v_add_f32_e32 v166, v118, v119
	v_add_f32_e32 v167, v120, v121
	v_add_f32_e32 v168, v122, v123
	v_add_f32_e32 v169, v124, v125
	v_add_f32_e32 v242, v126, v127
	v_add_f32_e32 v243, v128, v129
	v_add_f32_e32 v164, v164, v165
	v_add_f32_e32 v166, v166, v167
	v_add_f32_e32 v168, v168, v169
	v_add_f32_e32 v242, v242, v243
	v_add_f32_e32 v9, 0, v164
	v_add_f32_e32 v9, v9, v166
	v_add_f32_e32 v9, v9, v168
	v_add_f32_e32 v9, v9, v242
	ds_bpermute_b32 v28, v96, v9
	s_waitcnt lgkmcnt(0)
	v_add_f32_e32 v9, v9, v28
	ds_swizzle_b32 v28, v9 offset:swizzle(SWAP,16)
	s_waitcnt lgkmcnt(0)
	v_add_f32_e32 v9, v9, v28
	ds_swizzle_b32 v28, v9 offset:swizzle(SWAP,8)
	s_waitcnt lgkmcnt(0)
	v_add_f32_e32 v9, v9, v28
	ds_swizzle_b32 v28, v9 offset:swizzle(SWAP,4)
	s_waitcnt lgkmcnt(0)
	v_add_f32_e32 v9, v9, v28
	ds_swizzle_b32 v28, v9 offset:swizzle(SWAP,2)
	s_waitcnt lgkmcnt(0)
	v_add_f32_e32 v9, v9, v28
	ds_swizzle_b32 v28, v9 offset:swizzle(SWAP,1)
	s_waitcnt lgkmcnt(0)
	v_add_f32_e32 v9, v9, v28
	v_fmac_f32_e32 v114, 0xba800000, v9
	v_fmac_f32_e32 v115, 0xba800000, v9
	v_fmac_f32_e32 v116, 0xba800000, v9
	v_fmac_f32_e32 v117, 0xba800000, v9
	v_fmac_f32_e32 v118, 0xba800000, v9
	v_fmac_f32_e32 v119, 0xba800000, v9
	v_fmac_f32_e32 v120, 0xba800000, v9
	v_fmac_f32_e32 v121, 0xba800000, v9
	v_fmac_f32_e32 v122, 0xba800000, v9
	v_fmac_f32_e32 v123, 0xba800000, v9
	v_fmac_f32_e32 v124, 0xba800000, v9
	v_fmac_f32_e32 v125, 0xba800000, v9
	v_fmac_f32_e32 v126, 0xba800000, v9
	v_fmac_f32_e32 v127, 0xba800000, v9
	v_fmac_f32_e32 v128, 0xba800000, v9
	v_fmac_f32_e32 v129, 0xba800000, v9
	v_pk_mul_f32 v[244:245], v[114:115], v[114:115]
	v_pk_mul_f32 v[246:247], v[116:117], v[116:117]
	v_add_f32_e32 v244, v245, v244
	v_add_f32_e32 v246, v246, v247
	v_add_f32_e32 v164, v244, v246
	v_pk_mul_f32 v[244:245], v[118:119], v[118:119]
	v_pk_mul_f32 v[246:247], v[120:121], v[120:121]
	v_add_f32_e32 v244, v245, v244
	v_add_f32_e32 v246, v246, v247
	v_add_f32_e32 v165, v244, v246
	v_mul_f32_e32 v248, v122, v122
	v_mul_f32_e32 v249, v124, v124
	v_fmac_f32_e32 v248, v123, v123
	v_fmac_f32_e32 v249, v125, v125
	v_add_f32_e32 v166, v248, v249
	v_pk_mul_f32 v[244:245], v[126:127], v[126:127]
	v_pk_mul_f32 v[246:247], v[128:129], v[128:129]
	v_add_f32_e32 v244, v244, v245
	v_add_f32_e32 v246, v246, v247
	v_add_f32_e32 v167, v244, v246
	v_add_f32_e32 v164, v164, v165
	v_add_f32_e32 v164, v166, v164
	v_add_f32_e32 v9, v167, v164
	ds_bpermute_b32 v28, v96, v9
	s_waitcnt lgkmcnt(0)
	v_add_f32_e32 v9, v9, v28
	ds_swizzle_b32 v28, v9 offset:swizzle(SWAP,16)
	s_waitcnt lgkmcnt(0)
	v_add_f32_e32 v9, v9, v28
	ds_swizzle_b32 v28, v9 offset:swizzle(SWAP,8)
	s_waitcnt lgkmcnt(0)
	v_add_f32_e32 v9, v9, v28
	ds_swizzle_b32 v28, v9 offset:swizzle(SWAP,4)
	s_waitcnt lgkmcnt(0)
	v_add_f32_e32 v9, v9, v28
	ds_swizzle_b32 v28, v9 offset:swizzle(SWAP,2)
	s_waitcnt lgkmcnt(0)
	v_add_f32_e32 v9, v9, v28
	ds_swizzle_b32 v28, v9 offset:swizzle(SWAP,1)
	s_waitcnt lgkmcnt(0)
	v_add_f32_e32 v9, v9, v28
	v_mov_b32_e32 v28, 0x3727c5ac
	v_fmamk_f32 v9, v9, 0x3a800000, v28
	v_mul_f32_e32 v28, 0x4b800000, v9
	v_cmp_gt_f32_e32 vcc, s37, v9
	s_nop 1
	v_cndmask_b32_e32 v9, v9, v28, vcc
	v_rsq_f32_e32 v9, v9
	s_nop 0
	v_mul_f32_e32 v28, 0x45800000, v9
	v_cndmask_b32_e32 v30, v9, v28, vcc
	v_pk_mul_f32 v[114:115], v[114:115], v[30:31] op_sel_hi:[1,0]
	v_pk_mul_f32 v[116:117], v[116:117], v[30:31] op_sel_hi:[1,0]
	v_pk_fma_f32 v[20:21], v[140:141], v[114:115], v[98:99]
	v_pk_fma_f32 v[22:23], v[142:143], v[116:117], v[100:101]
	global_store_dwordx4 v[86:87], v[20:23], off sc1 nt
	v_pk_fma_f32 v[114:115], v[226:227], v[20:21], v[210:211]
	v_pk_fma_f32 v[116:117], v[228:229], v[22:23], v[212:213]
	s_nop 0
	v_cvt_pk_bf16_f32 v12, v114, v115
	v_cvt_pk_bf16_f32 v13, v116, v117
	global_store_dwordx2 v[88:89], v[12:13], off sc1
	v_pk_mul_f32 v[118:119], v[118:119], v[30:31] op_sel_hi:[1,0]
	v_pk_mul_f32 v[120:121], v[120:121], v[30:31] op_sel_hi:[1,0]
	v_pk_fma_f32 v[24:25], v[144:145], v[118:119], v[102:103]
	v_pk_fma_f32 v[26:27], v[146:147], v[120:121], v[104:105]
	global_store_dwordx4 v[86:87], v[24:27], off offset:1024 sc1 nt
	v_pk_fma_f32 v[118:119], v[230:231], v[24:25], v[214:215]
	v_pk_fma_f32 v[120:121], v[232:233], v[26:27], v[216:217]
	s_nop 0
	v_cvt_pk_bf16_f32 v14, v118, v119
	v_cvt_pk_bf16_f32 v15, v120, v121
	global_store_dwordx2 v[88:89], v[14:15], off offset:512 sc1
	v_pk_mul_f32 v[122:123], v[122:123], v[30:31] op_sel_hi:[1,0]
	v_pk_mul_f32 v[124:125], v[124:125], v[30:31] op_sel_hi:[1,0]
	v_pk_fma_f32 v[0:1], v[148:149], v[122:123], v[106:107]
	v_pk_fma_f32 v[2:3], v[150:151], v[124:125], v[108:109]
	global_store_dwordx4 v[86:87], v[0:3], off offset:2048 sc1 nt
	v_pk_fma_f32 v[122:123], v[234:235], v[0:1], v[218:219]
	v_pk_fma_f32 v[124:125], v[236:237], v[2:3], v[220:221]
	s_nop 0
	v_cvt_pk_bf16_f32 v16, v122, v123
	v_cvt_pk_bf16_f32 v17, v124, v125
	global_store_dwordx2 v[88:89], v[16:17], off offset:1024 sc1
	v_pk_mul_f32 v[126:127], v[126:127], v[30:31] op_sel_hi:[1,0]
	v_pk_mul_f32 v[128:129], v[128:129], v[30:31] op_sel_hi:[1,0]
	v_pk_fma_f32 v[4:5], v[152:153], v[126:127], v[110:111]
	v_pk_fma_f32 v[6:7], v[154:155], v[128:129], v[112:113]
	global_store_dwordx4 v[86:87], v[4:7], off offset:3072 sc1 nt
	v_pk_fma_f32 v[126:127], v[238:239], v[4:5], v[222:223]
	v_pk_fma_f32 v[128:129], v[240:241], v[6:7], v[224:225]
	s_nop 0
	v_cvt_pk_bf16_f32 v18, v126, v127
	v_cvt_pk_bf16_f32 v19, v128, v129
	global_store_dwordx2 v[88:89], v[18:19], off offset:1536 sc1
	v_lshl_add_u64 v[86:87], v[86:87], 0, s[0:1]
	v_lshl_add_u64 v[88:89], v[88:89], 0, s[20:21]
	global_load_dwordx4 v[20:23], v[82:83], off nt
	global_load_dwordx4 v[24:27], v[82:83], off offset:1024 nt
	global_load_dwordx4 v[0:3], v[82:83], off offset:2048 nt
	global_load_dwordx4 v[4:7], v[82:83], off offset:3072 nt
	global_load_dwordx2 v[12:13], v[84:85], off
	global_load_dwordx2 v[14:15], v[84:85], off offset:512
	global_load_dwordx2 v[16:17], v[84:85], off offset:1024
	global_load_dwordx2 v[18:19], v[84:85], off offset:1536
	v_lshl_add_u64 v[82:83], v[82:83], 0, s[0:1]
	v_lshl_add_u64 v[84:85], v[84:85], 0, s[20:21]
	s_waitcnt vmcnt(32)
	v_lshlrev_b32_e32 v156, 16, v50
	v_and_b32_e32 v157, 0xffff0000, v50
	v_lshlrev_b32_e32 v50, 16, v51
	v_and_b32_e32 v51, 0xffff0000, v51
	v_lshlrev_b32_e32 v158, 16, v52
	v_and_b32_e32 v159, 0xffff0000, v52
	v_lshlrev_b32_e32 v52, 16, v53
	v_and_b32_e32 v53, 0xffff0000, v53
	v_lshlrev_b32_e32 v160, 16, v54
	v_and_b32_e32 v161, 0xffff0000, v54
	v_lshlrev_b32_e32 v54, 16, v55
	v_and_b32_e32 v55, 0xffff0000, v55
	v_lshlrev_b32_e32 v162, 16, v56
	v_and_b32_e32 v163, 0xffff0000, v56
	v_lshlrev_b32_e32 v56, 16, v57
	v_and_b32_e32 v57, 0xffff0000, v57
	v_pk_mul_f32 v[114:115], v[194:195], v[156:157]
	v_pk_mul_f32 v[116:117], v[196:197], v[50:51]
	v_pk_mul_f32 v[118:119], v[198:199], v[158:159]
	v_pk_mul_f32 v[120:121], v[200:201], v[52:53]
	v_pk_mul_f32 v[122:123], v[202:203], v[160:161]
	v_pk_mul_f32 v[124:125], v[204:205], v[54:55]
	v_pk_mul_f32 v[126:127], v[206:207], v[162:163]
	v_pk_mul_f32 v[128:129], v[208:209], v[56:57]
	v_pk_mul_f32 v[114:115], v[10:11], v[114:115]
	v_pk_mul_f32 v[116:117], v[10:11], v[116:117]
	v_pk_mul_f32 v[118:119], v[10:11], v[118:119]
	v_pk_mul_f32 v[120:121], v[10:11], v[120:121]
	v_pk_mul_f32 v[122:123], v[10:11], v[122:123]
	v_pk_mul_f32 v[124:125], v[10:11], v[124:125]
	v_pk_mul_f32 v[126:127], v[10:11], v[126:127]
	v_pk_mul_f32 v[128:129], v[10:11], v[128:129]
	v_pk_fma_f32 v[114:115], v[34:35], s[28:29], v[114:115] op_sel_hi:[1,0,1]
	v_pk_fma_f32 v[116:117], v[36:37], s[28:29], v[116:117] op_sel_hi:[1,0,1]
	v_pk_fma_f32 v[118:119], v[38:39], s[28:29], v[118:119] op_sel_hi:[1,0,1]
	v_pk_fma_f32 v[120:121], v[40:41], s[28:29], v[120:121] op_sel_hi:[1,0,1]
	v_pk_fma_f32 v[122:123], v[42:43], s[28:29], v[122:123] op_sel_hi:[1,0,1]
	v_pk_fma_f32 v[124:125], v[44:45], s[28:29], v[124:125] op_sel_hi:[1,0,1]
	v_pk_fma_f32 v[126:127], v[46:47], s[28:29], v[126:127] op_sel_hi:[1,0,1]
	v_pk_fma_f32 v[128:129], v[48:49], s[28:29], v[128:129] op_sel_hi:[1,0,1]
	v_add_f32_e32 v164, v114, v115
	v_add_f32_e32 v165, v116, v117
	v_add_f32_e32 v166, v118, v119
	v_add_f32_e32 v167, v120, v121
	v_add_f32_e32 v168, v122, v123
	v_add_f32_e32 v169, v124, v125
	v_add_f32_e32 v242, v126, v127
	v_add_f32_e32 v243, v128, v129
	v_add_f32_e32 v164, v164, v165
	v_add_f32_e32 v166, v166, v167
	v_add_f32_e32 v168, v168, v169
	v_add_f32_e32 v242, v242, v243
	v_add_f32_e32 v9, 0, v164
	v_add_f32_e32 v9, v9, v166
	v_add_f32_e32 v9, v9, v168
	v_add_f32_e32 v9, v9, v242
	ds_bpermute_b32 v28, v96, v9
	s_waitcnt lgkmcnt(0)
	v_add_f32_e32 v9, v9, v28
	ds_swizzle_b32 v28, v9 offset:swizzle(SWAP,16)
	s_waitcnt lgkmcnt(0)
	v_add_f32_e32 v9, v9, v28
	ds_swizzle_b32 v28, v9 offset:swizzle(SWAP,8)
	s_waitcnt lgkmcnt(0)
	v_add_f32_e32 v9, v9, v28
	ds_swizzle_b32 v28, v9 offset:swizzle(SWAP,4)
	s_waitcnt lgkmcnt(0)
	v_add_f32_e32 v9, v9, v28
	ds_swizzle_b32 v28, v9 offset:swizzle(SWAP,2)
	s_waitcnt lgkmcnt(0)
	v_add_f32_e32 v9, v9, v28
	ds_swizzle_b32 v28, v9 offset:swizzle(SWAP,1)
	s_waitcnt lgkmcnt(0)
	v_add_f32_e32 v9, v9, v28
	v_fmac_f32_e32 v114, 0xba800000, v9
	v_fmac_f32_e32 v115, 0xba800000, v9
	v_fmac_f32_e32 v116, 0xba800000, v9
	v_fmac_f32_e32 v117, 0xba800000, v9
	v_fmac_f32_e32 v118, 0xba800000, v9
	v_fmac_f32_e32 v119, 0xba800000, v9
	v_fmac_f32_e32 v120, 0xba800000, v9
	v_fmac_f32_e32 v121, 0xba800000, v9
	v_fmac_f32_e32 v122, 0xba800000, v9
	v_fmac_f32_e32 v123, 0xba800000, v9
	v_fmac_f32_e32 v124, 0xba800000, v9
	v_fmac_f32_e32 v125, 0xba800000, v9
	v_fmac_f32_e32 v126, 0xba800000, v9
	v_fmac_f32_e32 v127, 0xba800000, v9
	v_fmac_f32_e32 v128, 0xba800000, v9
	v_fmac_f32_e32 v129, 0xba800000, v9
	v_pk_mul_f32 v[244:245], v[114:115], v[114:115]
	v_pk_mul_f32 v[246:247], v[116:117], v[116:117]
	v_add_f32_e32 v244, v245, v244
	v_add_f32_e32 v246, v246, v247
	v_add_f32_e32 v164, v244, v246
	v_pk_mul_f32 v[244:245], v[118:119], v[118:119]
	v_pk_mul_f32 v[246:247], v[120:121], v[120:121]
	v_add_f32_e32 v244, v245, v244
	v_add_f32_e32 v246, v246, v247
	v_add_f32_e32 v165, v244, v246
	v_mul_f32_e32 v248, v122, v122
	v_mul_f32_e32 v249, v124, v124
	v_fmac_f32_e32 v248, v123, v123
	v_fmac_f32_e32 v249, v125, v125
	v_add_f32_e32 v166, v248, v249
	v_pk_mul_f32 v[244:245], v[126:127], v[126:127]
	v_pk_mul_f32 v[246:247], v[128:129], v[128:129]
	v_add_f32_e32 v244, v244, v245
	v_add_f32_e32 v246, v246, v247
	v_add_f32_e32 v167, v244, v246
	v_add_f32_e32 v164, v164, v165
	v_add_f32_e32 v164, v166, v164
	v_add_f32_e32 v9, v167, v164
	ds_bpermute_b32 v28, v96, v9
	s_waitcnt lgkmcnt(0)
	v_add_f32_e32 v9, v9, v28
	ds_swizzle_b32 v28, v9 offset:swizzle(SWAP,16)
	s_waitcnt lgkmcnt(0)
	v_add_f32_e32 v9, v9, v28
	ds_swizzle_b32 v28, v9 offset:swizzle(SWAP,8)
	s_waitcnt lgkmcnt(0)
	v_add_f32_e32 v9, v9, v28
	ds_swizzle_b32 v28, v9 offset:swizzle(SWAP,4)
	s_waitcnt lgkmcnt(0)
	v_add_f32_e32 v9, v9, v28
	ds_swizzle_b32 v28, v9 offset:swizzle(SWAP,2)
	s_waitcnt lgkmcnt(0)
	v_add_f32_e32 v9, v9, v28
	ds_swizzle_b32 v28, v9 offset:swizzle(SWAP,1)
	s_waitcnt lgkmcnt(0)
	v_add_f32_e32 v9, v9, v28
	v_mov_b32_e32 v28, 0x3727c5ac
	v_fmamk_f32 v9, v9, 0x3a800000, v28
	v_mul_f32_e32 v28, 0x4b800000, v9
	v_cmp_gt_f32_e32 vcc, s37, v9
	s_nop 1
	v_cndmask_b32_e32 v9, v9, v28, vcc
	v_rsq_f32_e32 v9, v9
	s_nop 0
	v_mul_f32_e32 v28, 0x45800000, v9
	v_cndmask_b32_e32 v30, v9, v28, vcc
	v_pk_mul_f32 v[114:115], v[114:115], v[30:31] op_sel_hi:[1,0]
	v_pk_mul_f32 v[116:117], v[116:117], v[30:31] op_sel_hi:[1,0]
	v_pk_fma_f32 v[34:35], v[140:141], v[114:115], v[98:99]
	v_pk_fma_f32 v[36:37], v[142:143], v[116:117], v[100:101]
	global_store_dwordx4 v[86:87], v[34:37], off sc1 nt
	v_pk_fma_f32 v[114:115], v[226:227], v[34:35], v[210:211]
	v_pk_fma_f32 v[116:117], v[228:229], v[36:37], v[212:213]
	s_nop 0
	v_cvt_pk_bf16_f32 v50, v114, v115
	v_cvt_pk_bf16_f32 v51, v116, v117
	global_store_dwordx2 v[88:89], v[50:51], off sc1
	v_pk_mul_f32 v[118:119], v[118:119], v[30:31] op_sel_hi:[1,0]
	v_pk_mul_f32 v[120:121], v[120:121], v[30:31] op_sel_hi:[1,0]
	v_pk_fma_f32 v[38:39], v[144:145], v[118:119], v[102:103]
	v_pk_fma_f32 v[40:41], v[146:147], v[120:121], v[104:105]
	global_store_dwordx4 v[86:87], v[38:41], off offset:1024 sc1 nt
	v_pk_fma_f32 v[118:119], v[230:231], v[38:39], v[214:215]
	v_pk_fma_f32 v[120:121], v[232:233], v[40:41], v[216:217]
	s_nop 0
	v_cvt_pk_bf16_f32 v52, v118, v119
	v_cvt_pk_bf16_f32 v53, v120, v121
	global_store_dwordx2 v[88:89], v[52:53], off offset:512 sc1
	v_pk_mul_f32 v[122:123], v[122:123], v[30:31] op_sel_hi:[1,0]
	v_pk_mul_f32 v[124:125], v[124:125], v[30:31] op_sel_hi:[1,0]
	v_pk_fma_f32 v[42:43], v[148:149], v[122:123], v[106:107]
	v_pk_fma_f32 v[44:45], v[150:151], v[124:125], v[108:109]
	global_store_dwordx4 v[86:87], v[42:45], off offset:2048 sc1 nt
	v_pk_fma_f32 v[122:123], v[234:235], v[42:43], v[218:219]
	v_pk_fma_f32 v[124:125], v[236:237], v[44:45], v[220:221]
	s_nop 0
	v_cvt_pk_bf16_f32 v54, v122, v123
	v_cvt_pk_bf16_f32 v55, v124, v125
	global_store_dwordx2 v[88:89], v[54:55], off offset:1024 sc1
	v_pk_mul_f32 v[126:127], v[126:127], v[30:31] op_sel_hi:[1,0]
	v_pk_mul_f32 v[128:129], v[128:129], v[30:31] op_sel_hi:[1,0]
	v_pk_fma_f32 v[46:47], v[152:153], v[126:127], v[110:111]
	v_pk_fma_f32 v[48:49], v[154:155], v[128:129], v[112:113]
	global_store_dwordx4 v[86:87], v[46:49], off offset:3072 sc1 nt
	v_pk_fma_f32 v[126:127], v[238:239], v[46:47], v[222:223]
	v_pk_fma_f32 v[128:129], v[240:241], v[48:49], v[224:225]
	s_nop 0
	v_cvt_pk_bf16_f32 v56, v126, v127
	v_cvt_pk_bf16_f32 v57, v128, v129
	global_store_dwordx2 v[88:89], v[56:57], off offset:1536 sc1
	v_lshl_add_u64 v[86:87], v[86:87], 0, s[0:1]
	v_lshl_add_u64 v[88:89], v[88:89], 0, s[20:21]
	global_load_dwordx4 v[34:37], v[82:83], off nt
	global_load_dwordx4 v[38:41], v[82:83], off offset:1024 nt
	global_load_dwordx4 v[42:45], v[82:83], off offset:2048 nt
	global_load_dwordx4 v[46:49], v[82:83], off offset:3072 nt
	global_load_dwordx2 v[50:51], v[84:85], off
	global_load_dwordx2 v[52:53], v[84:85], off offset:512
	global_load_dwordx2 v[54:55], v[84:85], off offset:1024
	global_load_dwordx2 v[56:57], v[84:85], off offset:1536
	v_lshl_add_u64 v[82:83], v[82:83], 0, s[0:1]
	v_lshl_add_u64 v[84:85], v[84:85], 0, s[20:21]
	s_waitcnt vmcnt(32)
	v_lshlrev_b32_e32 v156, 16, v74
	v_and_b32_e32 v157, 0xffff0000, v74
	v_lshlrev_b32_e32 v74, 16, v75
	v_and_b32_e32 v75, 0xffff0000, v75
	v_lshlrev_b32_e32 v158, 16, v76
	v_and_b32_e32 v159, 0xffff0000, v76
	v_lshlrev_b32_e32 v76, 16, v77
	v_and_b32_e32 v77, 0xffff0000, v77
	v_lshlrev_b32_e32 v160, 16, v78
	v_and_b32_e32 v161, 0xffff0000, v78
	v_lshlrev_b32_e32 v78, 16, v79
	v_and_b32_e32 v79, 0xffff0000, v79
	v_lshlrev_b32_e32 v162, 16, v80
	v_and_b32_e32 v163, 0xffff0000, v80
	v_lshlrev_b32_e32 v80, 16, v81
	v_and_b32_e32 v81, 0xffff0000, v81
	v_pk_mul_f32 v[114:115], v[194:195], v[156:157]
	v_pk_mul_f32 v[116:117], v[196:197], v[74:75]
	v_pk_mul_f32 v[118:119], v[198:199], v[158:159]
	v_pk_mul_f32 v[120:121], v[200:201], v[76:77]
	v_pk_mul_f32 v[122:123], v[202:203], v[160:161]
	v_pk_mul_f32 v[124:125], v[204:205], v[78:79]
	v_pk_mul_f32 v[126:127], v[206:207], v[162:163]
	v_pk_mul_f32 v[128:129], v[208:209], v[80:81]
	v_pk_mul_f32 v[114:115], v[10:11], v[114:115]
	v_pk_mul_f32 v[116:117], v[10:11], v[116:117]
	v_pk_mul_f32 v[118:119], v[10:11], v[118:119]
	v_pk_mul_f32 v[120:121], v[10:11], v[120:121]
	v_pk_mul_f32 v[122:123], v[10:11], v[122:123]
	v_pk_mul_f32 v[124:125], v[10:11], v[124:125]
	v_pk_mul_f32 v[126:127], v[10:11], v[126:127]
	v_pk_mul_f32 v[128:129], v[10:11], v[128:129]
	v_pk_fma_f32 v[114:115], v[58:59], s[28:29], v[114:115] op_sel_hi:[1,0,1]
	v_pk_fma_f32 v[116:117], v[60:61], s[28:29], v[116:117] op_sel_hi:[1,0,1]
	v_pk_fma_f32 v[118:119], v[62:63], s[28:29], v[118:119] op_sel_hi:[1,0,1]
	v_pk_fma_f32 v[120:121], v[64:65], s[28:29], v[120:121] op_sel_hi:[1,0,1]
	v_pk_fma_f32 v[122:123], v[66:67], s[28:29], v[122:123] op_sel_hi:[1,0,1]
	v_pk_fma_f32 v[124:125], v[68:69], s[28:29], v[124:125] op_sel_hi:[1,0,1]
	v_pk_fma_f32 v[126:127], v[70:71], s[28:29], v[126:127] op_sel_hi:[1,0,1]
	v_pk_fma_f32 v[128:129], v[72:73], s[28:29], v[128:129] op_sel_hi:[1,0,1]
	v_add_f32_e32 v164, v114, v115
	v_add_f32_e32 v165, v116, v117
	v_add_f32_e32 v166, v118, v119
	v_add_f32_e32 v167, v120, v121
	v_add_f32_e32 v168, v122, v123
	v_add_f32_e32 v169, v124, v125
	v_add_f32_e32 v242, v126, v127
	v_add_f32_e32 v243, v128, v129
	v_add_f32_e32 v164, v164, v165
	v_add_f32_e32 v166, v166, v167
	v_add_f32_e32 v168, v168, v169
	v_add_f32_e32 v242, v242, v243
	v_add_f32_e32 v9, 0, v164
	v_add_f32_e32 v9, v9, v166
	v_add_f32_e32 v9, v9, v168
	v_add_f32_e32 v9, v9, v242
	ds_bpermute_b32 v28, v96, v9
	s_waitcnt lgkmcnt(0)
	v_add_f32_e32 v9, v9, v28
	ds_swizzle_b32 v28, v9 offset:swizzle(SWAP,16)
	s_waitcnt lgkmcnt(0)
	v_add_f32_e32 v9, v9, v28
	ds_swizzle_b32 v28, v9 offset:swizzle(SWAP,8)
	s_waitcnt lgkmcnt(0)
	v_add_f32_e32 v9, v9, v28
	ds_swizzle_b32 v28, v9 offset:swizzle(SWAP,4)
	s_waitcnt lgkmcnt(0)
	v_add_f32_e32 v9, v9, v28
	ds_swizzle_b32 v28, v9 offset:swizzle(SWAP,2)
	s_waitcnt lgkmcnt(0)
	v_add_f32_e32 v9, v9, v28
	ds_swizzle_b32 v28, v9 offset:swizzle(SWAP,1)
	s_waitcnt lgkmcnt(0)
	v_add_f32_e32 v9, v9, v28
	v_fmac_f32_e32 v114, 0xba800000, v9
	v_fmac_f32_e32 v115, 0xba800000, v9
	v_fmac_f32_e32 v116, 0xba800000, v9
	v_fmac_f32_e32 v117, 0xba800000, v9
	v_fmac_f32_e32 v118, 0xba800000, v9
	v_fmac_f32_e32 v119, 0xba800000, v9
	v_fmac_f32_e32 v120, 0xba800000, v9
	v_fmac_f32_e32 v121, 0xba800000, v9
	v_fmac_f32_e32 v122, 0xba800000, v9
	v_fmac_f32_e32 v123, 0xba800000, v9
	v_fmac_f32_e32 v124, 0xba800000, v9
	v_fmac_f32_e32 v125, 0xba800000, v9
	v_fmac_f32_e32 v126, 0xba800000, v9
	v_fmac_f32_e32 v127, 0xba800000, v9
	v_fmac_f32_e32 v128, 0xba800000, v9
	v_fmac_f32_e32 v129, 0xba800000, v9
	v_pk_mul_f32 v[244:245], v[114:115], v[114:115]
	v_pk_mul_f32 v[246:247], v[116:117], v[116:117]
	v_add_f32_e32 v244, v245, v244
	v_add_f32_e32 v246, v246, v247
	v_add_f32_e32 v164, v244, v246
	v_pk_mul_f32 v[244:245], v[118:119], v[118:119]
	v_pk_mul_f32 v[246:247], v[120:121], v[120:121]
	v_add_f32_e32 v244, v245, v244
	v_add_f32_e32 v246, v246, v247
	v_add_f32_e32 v165, v244, v246
	v_mul_f32_e32 v248, v122, v122
	v_mul_f32_e32 v249, v124, v124
	v_fmac_f32_e32 v248, v123, v123
	v_fmac_f32_e32 v249, v125, v125
	v_add_f32_e32 v166, v248, v249
	v_pk_mul_f32 v[244:245], v[126:127], v[126:127]
	v_pk_mul_f32 v[246:247], v[128:129], v[128:129]
	v_add_f32_e32 v244, v244, v245
	v_add_f32_e32 v246, v246, v247
	v_add_f32_e32 v167, v244, v246
	v_add_f32_e32 v164, v164, v165
	v_add_f32_e32 v164, v166, v164
	v_add_f32_e32 v9, v167, v164
	ds_bpermute_b32 v28, v96, v9
	s_waitcnt lgkmcnt(0)
	v_add_f32_e32 v9, v9, v28
	ds_swizzle_b32 v28, v9 offset:swizzle(SWAP,16)
	s_waitcnt lgkmcnt(0)
	v_add_f32_e32 v9, v9, v28
	ds_swizzle_b32 v28, v9 offset:swizzle(SWAP,8)
	s_waitcnt lgkmcnt(0)
	v_add_f32_e32 v9, v9, v28
	ds_swizzle_b32 v28, v9 offset:swizzle(SWAP,4)
	s_waitcnt lgkmcnt(0)
	v_add_f32_e32 v9, v9, v28
	ds_swizzle_b32 v28, v9 offset:swizzle(SWAP,2)
	s_waitcnt lgkmcnt(0)
	v_add_f32_e32 v9, v9, v28
	ds_swizzle_b32 v28, v9 offset:swizzle(SWAP,1)
	s_waitcnt lgkmcnt(0)
	v_add_f32_e32 v9, v9, v28
	v_mov_b32_e32 v28, 0x3727c5ac
	v_fmamk_f32 v9, v9, 0x3a800000, v28
	v_mul_f32_e32 v28, 0x4b800000, v9
	v_cmp_gt_f32_e32 vcc, s37, v9
	s_nop 1
	v_cndmask_b32_e32 v9, v9, v28, vcc
	v_rsq_f32_e32 v9, v9
	s_nop 0
	v_mul_f32_e32 v28, 0x45800000, v9
	v_cndmask_b32_e32 v30, v9, v28, vcc
	v_pk_mul_f32 v[114:115], v[114:115], v[30:31] op_sel_hi:[1,0]
	v_pk_mul_f32 v[116:117], v[116:117], v[30:31] op_sel_hi:[1,0]
	v_pk_fma_f32 v[58:59], v[140:141], v[114:115], v[98:99]
	v_pk_fma_f32 v[60:61], v[142:143], v[116:117], v[100:101]
	global_store_dwordx4 v[86:87], v[58:61], off sc1 nt
	v_pk_fma_f32 v[114:115], v[226:227], v[58:59], v[210:211]
	v_pk_fma_f32 v[116:117], v[228:229], v[60:61], v[212:213]
	s_nop 0
	v_cvt_pk_bf16_f32 v74, v114, v115
	v_cvt_pk_bf16_f32 v75, v116, v117
	global_store_dwordx2 v[88:89], v[74:75], off sc1
	v_pk_mul_f32 v[118:119], v[118:119], v[30:31] op_sel_hi:[1,0]
	v_pk_mul_f32 v[120:121], v[120:121], v[30:31] op_sel_hi:[1,0]
	v_pk_fma_f32 v[62:63], v[144:145], v[118:119], v[102:103]
	v_pk_fma_f32 v[64:65], v[146:147], v[120:121], v[104:105]
	global_store_dwordx4 v[86:87], v[62:65], off offset:1024 sc1 nt
	v_pk_fma_f32 v[118:119], v[230:231], v[62:63], v[214:215]
	v_pk_fma_f32 v[120:121], v[232:233], v[64:65], v[216:217]
	s_nop 0
	v_cvt_pk_bf16_f32 v76, v118, v119
	v_cvt_pk_bf16_f32 v77, v120, v121
	global_store_dwordx2 v[88:89], v[76:77], off offset:512 sc1
	v_pk_mul_f32 v[122:123], v[122:123], v[30:31] op_sel_hi:[1,0]
	v_pk_mul_f32 v[124:125], v[124:125], v[30:31] op_sel_hi:[1,0]
	v_pk_fma_f32 v[66:67], v[148:149], v[122:123], v[106:107]
	v_pk_fma_f32 v[68:69], v[150:151], v[124:125], v[108:109]
	global_store_dwordx4 v[86:87], v[66:69], off offset:2048 sc1 nt
	v_pk_fma_f32 v[122:123], v[234:235], v[66:67], v[218:219]
	v_pk_fma_f32 v[124:125], v[236:237], v[68:69], v[220:221]
	s_nop 0
	v_cvt_pk_bf16_f32 v78, v122, v123
	v_cvt_pk_bf16_f32 v79, v124, v125
	global_store_dwordx2 v[88:89], v[78:79], off offset:1024 sc1
	v_pk_mul_f32 v[126:127], v[126:127], v[30:31] op_sel_hi:[1,0]
	v_pk_mul_f32 v[128:129], v[128:129], v[30:31] op_sel_hi:[1,0]
	v_pk_fma_f32 v[70:71], v[152:153], v[126:127], v[110:111]
	v_pk_fma_f32 v[72:73], v[154:155], v[128:129], v[112:113]
	global_store_dwordx4 v[86:87], v[70:73], off offset:3072 sc1 nt
	v_pk_fma_f32 v[126:127], v[238:239], v[70:71], v[222:223]
	v_pk_fma_f32 v[128:129], v[240:241], v[72:73], v[224:225]
	s_nop 0
	v_cvt_pk_bf16_f32 v80, v126, v127
	v_cvt_pk_bf16_f32 v81, v128, v129
	global_store_dwordx2 v[88:89], v[80:81], off offset:1536 sc1
	v_lshl_add_u64 v[86:87], v[86:87], 0, s[0:1]
	v_lshl_add_u64 v[88:89], v[88:89], 0, s[20:21]
	global_load_dwordx4 v[58:61], v[82:83], off nt
	global_load_dwordx4 v[62:65], v[82:83], off offset:1024 nt
	global_load_dwordx4 v[66:69], v[82:83], off offset:2048 nt
	global_load_dwordx4 v[70:73], v[82:83], off offset:3072 nt
	global_load_dwordx2 v[74:75], v[84:85], off
	global_load_dwordx2 v[76:77], v[84:85], off offset:512
	global_load_dwordx2 v[78:79], v[84:85], off offset:1024
	global_load_dwordx2 v[80:81], v[84:85], off offset:1536
	v_lshl_add_u64 v[82:83], v[82:83], 0, s[0:1]
	v_lshl_add_u64 v[84:85], v[84:85], 0, s[20:21]
	s_waitcnt vmcnt(32)
	v_lshlrev_b32_e32 v156, 16, v12
	v_and_b32_e32 v157, 0xffff0000, v12
	v_lshlrev_b32_e32 v12, 16, v13
	v_and_b32_e32 v13, 0xffff0000, v13
	v_lshlrev_b32_e32 v158, 16, v14
	v_and_b32_e32 v159, 0xffff0000, v14
	v_lshlrev_b32_e32 v14, 16, v15
	v_and_b32_e32 v15, 0xffff0000, v15
	v_lshlrev_b32_e32 v160, 16, v16
	v_and_b32_e32 v161, 0xffff0000, v16
	v_lshlrev_b32_e32 v16, 16, v17
	v_and_b32_e32 v17, 0xffff0000, v17
	v_lshlrev_b32_e32 v162, 16, v18
	v_and_b32_e32 v163, 0xffff0000, v18
	v_lshlrev_b32_e32 v18, 16, v19
	v_and_b32_e32 v19, 0xffff0000, v19
	v_pk_mul_f32 v[114:115], v[194:195], v[156:157]
	v_pk_mul_f32 v[116:117], v[196:197], v[12:13]
	v_pk_mul_f32 v[118:119], v[198:199], v[158:159]
	v_pk_mul_f32 v[120:121], v[200:201], v[14:15]
	v_pk_mul_f32 v[122:123], v[202:203], v[160:161]
	v_pk_mul_f32 v[124:125], v[204:205], v[16:17]
	v_pk_mul_f32 v[126:127], v[206:207], v[162:163]
	v_pk_mul_f32 v[128:129], v[208:209], v[18:19]
	v_pk_mul_f32 v[114:115], v[10:11], v[114:115]
	v_pk_mul_f32 v[116:117], v[10:11], v[116:117]
	v_pk_mul_f32 v[118:119], v[10:11], v[118:119]
	v_pk_mul_f32 v[120:121], v[10:11], v[120:121]
	v_pk_mul_f32 v[122:123], v[10:11], v[122:123]
	v_pk_mul_f32 v[124:125], v[10:11], v[124:125]
	v_pk_mul_f32 v[126:127], v[10:11], v[126:127]
	v_pk_mul_f32 v[128:129], v[10:11], v[128:129]
	v_pk_fma_f32 v[114:115], v[20:21], s[28:29], v[114:115] op_sel_hi:[1,0,1]
	v_pk_fma_f32 v[116:117], v[22:23], s[28:29], v[116:117] op_sel_hi:[1,0,1]
	v_pk_fma_f32 v[118:119], v[24:25], s[28:29], v[118:119] op_sel_hi:[1,0,1]
	v_pk_fma_f32 v[120:121], v[26:27], s[28:29], v[120:121] op_sel_hi:[1,0,1]
	v_pk_fma_f32 v[122:123], v[0:1], s[28:29], v[122:123] op_sel_hi:[1,0,1]
	v_pk_fma_f32 v[124:125], v[2:3], s[28:29], v[124:125] op_sel_hi:[1,0,1]
	v_pk_fma_f32 v[126:127], v[4:5], s[28:29], v[126:127] op_sel_hi:[1,0,1]
	v_pk_fma_f32 v[128:129], v[6:7], s[28:29], v[128:129] op_sel_hi:[1,0,1]
	v_add_f32_e32 v164, v114, v115
	v_add_f32_e32 v165, v116, v117
	v_add_f32_e32 v166, v118, v119
	v_add_f32_e32 v167, v120, v121
	v_add_f32_e32 v168, v122, v123
	v_add_f32_e32 v169, v124, v125
	v_add_f32_e32 v242, v126, v127
	v_add_f32_e32 v243, v128, v129
	v_add_f32_e32 v164, v164, v165
	v_add_f32_e32 v166, v166, v167
	v_add_f32_e32 v168, v168, v169
	v_add_f32_e32 v242, v242, v243
	v_add_f32_e32 v9, 0, v164
	v_add_f32_e32 v9, v9, v166
	v_add_f32_e32 v9, v9, v168
	v_add_f32_e32 v9, v9, v242
	ds_bpermute_b32 v28, v96, v9
	s_waitcnt lgkmcnt(0)
	v_add_f32_e32 v9, v9, v28
	ds_swizzle_b32 v28, v9 offset:swizzle(SWAP,16)
	s_waitcnt lgkmcnt(0)
	v_add_f32_e32 v9, v9, v28
	ds_swizzle_b32 v28, v9 offset:swizzle(SWAP,8)
	s_waitcnt lgkmcnt(0)
	v_add_f32_e32 v9, v9, v28
	ds_swizzle_b32 v28, v9 offset:swizzle(SWAP,4)
	s_waitcnt lgkmcnt(0)
	v_add_f32_e32 v9, v9, v28
	ds_swizzle_b32 v28, v9 offset:swizzle(SWAP,2)
	s_waitcnt lgkmcnt(0)
	v_add_f32_e32 v9, v9, v28
	ds_swizzle_b32 v28, v9 offset:swizzle(SWAP,1)
	s_waitcnt lgkmcnt(0)
	v_add_f32_e32 v9, v9, v28
	v_fmac_f32_e32 v114, 0xba800000, v9
	v_fmac_f32_e32 v115, 0xba800000, v9
	v_fmac_f32_e32 v116, 0xba800000, v9
	v_fmac_f32_e32 v117, 0xba800000, v9
	v_fmac_f32_e32 v118, 0xba800000, v9
	v_fmac_f32_e32 v119, 0xba800000, v9
	v_fmac_f32_e32 v120, 0xba800000, v9
	v_fmac_f32_e32 v121, 0xba800000, v9
	v_fmac_f32_e32 v122, 0xba800000, v9
	v_fmac_f32_e32 v123, 0xba800000, v9
	v_fmac_f32_e32 v124, 0xba800000, v9
	v_fmac_f32_e32 v125, 0xba800000, v9
	v_fmac_f32_e32 v126, 0xba800000, v9
	v_fmac_f32_e32 v127, 0xba800000, v9
	v_fmac_f32_e32 v128, 0xba800000, v9
	v_fmac_f32_e32 v129, 0xba800000, v9
	v_pk_mul_f32 v[244:245], v[114:115], v[114:115]
	v_pk_mul_f32 v[246:247], v[116:117], v[116:117]
	v_add_f32_e32 v244, v245, v244
	v_add_f32_e32 v246, v246, v247
	v_add_f32_e32 v164, v244, v246
	v_pk_mul_f32 v[244:245], v[118:119], v[118:119]
	v_pk_mul_f32 v[246:247], v[120:121], v[120:121]
	v_add_f32_e32 v244, v245, v244
	v_add_f32_e32 v246, v246, v247
	v_add_f32_e32 v165, v244, v246
	v_mul_f32_e32 v248, v122, v122
	v_mul_f32_e32 v249, v124, v124
	v_fmac_f32_e32 v248, v123, v123
	v_fmac_f32_e32 v249, v125, v125
	v_add_f32_e32 v166, v248, v249
	v_pk_mul_f32 v[244:245], v[126:127], v[126:127]
	v_pk_mul_f32 v[246:247], v[128:129], v[128:129]
	v_add_f32_e32 v244, v244, v245
	v_add_f32_e32 v246, v246, v247
	v_add_f32_e32 v167, v244, v246
	v_add_f32_e32 v164, v164, v165
	v_add_f32_e32 v164, v166, v164
	v_add_f32_e32 v9, v167, v164
	ds_bpermute_b32 v28, v96, v9
	s_waitcnt lgkmcnt(0)
	v_add_f32_e32 v9, v9, v28
	ds_swizzle_b32 v28, v9 offset:swizzle(SWAP,16)
	s_waitcnt lgkmcnt(0)
	v_add_f32_e32 v9, v9, v28
	ds_swizzle_b32 v28, v9 offset:swizzle(SWAP,8)
	s_waitcnt lgkmcnt(0)
	v_add_f32_e32 v9, v9, v28
	ds_swizzle_b32 v28, v9 offset:swizzle(SWAP,4)
	s_waitcnt lgkmcnt(0)
	v_add_f32_e32 v9, v9, v28
	ds_swizzle_b32 v28, v9 offset:swizzle(SWAP,2)
	s_waitcnt lgkmcnt(0)
	v_add_f32_e32 v9, v9, v28
	ds_swizzle_b32 v28, v9 offset:swizzle(SWAP,1)
	s_waitcnt lgkmcnt(0)
	v_add_f32_e32 v9, v9, v28
	v_mov_b32_e32 v28, 0x3727c5ac
	v_fmamk_f32 v9, v9, 0x3a800000, v28
	v_mul_f32_e32 v28, 0x4b800000, v9
	v_cmp_gt_f32_e32 vcc, s37, v9
	s_nop 1
	v_cndmask_b32_e32 v9, v9, v28, vcc
	v_rsq_f32_e32 v9, v9
	s_nop 0
	v_mul_f32_e32 v28, 0x45800000, v9
	v_cndmask_b32_e32 v30, v9, v28, vcc
	v_pk_mul_f32 v[114:115], v[114:115], v[30:31] op_sel_hi:[1,0]
	v_pk_mul_f32 v[116:117], v[116:117], v[30:31] op_sel_hi:[1,0]
	v_pk_fma_f32 v[20:21], v[140:141], v[114:115], v[98:99]
	v_pk_fma_f32 v[22:23], v[142:143], v[116:117], v[100:101]
	global_store_dwordx4 v[86:87], v[20:23], off sc1 nt
	v_pk_fma_f32 v[114:115], v[226:227], v[20:21], v[210:211]
	v_pk_fma_f32 v[116:117], v[228:229], v[22:23], v[212:213]
	s_nop 0
	v_cvt_pk_bf16_f32 v12, v114, v115
	v_cvt_pk_bf16_f32 v13, v116, v117
	global_store_dwordx2 v[88:89], v[12:13], off sc1
	v_pk_mul_f32 v[118:119], v[118:119], v[30:31] op_sel_hi:[1,0]
	v_pk_mul_f32 v[120:121], v[120:121], v[30:31] op_sel_hi:[1,0]
	v_pk_fma_f32 v[24:25], v[144:145], v[118:119], v[102:103]
	v_pk_fma_f32 v[26:27], v[146:147], v[120:121], v[104:105]
	global_store_dwordx4 v[86:87], v[24:27], off offset:1024 sc1 nt
	v_pk_fma_f32 v[118:119], v[230:231], v[24:25], v[214:215]
	v_pk_fma_f32 v[120:121], v[232:233], v[26:27], v[216:217]
	s_nop 0
	v_cvt_pk_bf16_f32 v14, v118, v119
	v_cvt_pk_bf16_f32 v15, v120, v121
	global_store_dwordx2 v[88:89], v[14:15], off offset:512 sc1
	v_pk_mul_f32 v[122:123], v[122:123], v[30:31] op_sel_hi:[1,0]
	v_pk_mul_f32 v[124:125], v[124:125], v[30:31] op_sel_hi:[1,0]
	v_pk_fma_f32 v[0:1], v[148:149], v[122:123], v[106:107]
	v_pk_fma_f32 v[2:3], v[150:151], v[124:125], v[108:109]
	global_store_dwordx4 v[86:87], v[0:3], off offset:2048 sc1 nt
	v_pk_fma_f32 v[122:123], v[234:235], v[0:1], v[218:219]
	v_pk_fma_f32 v[124:125], v[236:237], v[2:3], v[220:221]
	s_nop 0
	v_cvt_pk_bf16_f32 v16, v122, v123
	v_cvt_pk_bf16_f32 v17, v124, v125
	global_store_dwordx2 v[88:89], v[16:17], off offset:1024 sc1
	v_pk_mul_f32 v[126:127], v[126:127], v[30:31] op_sel_hi:[1,0]
	v_pk_mul_f32 v[128:129], v[128:129], v[30:31] op_sel_hi:[1,0]
	v_pk_fma_f32 v[4:5], v[152:153], v[126:127], v[110:111]
	v_pk_fma_f32 v[6:7], v[154:155], v[128:129], v[112:113]
	global_store_dwordx4 v[86:87], v[4:7], off offset:3072 sc1 nt
	v_pk_fma_f32 v[126:127], v[238:239], v[4:5], v[222:223]
	v_pk_fma_f32 v[128:129], v[240:241], v[6:7], v[224:225]
	s_nop 0
	v_cvt_pk_bf16_f32 v18, v126, v127
	v_cvt_pk_bf16_f32 v19, v128, v129
	global_store_dwordx2 v[88:89], v[18:19], off offset:1536 sc1
	v_lshl_add_u64 v[86:87], v[86:87], 0, s[0:1]
	v_lshl_add_u64 v[88:89], v[88:89], 0, s[20:21]
	global_load_dwordx4 v[20:23], v[82:83], off nt
	global_load_dwordx4 v[24:27], v[82:83], off offset:1024 nt
	global_load_dwordx4 v[0:3], v[82:83], off offset:2048 nt
	global_load_dwordx4 v[4:7], v[82:83], off offset:3072 nt
	global_load_dwordx2 v[12:13], v[84:85], off
	global_load_dwordx2 v[14:15], v[84:85], off offset:512
	global_load_dwordx2 v[16:17], v[84:85], off offset:1024
	global_load_dwordx2 v[18:19], v[84:85], off offset:1536
	v_lshl_add_u64 v[82:83], v[82:83], 0, s[0:1]
	v_lshl_add_u64 v[84:85], v[84:85], 0, s[20:21]
	s_waitcnt vmcnt(32)
	v_lshlrev_b32_e32 v156, 16, v50
	v_and_b32_e32 v157, 0xffff0000, v50
	v_lshlrev_b32_e32 v50, 16, v51
	v_and_b32_e32 v51, 0xffff0000, v51
	v_lshlrev_b32_e32 v158, 16, v52
	v_and_b32_e32 v159, 0xffff0000, v52
	v_lshlrev_b32_e32 v52, 16, v53
	v_and_b32_e32 v53, 0xffff0000, v53
	v_lshlrev_b32_e32 v160, 16, v54
	v_and_b32_e32 v161, 0xffff0000, v54
	v_lshlrev_b32_e32 v54, 16, v55
	v_and_b32_e32 v55, 0xffff0000, v55
	v_lshlrev_b32_e32 v162, 16, v56
	v_and_b32_e32 v163, 0xffff0000, v56
	v_lshlrev_b32_e32 v56, 16, v57
	v_and_b32_e32 v57, 0xffff0000, v57
	v_pk_mul_f32 v[114:115], v[194:195], v[156:157]
	v_pk_mul_f32 v[116:117], v[196:197], v[50:51]
	v_pk_mul_f32 v[118:119], v[198:199], v[158:159]
	v_pk_mul_f32 v[120:121], v[200:201], v[52:53]
	v_pk_mul_f32 v[122:123], v[202:203], v[160:161]
	v_pk_mul_f32 v[124:125], v[204:205], v[54:55]
	v_pk_mul_f32 v[126:127], v[206:207], v[162:163]
	v_pk_mul_f32 v[128:129], v[208:209], v[56:57]
	v_pk_mul_f32 v[114:115], v[10:11], v[114:115]
	v_pk_mul_f32 v[116:117], v[10:11], v[116:117]
	v_pk_mul_f32 v[118:119], v[10:11], v[118:119]
	v_pk_mul_f32 v[120:121], v[10:11], v[120:121]
	v_pk_mul_f32 v[122:123], v[10:11], v[122:123]
	v_pk_mul_f32 v[124:125], v[10:11], v[124:125]
	v_pk_mul_f32 v[126:127], v[10:11], v[126:127]
	v_pk_mul_f32 v[128:129], v[10:11], v[128:129]
	v_pk_fma_f32 v[114:115], v[34:35], s[28:29], v[114:115] op_sel_hi:[1,0,1]
	v_pk_fma_f32 v[116:117], v[36:37], s[28:29], v[116:117] op_sel_hi:[1,0,1]
	v_pk_fma_f32 v[118:119], v[38:39], s[28:29], v[118:119] op_sel_hi:[1,0,1]
	v_pk_fma_f32 v[120:121], v[40:41], s[28:29], v[120:121] op_sel_hi:[1,0,1]
	v_pk_fma_f32 v[122:123], v[42:43], s[28:29], v[122:123] op_sel_hi:[1,0,1]
	v_pk_fma_f32 v[124:125], v[44:45], s[28:29], v[124:125] op_sel_hi:[1,0,1]
	v_pk_fma_f32 v[126:127], v[46:47], s[28:29], v[126:127] op_sel_hi:[1,0,1]
	v_pk_fma_f32 v[128:129], v[48:49], s[28:29], v[128:129] op_sel_hi:[1,0,1]
	v_add_f32_e32 v164, v114, v115
	v_add_f32_e32 v165, v116, v117
	v_add_f32_e32 v166, v118, v119
	v_add_f32_e32 v167, v120, v121
	v_add_f32_e32 v168, v122, v123
	v_add_f32_e32 v169, v124, v125
	v_add_f32_e32 v242, v126, v127
	v_add_f32_e32 v243, v128, v129
	v_add_f32_e32 v164, v164, v165
	v_add_f32_e32 v166, v166, v167
	v_add_f32_e32 v168, v168, v169
	v_add_f32_e32 v242, v242, v243
	v_add_f32_e32 v9, 0, v164
	v_add_f32_e32 v9, v9, v166
	v_add_f32_e32 v9, v9, v168
	v_add_f32_e32 v9, v9, v242
	ds_bpermute_b32 v28, v96, v9
	s_waitcnt lgkmcnt(0)
	v_add_f32_e32 v9, v9, v28
	ds_swizzle_b32 v28, v9 offset:swizzle(SWAP,16)
	s_waitcnt lgkmcnt(0)
	v_add_f32_e32 v9, v9, v28
	ds_swizzle_b32 v28, v9 offset:swizzle(SWAP,8)
	s_waitcnt lgkmcnt(0)
	v_add_f32_e32 v9, v9, v28
	ds_swizzle_b32 v28, v9 offset:swizzle(SWAP,4)
	s_waitcnt lgkmcnt(0)
	v_add_f32_e32 v9, v9, v28
	ds_swizzle_b32 v28, v9 offset:swizzle(SWAP,2)
	s_waitcnt lgkmcnt(0)
	v_add_f32_e32 v9, v9, v28
	ds_swizzle_b32 v28, v9 offset:swizzle(SWAP,1)
	s_waitcnt lgkmcnt(0)
	v_add_f32_e32 v9, v9, v28
	v_fmac_f32_e32 v114, 0xba800000, v9
	v_fmac_f32_e32 v115, 0xba800000, v9
	v_fmac_f32_e32 v116, 0xba800000, v9
	v_fmac_f32_e32 v117, 0xba800000, v9
	v_fmac_f32_e32 v118, 0xba800000, v9
	v_fmac_f32_e32 v119, 0xba800000, v9
	v_fmac_f32_e32 v120, 0xba800000, v9
	v_fmac_f32_e32 v121, 0xba800000, v9
	v_fmac_f32_e32 v122, 0xba800000, v9
	v_fmac_f32_e32 v123, 0xba800000, v9
	v_fmac_f32_e32 v124, 0xba800000, v9
	v_fmac_f32_e32 v125, 0xba800000, v9
	v_fmac_f32_e32 v126, 0xba800000, v9
	v_fmac_f32_e32 v127, 0xba800000, v9
	v_fmac_f32_e32 v128, 0xba800000, v9
	v_fmac_f32_e32 v129, 0xba800000, v9
	v_pk_mul_f32 v[244:245], v[114:115], v[114:115]
	v_pk_mul_f32 v[246:247], v[116:117], v[116:117]
	v_add_f32_e32 v244, v245, v244
	v_add_f32_e32 v246, v246, v247
	v_add_f32_e32 v164, v244, v246
	v_pk_mul_f32 v[244:245], v[118:119], v[118:119]
	v_pk_mul_f32 v[246:247], v[120:121], v[120:121]
	v_add_f32_e32 v244, v245, v244
	v_add_f32_e32 v246, v246, v247
	v_add_f32_e32 v165, v244, v246
	v_mul_f32_e32 v248, v122, v122
	v_mul_f32_e32 v249, v124, v124
	v_fmac_f32_e32 v248, v123, v123
	v_fmac_f32_e32 v249, v125, v125
	v_add_f32_e32 v166, v248, v249
	v_pk_mul_f32 v[244:245], v[126:127], v[126:127]
	v_pk_mul_f32 v[246:247], v[128:129], v[128:129]
	v_add_f32_e32 v244, v244, v245
	v_add_f32_e32 v246, v246, v247
	v_add_f32_e32 v167, v244, v246
	v_add_f32_e32 v164, v164, v165
	v_add_f32_e32 v164, v166, v164
	v_add_f32_e32 v9, v167, v164
	ds_bpermute_b32 v28, v96, v9
	s_waitcnt lgkmcnt(0)
	v_add_f32_e32 v9, v9, v28
	ds_swizzle_b32 v28, v9 offset:swizzle(SWAP,16)
	s_waitcnt lgkmcnt(0)
	v_add_f32_e32 v9, v9, v28
	ds_swizzle_b32 v28, v9 offset:swizzle(SWAP,8)
	s_waitcnt lgkmcnt(0)
	v_add_f32_e32 v9, v9, v28
	ds_swizzle_b32 v28, v9 offset:swizzle(SWAP,4)
	s_waitcnt lgkmcnt(0)
	v_add_f32_e32 v9, v9, v28
	ds_swizzle_b32 v28, v9 offset:swizzle(SWAP,2)
	s_waitcnt lgkmcnt(0)
	v_add_f32_e32 v9, v9, v28
	ds_swizzle_b32 v28, v9 offset:swizzle(SWAP,1)
	s_waitcnt lgkmcnt(0)
	v_add_f32_e32 v9, v9, v28
	v_mov_b32_e32 v28, 0x3727c5ac
	v_fmamk_f32 v9, v9, 0x3a800000, v28
	v_mul_f32_e32 v28, 0x4b800000, v9
	v_cmp_gt_f32_e32 vcc, s37, v9
	s_nop 1
	v_cndmask_b32_e32 v9, v9, v28, vcc
	v_rsq_f32_e32 v9, v9
	s_nop 0
	v_mul_f32_e32 v28, 0x45800000, v9
	v_cndmask_b32_e32 v30, v9, v28, vcc
	v_pk_mul_f32 v[114:115], v[114:115], v[30:31] op_sel_hi:[1,0]
	v_pk_mul_f32 v[116:117], v[116:117], v[30:31] op_sel_hi:[1,0]
	v_pk_fma_f32 v[34:35], v[140:141], v[114:115], v[98:99]
	v_pk_fma_f32 v[36:37], v[142:143], v[116:117], v[100:101]
	global_store_dwordx4 v[86:87], v[34:37], off sc1 nt
	v_pk_fma_f32 v[114:115], v[226:227], v[34:35], v[210:211]
	v_pk_fma_f32 v[116:117], v[228:229], v[36:37], v[212:213]
	s_nop 0
	v_cvt_pk_bf16_f32 v50, v114, v115
	v_cvt_pk_bf16_f32 v51, v116, v117
	global_store_dwordx2 v[88:89], v[50:51], off sc1
	v_pk_mul_f32 v[118:119], v[118:119], v[30:31] op_sel_hi:[1,0]
	v_pk_mul_f32 v[120:121], v[120:121], v[30:31] op_sel_hi:[1,0]
	v_pk_fma_f32 v[38:39], v[144:145], v[118:119], v[102:103]
	v_pk_fma_f32 v[40:41], v[146:147], v[120:121], v[104:105]
	global_store_dwordx4 v[86:87], v[38:41], off offset:1024 sc1 nt
	v_pk_fma_f32 v[118:119], v[230:231], v[38:39], v[214:215]
	v_pk_fma_f32 v[120:121], v[232:233], v[40:41], v[216:217]
	s_nop 0
	v_cvt_pk_bf16_f32 v52, v118, v119
	v_cvt_pk_bf16_f32 v53, v120, v121
	global_store_dwordx2 v[88:89], v[52:53], off offset:512 sc1
	v_pk_mul_f32 v[122:123], v[122:123], v[30:31] op_sel_hi:[1,0]
	v_pk_mul_f32 v[124:125], v[124:125], v[30:31] op_sel_hi:[1,0]
	v_pk_fma_f32 v[42:43], v[148:149], v[122:123], v[106:107]
	v_pk_fma_f32 v[44:45], v[150:151], v[124:125], v[108:109]
	global_store_dwordx4 v[86:87], v[42:45], off offset:2048 sc1 nt
	v_pk_fma_f32 v[122:123], v[234:235], v[42:43], v[218:219]
	v_pk_fma_f32 v[124:125], v[236:237], v[44:45], v[220:221]
	s_nop 0
	v_cvt_pk_bf16_f32 v54, v122, v123
	v_cvt_pk_bf16_f32 v55, v124, v125
	global_store_dwordx2 v[88:89], v[54:55], off offset:1024 sc1
	v_pk_mul_f32 v[126:127], v[126:127], v[30:31] op_sel_hi:[1,0]
	v_pk_mul_f32 v[128:129], v[128:129], v[30:31] op_sel_hi:[1,0]
	v_pk_fma_f32 v[46:47], v[152:153], v[126:127], v[110:111]
	v_pk_fma_f32 v[48:49], v[154:155], v[128:129], v[112:113]
	global_store_dwordx4 v[86:87], v[46:49], off offset:3072 sc1 nt
	v_pk_fma_f32 v[126:127], v[238:239], v[46:47], v[222:223]
	v_pk_fma_f32 v[128:129], v[240:241], v[48:49], v[224:225]
	s_nop 0
	v_cvt_pk_bf16_f32 v56, v126, v127
	v_cvt_pk_bf16_f32 v57, v128, v129
	global_store_dwordx2 v[88:89], v[56:57], off offset:1536 sc1
	v_lshl_add_u64 v[86:87], v[86:87], 0, s[0:1]
	v_lshl_add_u64 v[88:89], v[88:89], 0, s[20:21]
	global_load_dwordx4 v[34:37], v[82:83], off nt
	global_load_dwordx4 v[38:41], v[82:83], off offset:1024 nt
	global_load_dwordx4 v[42:45], v[82:83], off offset:2048 nt
	global_load_dwordx4 v[46:49], v[82:83], off offset:3072 nt
	global_load_dwordx2 v[50:51], v[84:85], off
	global_load_dwordx2 v[52:53], v[84:85], off offset:512
	global_load_dwordx2 v[54:55], v[84:85], off offset:1024
	global_load_dwordx2 v[56:57], v[84:85], off offset:1536
	v_lshl_add_u64 v[82:83], v[82:83], 0, s[0:1]
	v_lshl_add_u64 v[84:85], v[84:85], 0, s[20:21]
	s_waitcnt vmcnt(32)
	v_lshlrev_b32_e32 v156, 16, v74
	v_and_b32_e32 v157, 0xffff0000, v74
	v_lshlrev_b32_e32 v74, 16, v75
	v_and_b32_e32 v75, 0xffff0000, v75
	v_lshlrev_b32_e32 v158, 16, v76
	v_and_b32_e32 v159, 0xffff0000, v76
	v_lshlrev_b32_e32 v76, 16, v77
	v_and_b32_e32 v77, 0xffff0000, v77
	v_lshlrev_b32_e32 v160, 16, v78
	v_and_b32_e32 v161, 0xffff0000, v78
	v_lshlrev_b32_e32 v78, 16, v79
	v_and_b32_e32 v79, 0xffff0000, v79
	v_lshlrev_b32_e32 v162, 16, v80
	v_and_b32_e32 v163, 0xffff0000, v80
	v_lshlrev_b32_e32 v80, 16, v81
	v_and_b32_e32 v81, 0xffff0000, v81
	v_pk_mul_f32 v[114:115], v[194:195], v[156:157]
	v_pk_mul_f32 v[116:117], v[196:197], v[74:75]
	v_pk_mul_f32 v[118:119], v[198:199], v[158:159]
	v_pk_mul_f32 v[120:121], v[200:201], v[76:77]
	v_pk_mul_f32 v[122:123], v[202:203], v[160:161]
	v_pk_mul_f32 v[124:125], v[204:205], v[78:79]
	v_pk_mul_f32 v[126:127], v[206:207], v[162:163]
	v_pk_mul_f32 v[128:129], v[208:209], v[80:81]
	v_pk_mul_f32 v[114:115], v[10:11], v[114:115]
	v_pk_mul_f32 v[116:117], v[10:11], v[116:117]
	v_pk_mul_f32 v[118:119], v[10:11], v[118:119]
	v_pk_mul_f32 v[120:121], v[10:11], v[120:121]
	v_pk_mul_f32 v[122:123], v[10:11], v[122:123]
	v_pk_mul_f32 v[124:125], v[10:11], v[124:125]
	v_pk_mul_f32 v[126:127], v[10:11], v[126:127]
	v_pk_mul_f32 v[128:129], v[10:11], v[128:129]
	v_pk_fma_f32 v[114:115], v[58:59], s[28:29], v[114:115] op_sel_hi:[1,0,1]
	v_pk_fma_f32 v[116:117], v[60:61], s[28:29], v[116:117] op_sel_hi:[1,0,1]
	v_pk_fma_f32 v[118:119], v[62:63], s[28:29], v[118:119] op_sel_hi:[1,0,1]
	v_pk_fma_f32 v[120:121], v[64:65], s[28:29], v[120:121] op_sel_hi:[1,0,1]
	v_pk_fma_f32 v[122:123], v[66:67], s[28:29], v[122:123] op_sel_hi:[1,0,1]
	v_pk_fma_f32 v[124:125], v[68:69], s[28:29], v[124:125] op_sel_hi:[1,0,1]
	v_pk_fma_f32 v[126:127], v[70:71], s[28:29], v[126:127] op_sel_hi:[1,0,1]
	v_pk_fma_f32 v[128:129], v[72:73], s[28:29], v[128:129] op_sel_hi:[1,0,1]
	v_add_f32_e32 v164, v114, v115
	v_add_f32_e32 v165, v116, v117
	v_add_f32_e32 v166, v118, v119
	v_add_f32_e32 v167, v120, v121
	v_add_f32_e32 v168, v122, v123
	v_add_f32_e32 v169, v124, v125
	v_add_f32_e32 v242, v126, v127
	v_add_f32_e32 v243, v128, v129
	v_add_f32_e32 v164, v164, v165
	v_add_f32_e32 v166, v166, v167
	v_add_f32_e32 v168, v168, v169
	v_add_f32_e32 v242, v242, v243
	v_add_f32_e32 v9, 0, v164
	v_add_f32_e32 v9, v9, v166
	v_add_f32_e32 v9, v9, v168
	v_add_f32_e32 v9, v9, v242
	ds_bpermute_b32 v28, v96, v9
	s_waitcnt lgkmcnt(0)
	v_add_f32_e32 v9, v9, v28
	ds_swizzle_b32 v28, v9 offset:swizzle(SWAP,16)
	s_waitcnt lgkmcnt(0)
	v_add_f32_e32 v9, v9, v28
	ds_swizzle_b32 v28, v9 offset:swizzle(SWAP,8)
	s_waitcnt lgkmcnt(0)
	v_add_f32_e32 v9, v9, v28
	ds_swizzle_b32 v28, v9 offset:swizzle(SWAP,4)
	s_waitcnt lgkmcnt(0)
	v_add_f32_e32 v9, v9, v28
	ds_swizzle_b32 v28, v9 offset:swizzle(SWAP,2)
	s_waitcnt lgkmcnt(0)
	v_add_f32_e32 v9, v9, v28
	ds_swizzle_b32 v28, v9 offset:swizzle(SWAP,1)
	s_waitcnt lgkmcnt(0)
	v_add_f32_e32 v9, v9, v28
	v_fmac_f32_e32 v114, 0xba800000, v9
	v_fmac_f32_e32 v115, 0xba800000, v9
	v_fmac_f32_e32 v116, 0xba800000, v9
	v_fmac_f32_e32 v117, 0xba800000, v9
	v_fmac_f32_e32 v118, 0xba800000, v9
	v_fmac_f32_e32 v119, 0xba800000, v9
	v_fmac_f32_e32 v120, 0xba800000, v9
	v_fmac_f32_e32 v121, 0xba800000, v9
	v_fmac_f32_e32 v122, 0xba800000, v9
	v_fmac_f32_e32 v123, 0xba800000, v9
	v_fmac_f32_e32 v124, 0xba800000, v9
	v_fmac_f32_e32 v125, 0xba800000, v9
	v_fmac_f32_e32 v126, 0xba800000, v9
	v_fmac_f32_e32 v127, 0xba800000, v9
	v_fmac_f32_e32 v128, 0xba800000, v9
	v_fmac_f32_e32 v129, 0xba800000, v9
	v_pk_mul_f32 v[244:245], v[114:115], v[114:115]
	v_pk_mul_f32 v[246:247], v[116:117], v[116:117]
	v_add_f32_e32 v244, v245, v244
	v_add_f32_e32 v246, v246, v247
	v_add_f32_e32 v164, v244, v246
	v_pk_mul_f32 v[244:245], v[118:119], v[118:119]
	v_pk_mul_f32 v[246:247], v[120:121], v[120:121]
	v_add_f32_e32 v244, v245, v244
	v_add_f32_e32 v246, v246, v247
	v_add_f32_e32 v165, v244, v246
	v_mul_f32_e32 v248, v122, v122
	v_mul_f32_e32 v249, v124, v124
	v_fmac_f32_e32 v248, v123, v123
	v_fmac_f32_e32 v249, v125, v125
	v_add_f32_e32 v166, v248, v249
	v_pk_mul_f32 v[244:245], v[126:127], v[126:127]
	v_pk_mul_f32 v[246:247], v[128:129], v[128:129]
	v_add_f32_e32 v244, v244, v245
	v_add_f32_e32 v246, v246, v247
	v_add_f32_e32 v167, v244, v246
	v_add_f32_e32 v164, v164, v165
	v_add_f32_e32 v164, v166, v164
	v_add_f32_e32 v9, v167, v164
	ds_bpermute_b32 v28, v96, v9
	s_waitcnt lgkmcnt(0)
	v_add_f32_e32 v9, v9, v28
	ds_swizzle_b32 v28, v9 offset:swizzle(SWAP,16)
	s_waitcnt lgkmcnt(0)
	v_add_f32_e32 v9, v9, v28
	ds_swizzle_b32 v28, v9 offset:swizzle(SWAP,8)
	s_waitcnt lgkmcnt(0)
	v_add_f32_e32 v9, v9, v28
	ds_swizzle_b32 v28, v9 offset:swizzle(SWAP,4)
	s_waitcnt lgkmcnt(0)
	v_add_f32_e32 v9, v9, v28
	ds_swizzle_b32 v28, v9 offset:swizzle(SWAP,2)
	s_waitcnt lgkmcnt(0)
	v_add_f32_e32 v9, v9, v28
	ds_swizzle_b32 v28, v9 offset:swizzle(SWAP,1)
	s_waitcnt lgkmcnt(0)
	v_add_f32_e32 v9, v9, v28
	v_mov_b32_e32 v28, 0x3727c5ac
	v_fmamk_f32 v9, v9, 0x3a800000, v28
	v_mul_f32_e32 v28, 0x4b800000, v9
	v_cmp_gt_f32_e32 vcc, s37, v9
	s_nop 1
	v_cndmask_b32_e32 v9, v9, v28, vcc
	v_rsq_f32_e32 v9, v9
	s_nop 0
	v_mul_f32_e32 v28, 0x45800000, v9
	v_cndmask_b32_e32 v30, v9, v28, vcc
	v_pk_mul_f32 v[114:115], v[114:115], v[30:31] op_sel_hi:[1,0]
	v_pk_mul_f32 v[116:117], v[116:117], v[30:31] op_sel_hi:[1,0]
	v_pk_fma_f32 v[58:59], v[140:141], v[114:115], v[98:99]
	v_pk_fma_f32 v[60:61], v[142:143], v[116:117], v[100:101]
	global_store_dwordx4 v[86:87], v[58:61], off sc1 nt
	v_pk_fma_f32 v[114:115], v[226:227], v[58:59], v[210:211]
	v_pk_fma_f32 v[116:117], v[228:229], v[60:61], v[212:213]
	s_nop 0
	v_cvt_pk_bf16_f32 v74, v114, v115
	v_cvt_pk_bf16_f32 v75, v116, v117
	global_store_dwordx2 v[88:89], v[74:75], off sc1
	v_pk_mul_f32 v[118:119], v[118:119], v[30:31] op_sel_hi:[1,0]
	v_pk_mul_f32 v[120:121], v[120:121], v[30:31] op_sel_hi:[1,0]
	v_pk_fma_f32 v[62:63], v[144:145], v[118:119], v[102:103]
	v_pk_fma_f32 v[64:65], v[146:147], v[120:121], v[104:105]
	global_store_dwordx4 v[86:87], v[62:65], off offset:1024 sc1 nt
	v_pk_fma_f32 v[118:119], v[230:231], v[62:63], v[214:215]
	v_pk_fma_f32 v[120:121], v[232:233], v[64:65], v[216:217]
	s_nop 0
	v_cvt_pk_bf16_f32 v76, v118, v119
	v_cvt_pk_bf16_f32 v77, v120, v121
	global_store_dwordx2 v[88:89], v[76:77], off offset:512 sc1
	v_pk_mul_f32 v[122:123], v[122:123], v[30:31] op_sel_hi:[1,0]
	v_pk_mul_f32 v[124:125], v[124:125], v[30:31] op_sel_hi:[1,0]
	v_pk_fma_f32 v[66:67], v[148:149], v[122:123], v[106:107]
	v_pk_fma_f32 v[68:69], v[150:151], v[124:125], v[108:109]
	global_store_dwordx4 v[86:87], v[66:69], off offset:2048 sc1 nt
	v_pk_fma_f32 v[122:123], v[234:235], v[66:67], v[218:219]
	v_pk_fma_f32 v[124:125], v[236:237], v[68:69], v[220:221]
	s_nop 0
	v_cvt_pk_bf16_f32 v78, v122, v123
	v_cvt_pk_bf16_f32 v79, v124, v125
	global_store_dwordx2 v[88:89], v[78:79], off offset:1024 sc1
	v_pk_mul_f32 v[126:127], v[126:127], v[30:31] op_sel_hi:[1,0]
	v_pk_mul_f32 v[128:129], v[128:129], v[30:31] op_sel_hi:[1,0]
	v_pk_fma_f32 v[70:71], v[152:153], v[126:127], v[110:111]
	v_pk_fma_f32 v[72:73], v[154:155], v[128:129], v[112:113]
	global_store_dwordx4 v[86:87], v[70:73], off offset:3072 sc1 nt
	v_pk_fma_f32 v[126:127], v[238:239], v[70:71], v[222:223]
	v_pk_fma_f32 v[128:129], v[240:241], v[72:73], v[224:225]
	s_nop 0
	v_cvt_pk_bf16_f32 v80, v126, v127
	v_cvt_pk_bf16_f32 v81, v128, v129
	global_store_dwordx2 v[88:89], v[80:81], off offset:1536 sc1
	v_lshl_add_u64 v[86:87], v[86:87], 0, s[0:1]
	v_lshl_add_u64 v[88:89], v[88:89], 0, s[20:21]
	s_waitcnt vmcnt(24)
	v_lshlrev_b32_e32 v156, 16, v12
	v_and_b32_e32 v157, 0xffff0000, v12
	v_lshlrev_b32_e32 v12, 16, v13
	v_and_b32_e32 v13, 0xffff0000, v13
	v_lshlrev_b32_e32 v158, 16, v14
	v_and_b32_e32 v159, 0xffff0000, v14
	v_lshlrev_b32_e32 v14, 16, v15
	v_and_b32_e32 v15, 0xffff0000, v15
	v_lshlrev_b32_e32 v160, 16, v16
	v_and_b32_e32 v161, 0xffff0000, v16
	v_lshlrev_b32_e32 v16, 16, v17
	v_and_b32_e32 v17, 0xffff0000, v17
	v_lshlrev_b32_e32 v162, 16, v18
	v_and_b32_e32 v163, 0xffff0000, v18
	v_lshlrev_b32_e32 v18, 16, v19
	v_and_b32_e32 v19, 0xffff0000, v19
	v_pk_mul_f32 v[114:115], v[194:195], v[156:157]
	v_pk_mul_f32 v[116:117], v[196:197], v[12:13]
	v_pk_mul_f32 v[118:119], v[198:199], v[158:159]
	v_pk_mul_f32 v[120:121], v[200:201], v[14:15]
	v_pk_mul_f32 v[122:123], v[202:203], v[160:161]
	v_pk_mul_f32 v[124:125], v[204:205], v[16:17]
	v_pk_mul_f32 v[126:127], v[206:207], v[162:163]
	v_pk_mul_f32 v[128:129], v[208:209], v[18:19]
	v_pk_mul_f32 v[114:115], v[10:11], v[114:115]
	v_pk_mul_f32 v[116:117], v[10:11], v[116:117]
	v_pk_mul_f32 v[118:119], v[10:11], v[118:119]
	v_pk_mul_f32 v[120:121], v[10:11], v[120:121]
	v_pk_mul_f32 v[122:123], v[10:11], v[122:123]
	v_pk_mul_f32 v[124:125], v[10:11], v[124:125]
	v_pk_mul_f32 v[126:127], v[10:11], v[126:127]
	v_pk_mul_f32 v[128:129], v[10:11], v[128:129]
	v_pk_fma_f32 v[114:115], v[20:21], s[28:29], v[114:115] op_sel_hi:[1,0,1]
	v_pk_fma_f32 v[116:117], v[22:23], s[28:29], v[116:117] op_sel_hi:[1,0,1]
	v_pk_fma_f32 v[118:119], v[24:25], s[28:29], v[118:119] op_sel_hi:[1,0,1]
	v_pk_fma_f32 v[120:121], v[26:27], s[28:29], v[120:121] op_sel_hi:[1,0,1]
	v_pk_fma_f32 v[122:123], v[0:1], s[28:29], v[122:123] op_sel_hi:[1,0,1]
	v_pk_fma_f32 v[124:125], v[2:3], s[28:29], v[124:125] op_sel_hi:[1,0,1]
	v_pk_fma_f32 v[126:127], v[4:5], s[28:29], v[126:127] op_sel_hi:[1,0,1]
	v_pk_fma_f32 v[128:129], v[6:7], s[28:29], v[128:129] op_sel_hi:[1,0,1]
	v_add_f32_e32 v164, v114, v115
	v_add_f32_e32 v165, v116, v117
	v_add_f32_e32 v166, v118, v119
	v_add_f32_e32 v167, v120, v121
	v_add_f32_e32 v168, v122, v123
	v_add_f32_e32 v169, v124, v125
	v_add_f32_e32 v242, v126, v127
	v_add_f32_e32 v243, v128, v129
	v_add_f32_e32 v164, v164, v165
	v_add_f32_e32 v166, v166, v167
	v_add_f32_e32 v168, v168, v169
	v_add_f32_e32 v242, v242, v243
	v_add_f32_e32 v9, 0, v164
	v_add_f32_e32 v9, v9, v166
	v_add_f32_e32 v9, v9, v168
	v_add_f32_e32 v9, v9, v242
	ds_bpermute_b32 v28, v96, v9
	s_waitcnt lgkmcnt(0)
	v_add_f32_e32 v9, v9, v28
	ds_swizzle_b32 v28, v9 offset:swizzle(SWAP,16)
	s_waitcnt lgkmcnt(0)
	v_add_f32_e32 v9, v9, v28
	ds_swizzle_b32 v28, v9 offset:swizzle(SWAP,8)
	s_waitcnt lgkmcnt(0)
	v_add_f32_e32 v9, v9, v28
	ds_swizzle_b32 v28, v9 offset:swizzle(SWAP,4)
	s_waitcnt lgkmcnt(0)
	v_add_f32_e32 v9, v9, v28
	ds_swizzle_b32 v28, v9 offset:swizzle(SWAP,2)
	s_waitcnt lgkmcnt(0)
	v_add_f32_e32 v9, v9, v28
	ds_swizzle_b32 v28, v9 offset:swizzle(SWAP,1)
	s_waitcnt lgkmcnt(0)
	v_add_f32_e32 v9, v9, v28
	v_fmac_f32_e32 v114, 0xba800000, v9
	v_fmac_f32_e32 v115, 0xba800000, v9
	v_fmac_f32_e32 v116, 0xba800000, v9
	v_fmac_f32_e32 v117, 0xba800000, v9
	v_fmac_f32_e32 v118, 0xba800000, v9
	v_fmac_f32_e32 v119, 0xba800000, v9
	v_fmac_f32_e32 v120, 0xba800000, v9
	v_fmac_f32_e32 v121, 0xba800000, v9
	v_fmac_f32_e32 v122, 0xba800000, v9
	v_fmac_f32_e32 v123, 0xba800000, v9
	v_fmac_f32_e32 v124, 0xba800000, v9
	v_fmac_f32_e32 v125, 0xba800000, v9
	v_fmac_f32_e32 v126, 0xba800000, v9
	v_fmac_f32_e32 v127, 0xba800000, v9
	v_fmac_f32_e32 v128, 0xba800000, v9
	v_fmac_f32_e32 v129, 0xba800000, v9
	v_pk_mul_f32 v[244:245], v[114:115], v[114:115]
	v_pk_mul_f32 v[246:247], v[116:117], v[116:117]
	v_add_f32_e32 v244, v245, v244
	v_add_f32_e32 v246, v246, v247
	v_add_f32_e32 v164, v244, v246
	v_pk_mul_f32 v[244:245], v[118:119], v[118:119]
	v_pk_mul_f32 v[246:247], v[120:121], v[120:121]
	v_add_f32_e32 v244, v245, v244
	v_add_f32_e32 v246, v246, v247
	v_add_f32_e32 v165, v244, v246
	v_mul_f32_e32 v248, v122, v122
	v_mul_f32_e32 v249, v124, v124
	v_fmac_f32_e32 v248, v123, v123
	v_fmac_f32_e32 v249, v125, v125
	v_add_f32_e32 v166, v248, v249
	v_pk_mul_f32 v[244:245], v[126:127], v[126:127]
	v_pk_mul_f32 v[246:247], v[128:129], v[128:129]
	v_add_f32_e32 v244, v244, v245
	v_add_f32_e32 v246, v246, v247
	v_add_f32_e32 v167, v244, v246
	v_add_f32_e32 v164, v164, v165
	v_add_f32_e32 v164, v166, v164
	v_add_f32_e32 v9, v167, v164
	ds_bpermute_b32 v28, v96, v9
	s_waitcnt lgkmcnt(0)
	v_add_f32_e32 v9, v9, v28
	ds_swizzle_b32 v28, v9 offset:swizzle(SWAP,16)
	s_waitcnt lgkmcnt(0)
	v_add_f32_e32 v9, v9, v28
	ds_swizzle_b32 v28, v9 offset:swizzle(SWAP,8)
	s_waitcnt lgkmcnt(0)
	v_add_f32_e32 v9, v9, v28
	ds_swizzle_b32 v28, v9 offset:swizzle(SWAP,4)
	s_waitcnt lgkmcnt(0)
	v_add_f32_e32 v9, v9, v28
	ds_swizzle_b32 v28, v9 offset:swizzle(SWAP,2)
	s_waitcnt lgkmcnt(0)
	v_add_f32_e32 v9, v9, v28
	ds_swizzle_b32 v28, v9 offset:swizzle(SWAP,1)
	s_waitcnt lgkmcnt(0)
	v_add_f32_e32 v9, v9, v28
	v_mov_b32_e32 v28, 0x3727c5ac
	v_fmamk_f32 v9, v9, 0x3a800000, v28
	v_mul_f32_e32 v28, 0x4b800000, v9
	v_cmp_gt_f32_e32 vcc, s37, v9
	s_nop 1
	v_cndmask_b32_e32 v9, v9, v28, vcc
	v_rsq_f32_e32 v9, v9
	s_nop 0
	v_mul_f32_e32 v28, 0x45800000, v9
	v_cndmask_b32_e32 v30, v9, v28, vcc
	v_pk_mul_f32 v[114:115], v[114:115], v[30:31] op_sel_hi:[1,0]
	v_pk_mul_f32 v[116:117], v[116:117], v[30:31] op_sel_hi:[1,0]
	v_pk_fma_f32 v[20:21], v[140:141], v[114:115], v[98:99]
	v_pk_fma_f32 v[22:23], v[142:143], v[116:117], v[100:101]
	global_store_dwordx4 v[86:87], v[20:23], off sc1 nt
	v_pk_fma_f32 v[114:115], v[226:227], v[20:21], v[210:211]
	v_pk_fma_f32 v[116:117], v[228:229], v[22:23], v[212:213]
	s_nop 0
	v_cvt_pk_bf16_f32 v12, v114, v115
	v_cvt_pk_bf16_f32 v13, v116, v117
	global_store_dwordx2 v[88:89], v[12:13], off sc1
	v_pk_mul_f32 v[118:119], v[118:119], v[30:31] op_sel_hi:[1,0]
	v_pk_mul_f32 v[120:121], v[120:121], v[30:31] op_sel_hi:[1,0]
	v_pk_fma_f32 v[24:25], v[144:145], v[118:119], v[102:103]
	v_pk_fma_f32 v[26:27], v[146:147], v[120:121], v[104:105]
	global_store_dwordx4 v[86:87], v[24:27], off offset:1024 sc1 nt
	v_pk_fma_f32 v[118:119], v[230:231], v[24:25], v[214:215]
	v_pk_fma_f32 v[120:121], v[232:233], v[26:27], v[216:217]
	s_nop 0
	v_cvt_pk_bf16_f32 v14, v118, v119
	v_cvt_pk_bf16_f32 v15, v120, v121
	global_store_dwordx2 v[88:89], v[14:15], off offset:512 sc1
	v_pk_mul_f32 v[122:123], v[122:123], v[30:31] op_sel_hi:[1,0]
	v_pk_mul_f32 v[124:125], v[124:125], v[30:31] op_sel_hi:[1,0]
	v_pk_fma_f32 v[0:1], v[148:149], v[122:123], v[106:107]
	v_pk_fma_f32 v[2:3], v[150:151], v[124:125], v[108:109]
	global_store_dwordx4 v[86:87], v[0:3], off offset:2048 sc1 nt
	v_pk_fma_f32 v[122:123], v[234:235], v[0:1], v[218:219]
	v_pk_fma_f32 v[124:125], v[236:237], v[2:3], v[220:221]
	s_nop 0
	v_cvt_pk_bf16_f32 v16, v122, v123
	v_cvt_pk_bf16_f32 v17, v124, v125
	global_store_dwordx2 v[88:89], v[16:17], off offset:1024 sc1
	v_pk_mul_f32 v[126:127], v[126:127], v[30:31] op_sel_hi:[1,0]
	v_pk_mul_f32 v[128:129], v[128:129], v[30:31] op_sel_hi:[1,0]
	v_pk_fma_f32 v[4:5], v[152:153], v[126:127], v[110:111]
	v_pk_fma_f32 v[6:7], v[154:155], v[128:129], v[112:113]
	global_store_dwordx4 v[86:87], v[4:7], off offset:3072 sc1 nt
	v_pk_fma_f32 v[126:127], v[238:239], v[4:5], v[222:223]
	v_pk_fma_f32 v[128:129], v[240:241], v[6:7], v[224:225]
	s_nop 0
	v_cvt_pk_bf16_f32 v18, v126, v127
	v_cvt_pk_bf16_f32 v19, v128, v129
	global_store_dwordx2 v[88:89], v[18:19], off offset:1536 sc1
	v_lshl_add_u64 v[86:87], v[86:87], 0, s[0:1]
	v_lshl_add_u64 v[88:89], v[88:89], 0, s[20:21]
	s_waitcnt vmcnt(16)
	v_lshlrev_b32_e32 v156, 16, v50
	v_and_b32_e32 v157, 0xffff0000, v50
	v_lshlrev_b32_e32 v50, 16, v51
	v_and_b32_e32 v51, 0xffff0000, v51
	v_lshlrev_b32_e32 v158, 16, v52
	v_and_b32_e32 v159, 0xffff0000, v52
	v_lshlrev_b32_e32 v52, 16, v53
	v_and_b32_e32 v53, 0xffff0000, v53
	v_lshlrev_b32_e32 v160, 16, v54
	v_and_b32_e32 v161, 0xffff0000, v54
	v_lshlrev_b32_e32 v54, 16, v55
	v_and_b32_e32 v55, 0xffff0000, v55
	v_lshlrev_b32_e32 v162, 16, v56
	v_and_b32_e32 v163, 0xffff0000, v56
	v_lshlrev_b32_e32 v56, 16, v57
	v_and_b32_e32 v57, 0xffff0000, v57
	v_pk_mul_f32 v[114:115], v[194:195], v[156:157]
	v_pk_mul_f32 v[116:117], v[196:197], v[50:51]
	v_pk_mul_f32 v[118:119], v[198:199], v[158:159]
	v_pk_mul_f32 v[120:121], v[200:201], v[52:53]
	v_pk_mul_f32 v[122:123], v[202:203], v[160:161]
	v_pk_mul_f32 v[124:125], v[204:205], v[54:55]
	v_pk_mul_f32 v[126:127], v[206:207], v[162:163]
	v_pk_mul_f32 v[128:129], v[208:209], v[56:57]
	v_pk_mul_f32 v[114:115], v[10:11], v[114:115]
	v_pk_mul_f32 v[116:117], v[10:11], v[116:117]
	v_pk_mul_f32 v[118:119], v[10:11], v[118:119]
	v_pk_mul_f32 v[120:121], v[10:11], v[120:121]
	v_pk_mul_f32 v[122:123], v[10:11], v[122:123]
	v_pk_mul_f32 v[124:125], v[10:11], v[124:125]
	v_pk_mul_f32 v[126:127], v[10:11], v[126:127]
	v_pk_mul_f32 v[128:129], v[10:11], v[128:129]
	v_pk_fma_f32 v[114:115], v[34:35], s[28:29], v[114:115] op_sel_hi:[1,0,1]
	v_pk_fma_f32 v[116:117], v[36:37], s[28:29], v[116:117] op_sel_hi:[1,0,1]
	v_pk_fma_f32 v[118:119], v[38:39], s[28:29], v[118:119] op_sel_hi:[1,0,1]
	v_pk_fma_f32 v[120:121], v[40:41], s[28:29], v[120:121] op_sel_hi:[1,0,1]
	v_pk_fma_f32 v[122:123], v[42:43], s[28:29], v[122:123] op_sel_hi:[1,0,1]
	v_pk_fma_f32 v[124:125], v[44:45], s[28:29], v[124:125] op_sel_hi:[1,0,1]
	v_pk_fma_f32 v[126:127], v[46:47], s[28:29], v[126:127] op_sel_hi:[1,0,1]
	v_pk_fma_f32 v[128:129], v[48:49], s[28:29], v[128:129] op_sel_hi:[1,0,1]
	v_add_f32_e32 v164, v114, v115
	v_add_f32_e32 v165, v116, v117
	v_add_f32_e32 v166, v118, v119
	v_add_f32_e32 v167, v120, v121
	v_add_f32_e32 v168, v122, v123
	v_add_f32_e32 v169, v124, v125
	v_add_f32_e32 v242, v126, v127
	v_add_f32_e32 v243, v128, v129
	v_add_f32_e32 v164, v164, v165
	v_add_f32_e32 v166, v166, v167
	v_add_f32_e32 v168, v168, v169
	v_add_f32_e32 v242, v242, v243
	v_add_f32_e32 v9, 0, v164
	v_add_f32_e32 v9, v9, v166
	v_add_f32_e32 v9, v9, v168
	v_add_f32_e32 v9, v9, v242
	ds_bpermute_b32 v28, v96, v9
	s_waitcnt lgkmcnt(0)
	v_add_f32_e32 v9, v9, v28
	ds_swizzle_b32 v28, v9 offset:swizzle(SWAP,16)
	s_waitcnt lgkmcnt(0)
	v_add_f32_e32 v9, v9, v28
	ds_swizzle_b32 v28, v9 offset:swizzle(SWAP,8)
	s_waitcnt lgkmcnt(0)
	v_add_f32_e32 v9, v9, v28
	ds_swizzle_b32 v28, v9 offset:swizzle(SWAP,4)
	s_waitcnt lgkmcnt(0)
	v_add_f32_e32 v9, v9, v28
	ds_swizzle_b32 v28, v9 offset:swizzle(SWAP,2)
	s_waitcnt lgkmcnt(0)
	v_add_f32_e32 v9, v9, v28
	ds_swizzle_b32 v28, v9 offset:swizzle(SWAP,1)
	s_waitcnt lgkmcnt(0)
	v_add_f32_e32 v9, v9, v28
	v_fmac_f32_e32 v114, 0xba800000, v9
	v_fmac_f32_e32 v115, 0xba800000, v9
	v_fmac_f32_e32 v116, 0xba800000, v9
	v_fmac_f32_e32 v117, 0xba800000, v9
	v_fmac_f32_e32 v118, 0xba800000, v9
	v_fmac_f32_e32 v119, 0xba800000, v9
	v_fmac_f32_e32 v120, 0xba800000, v9
	v_fmac_f32_e32 v121, 0xba800000, v9
	v_fmac_f32_e32 v122, 0xba800000, v9
	v_fmac_f32_e32 v123, 0xba800000, v9
	v_fmac_f32_e32 v124, 0xba800000, v9
	v_fmac_f32_e32 v125, 0xba800000, v9
	v_fmac_f32_e32 v126, 0xba800000, v9
	v_fmac_f32_e32 v127, 0xba800000, v9
	v_fmac_f32_e32 v128, 0xba800000, v9
	v_fmac_f32_e32 v129, 0xba800000, v9
	v_pk_mul_f32 v[244:245], v[114:115], v[114:115]
	v_pk_mul_f32 v[246:247], v[116:117], v[116:117]
	v_add_f32_e32 v244, v245, v244
	v_add_f32_e32 v246, v246, v247
	v_add_f32_e32 v164, v244, v246
	v_pk_mul_f32 v[244:245], v[118:119], v[118:119]
	v_pk_mul_f32 v[246:247], v[120:121], v[120:121]
	v_add_f32_e32 v244, v245, v244
	v_add_f32_e32 v246, v246, v247
	v_add_f32_e32 v165, v244, v246
	v_mul_f32_e32 v248, v122, v122
	v_mul_f32_e32 v249, v124, v124
	v_fmac_f32_e32 v248, v123, v123
	v_fmac_f32_e32 v249, v125, v125
	v_add_f32_e32 v166, v248, v249
	v_pk_mul_f32 v[244:245], v[126:127], v[126:127]
	v_pk_mul_f32 v[246:247], v[128:129], v[128:129]
	v_add_f32_e32 v244, v244, v245
	v_add_f32_e32 v246, v246, v247
	v_add_f32_e32 v167, v244, v246
	v_add_f32_e32 v164, v164, v165
	v_add_f32_e32 v164, v166, v164
	v_add_f32_e32 v9, v167, v164
	ds_bpermute_b32 v28, v96, v9
	s_waitcnt lgkmcnt(0)
	v_add_f32_e32 v9, v9, v28
	ds_swizzle_b32 v28, v9 offset:swizzle(SWAP,16)
	s_waitcnt lgkmcnt(0)
	v_add_f32_e32 v9, v9, v28
	ds_swizzle_b32 v28, v9 offset:swizzle(SWAP,8)
	s_waitcnt lgkmcnt(0)
	v_add_f32_e32 v9, v9, v28
	ds_swizzle_b32 v28, v9 offset:swizzle(SWAP,4)
	s_waitcnt lgkmcnt(0)
	v_add_f32_e32 v9, v9, v28
	ds_swizzle_b32 v28, v9 offset:swizzle(SWAP,2)
	s_waitcnt lgkmcnt(0)
	v_add_f32_e32 v9, v9, v28
	ds_swizzle_b32 v28, v9 offset:swizzle(SWAP,1)
	s_waitcnt lgkmcnt(0)
	v_add_f32_e32 v9, v9, v28
	v_mov_b32_e32 v28, 0x3727c5ac
	v_fmamk_f32 v9, v9, 0x3a800000, v28
	v_mul_f32_e32 v28, 0x4b800000, v9
	v_cmp_gt_f32_e32 vcc, s37, v9
	s_nop 1
	v_cndmask_b32_e32 v9, v9, v28, vcc
	v_rsq_f32_e32 v9, v9
	s_nop 0
	v_mul_f32_e32 v28, 0x45800000, v9
	v_cndmask_b32_e32 v30, v9, v28, vcc
	v_pk_mul_f32 v[114:115], v[114:115], v[30:31] op_sel_hi:[1,0]
	v_pk_mul_f32 v[116:117], v[116:117], v[30:31] op_sel_hi:[1,0]
	v_pk_fma_f32 v[34:35], v[140:141], v[114:115], v[98:99]
	v_pk_fma_f32 v[36:37], v[142:143], v[116:117], v[100:101]
	global_store_dwordx4 v[86:87], v[34:37], off sc1 nt
	v_pk_fma_f32 v[114:115], v[226:227], v[34:35], v[210:211]
	v_pk_fma_f32 v[116:117], v[228:229], v[36:37], v[212:213]
	s_nop 0
	v_cvt_pk_bf16_f32 v50, v114, v115
	v_cvt_pk_bf16_f32 v51, v116, v117
	global_store_dwordx2 v[88:89], v[50:51], off sc1
	v_pk_mul_f32 v[118:119], v[118:119], v[30:31] op_sel_hi:[1,0]
	v_pk_mul_f32 v[120:121], v[120:121], v[30:31] op_sel_hi:[1,0]
	v_pk_fma_f32 v[38:39], v[144:145], v[118:119], v[102:103]
	v_pk_fma_f32 v[40:41], v[146:147], v[120:121], v[104:105]
	global_store_dwordx4 v[86:87], v[38:41], off offset:1024 sc1 nt
	v_pk_fma_f32 v[118:119], v[230:231], v[38:39], v[214:215]
	v_pk_fma_f32 v[120:121], v[232:233], v[40:41], v[216:217]
	s_nop 0
	v_cvt_pk_bf16_f32 v52, v118, v119
	v_cvt_pk_bf16_f32 v53, v120, v121
	global_store_dwordx2 v[88:89], v[52:53], off offset:512 sc1
	v_pk_mul_f32 v[122:123], v[122:123], v[30:31] op_sel_hi:[1,0]
	v_pk_mul_f32 v[124:125], v[124:125], v[30:31] op_sel_hi:[1,0]
	v_pk_fma_f32 v[42:43], v[148:149], v[122:123], v[106:107]
	v_pk_fma_f32 v[44:45], v[150:151], v[124:125], v[108:109]
	global_store_dwordx4 v[86:87], v[42:45], off offset:2048 sc1 nt
	v_pk_fma_f32 v[122:123], v[234:235], v[42:43], v[218:219]
	v_pk_fma_f32 v[124:125], v[236:237], v[44:45], v[220:221]
	s_nop 0
	v_cvt_pk_bf16_f32 v54, v122, v123
	v_cvt_pk_bf16_f32 v55, v124, v125
	global_store_dwordx2 v[88:89], v[54:55], off offset:1024 sc1
	v_pk_mul_f32 v[126:127], v[126:127], v[30:31] op_sel_hi:[1,0]
	v_pk_mul_f32 v[128:129], v[128:129], v[30:31] op_sel_hi:[1,0]
	v_pk_fma_f32 v[46:47], v[152:153], v[126:127], v[110:111]
	v_pk_fma_f32 v[48:49], v[154:155], v[128:129], v[112:113]
	global_store_dwordx4 v[86:87], v[46:49], off offset:3072 sc1 nt
	v_pk_fma_f32 v[126:127], v[238:239], v[46:47], v[222:223]
	v_pk_fma_f32 v[128:129], v[240:241], v[48:49], v[224:225]
	s_nop 0
	v_cvt_pk_bf16_f32 v56, v126, v127
	v_cvt_pk_bf16_f32 v57, v128, v129
	global_store_dwordx2 v[88:89], v[56:57], off offset:1536 sc1
	v_lshl_add_u64 v[86:87], v[86:87], 0, s[0:1]
	v_lshl_add_u64 v[88:89], v[88:89], 0, s[20:21]
	s_branch .LBB0_53
